# v8: hoisted serialized load chains (sample items q/k/xf loads, ma_even per-token loads, state streaming, Vs fill) to batch issue with single wait
# speedup vs baseline: 1.0532x; 1.0206x over previous
; __device__ __forceinline__ unsigned f2bf(float f) { unsigned u = __builtin_bit_cast(unsigned, f); return (u + 0x7fffu + ((u >> 16) & 1u)) >> 16; }
; __device__ __forceinline__ float siluf(float x) { return x * __builtin_amdgcn_rcpf(1.0f + __expf(-x)); }
; template <int TY> __device__ __forceinline__ void sample_item(const Params& p, ldsp lds, int item) {
;     ...
;     { const int t = wave; float val[DV / 64]; float ssq = 0.f;
; #pragma unroll
;       for (int i = 0; i < DV / 64; ++i) { const int e = lane + 64 * i; float a = 0.f;
;           for (int g = 0; g < NG; ++g) a += OP[(g * 8 + t) * DV + e];
;           for (int s = 0; s <= t; ++s) a += As[t * 8 + s] * Vs[s * DV + e];
;           val[i] = a; ssq += a * a; }
;       ssq = wave_sum(ssq); const float rstd = rsqrtf(ssq * (1.0f / DV) + EPS);
;       const float* nwp = TY == 0 ? p.in[12] : (TY == 1 ? p.in[14] : p.in[17]);
;       const int goff = TY == 0 ? E_RA + h * 128 : (TY == 1 ? E_GB + h * 128 : O_G + h * 512);
;       constexpr int LDY = TY == 2 ? 2048 : 1024; const int ycol = TY == 0 ? h * 128 : (TY == 1 ? 512 + h * 128 : h * 512);
;       bf16_t* Y = (bf16_t*)(p.ws + WS_Y) + (size_t)(r0 + t) * LDY + ycol;
; #pragma unroll
;       for (int i = 0; i < DV / 64; ++i) { const int e = lane + 64 * i; const float g = bf2f(Pb[(size_t)t * PP + goff + e]);
;           Y[e] = (bf16_t)f2bf(val[i] * rstd * nwp[e] * siluf(g)); } }
.LBB0_683:
	v_mul_f32_e32 v8, v6, v6
	v_fmac_f32_e32 v8, v7, v7
	v_fmac_f32_e32 v8, v9, v9
	v_fmac_f32_e32 v8, v5, v5
	v_pk_mul_f32 v[10:11], v[2:3], v[2:3]
	s_add_i32 s0, s19, s37
	v_add_f32_e32 v8, v8, v10
	v_add_f32_e32 v8, v8, v11
	v_pk_mul_f32 v[10:11], v[0:1], v[0:1]
	s_ashr_i32 s1, s0, 31
	v_add_f32_e32 v8, v8, v10
	v_xor_b32_e32 v10, 1, v164
	v_cmp_lt_i32_e32 vcc, v10, v165
	v_add_f32_e32 v8, v8, v11
	s_lshl_b64 s[0:1], s[0:1], 12
	v_cndmask_b32_e32 v10, v164, v10, vcc
	v_lshlrev_b32_e32 v10, 2, v10
	ds_bpermute_b32 v10, v10, v8
	s_add_u32 s0, s61, s0
	v_readlane_b32 s8, v253, 31
	s_addc_u32 s1, s8, s1
	s_lshl_b32 s8, s36, 1
	s_waitcnt lgkmcnt(0)
	v_add_f32_e32 v8, v8, v10
	v_xor_b32_e32 v10, 2, v164
	v_cmp_lt_i32_e32 vcc, v10, v165
	s_add_u32 s0, s0, s8
	s_addc_u32 s1, s1, 0
	v_cndmask_b32_e32 v10, v164, v10, vcc
	v_lshlrev_b32_e32 v10, 2, v10
	ds_bpermute_b32 v10, v10, v8
	v_cmp_lt_i32_e32 vcc, v184, v165
	s_mul_hi_i32 s9, s19, 0x3000
	s_mulk_i32 s19, 0x3000
	s_add_u32 s10, s20, s19
	s_waitcnt lgkmcnt(0)
	v_add_f32_e32 v8, v8, v10
	v_cndmask_b32_e32 v10, v164, v184, vcc
	v_lshlrev_b32_e32 v10, 2, v10
	ds_bpermute_b32 v10, v10, v8
	s_addc_u32 s9, s21, s9
	s_add_u32 s8, s10, s8
	s_addc_u32 s9, s9, 0
	s_add_u32 s8, s8, 0x2000
	s_waitcnt lgkmcnt(0)
	v_add_f32_e32 v8, v8, v10
	v_xor_b32_e32 v10, 8, v164
	v_cmp_lt_i32_e32 vcc, v10, v165
	v_lshlrev_b32_e32 v4, 1, v116
	s_addc_u32 s9, s9, 0
	v_cndmask_b32_e32 v10, v164, v10, vcc
	v_lshlrev_b32_e32 v10, 2, v10
	ds_bpermute_b32 v10, v10, v8
	v_cmp_lt_i32_e32 vcc, v170, v165
	s_add_i32 s18, s18, s70
	s_waitcnt lgkmcnt(0)
	v_add_f32_e32 v8, v8, v10
	v_cndmask_b32_e32 v10, v164, v170, vcc
	v_lshlrev_b32_e32 v10, 2, v10
	ds_bpermute_b32 v10, v10, v8
	v_cmp_lt_i32_e32 vcc, v171, v165
	s_waitcnt lgkmcnt(0)
	v_add_f32_e32 v8, v8, v10
	v_cndmask_b32_e32 v10, v164, v171, vcc
	v_lshlrev_b32_e32 v10, 2, v10
	ds_bpermute_b32 v10, v10, v8
	s_waitcnt lgkmcnt(0)
	v_add_f32_e32 v8, v8, v10
	v_mov_b32_e32 v10, 0x358637bd
	v_fmamk_f32 v8, v8, 0x3b000000, v10
	v_cmp_gt_f32_e32 vcc, s33, v8
	v_mul_f32_e32 v10, 0x4b800000, v8
	s_nop 0
	v_cndmask_b32_e32 v8, v8, v10, vcc
	v_rsq_f32_e32 v8, v8
	s_nop 0
	v_mul_f32_e32 v10, 0x45800000, v8
	v_cndmask_b32_e32 v8, v8, v10, vcc
	global_load_ushort v210, v4, s[8:9]
	v_lshlrev_b32_e32 v211, 2, v116
	global_load_dword v212, v211, s[62:63]
	v_or_b32_e32 v213, 0x80, v4
	global_load_ushort v214, v213, s[8:9]
	global_load_dword v215, v211, s[62:63] offset:256
	v_or_b32_e32 v216, 0x100, v4
	global_load_ushort v217, v216, s[8:9]
	global_load_dword v218, v211, s[62:63] offset:512
	v_or_b32_e32 v219, 0x180, v4
	global_load_ushort v220, v219, s[8:9]
	global_load_dword v221, v211, s[62:63] offset:768
	v_or_b32_e32 v222, 0x200, v4
	global_load_ushort v223, v222, s[8:9]
	global_load_dword v224, v211, s[62:63] offset:1024
	v_or_b32_e32 v225, 0x280, v4
	global_load_ushort v226, v225, s[8:9]
	global_load_dword v227, v211, s[62:63] offset:1280
	v_or_b32_e32 v228, 0x300, v4
	global_load_ushort v229, v228, s[8:9]
	global_load_dword v230, v211, s[62:63] offset:1536
	v_or_b32_e32 v231, 0x380, v4
	global_load_ushort v232, v231, s[8:9]
	global_load_dword v233, v211, s[62:63] offset:1792
	v_mul_f32_e32 v11, v7, v8
	v_lshlrev_b32_e32 v7, 2, v116
	v_mul_f32_e32 v6, v6, v8
	v_mul_f32_e32 v9, v9, v8
	v_mul_f32_e32 v5, v5, v8
	v_mul_f32_e32 v2, v2, v8
	v_mul_f32_e32 v3, v3, v8
	v_mul_f32_e32 v0, v0, v8
	v_mul_f32_e32 v1, v1, v8
	s_waitcnt vmcnt(0)
	v_lshlrev_b32_e32 v10, 16, v210
	v_mul_f32_e32 v11, v212, v11
	v_mul_f32_e32 v12, 0xbfb8aa3b, v10
	v_exp_f32_e32 v12, v12
	s_nop 0
	v_add_f32_e32 v12, 1.0, v12
	v_rcp_f32_e32 v12, v12
	s_nop 0
	v_mul_f32_e32 v10, v12, v10
	v_mul_f32_e32 v10, v10, v11
	v_bfe_u32 v11, v10, 16, 1
	v_add3_u32 v10, v10, v11, s52
	global_store_short_d16_hi v4, v10, s[0:1]
	v_or_b32_e32 v10, 0x80, v4
	v_lshlrev_b32_e32 v10, 16, v214
	v_mul_f32_e32 v6, v215, v6
	v_mul_f32_e32 v11, 0xbfb8aa3b, v10
	v_exp_f32_e32 v11, v11
	s_nop 0
	v_add_f32_e32 v11, 1.0, v11
	v_rcp_f32_e32 v11, v11
	s_nop 0
	v_mul_f32_e32 v10, v11, v10
	v_mul_f32_e32 v6, v6, v10
	v_bfe_u32 v10, v6, 16, 1
	v_add3_u32 v6, v6, v10, s52
	global_store_short_d16_hi v4, v6, s[0:1] offset:128
	v_or_b32_e32 v6, 0x100, v4
	v_lshlrev_b32_e32 v6, 16, v217
	v_mul_f32_e32 v9, v218, v9
	v_mul_f32_e32 v10, 0xbfb8aa3b, v6
	v_exp_f32_e32 v10, v10
	s_nop 0
	v_add_f32_e32 v10, 1.0, v10
	v_rcp_f32_e32 v10, v10
	s_nop 0
	v_mul_f32_e32 v6, v10, v6
	v_mul_f32_e32 v6, v9, v6
	v_bfe_u32 v9, v6, 16, 1
	v_add3_u32 v6, v6, v9, s52
	global_store_short_d16_hi v4, v6, s[0:1] offset:256
	v_or_b32_e32 v6, 0x180, v4
	v_lshlrev_b32_e32 v6, 16, v220
	v_mul_f32_e32 v5, v5, v221
	v_mul_f32_e32 v9, 0xbfb8aa3b, v6
	v_exp_f32_e32 v9, v9
	s_nop 0
	v_add_f32_e32 v9, 1.0, v9
	v_rcp_f32_e32 v9, v9
	s_nop 0
	v_mul_f32_e32 v6, v9, v6
	v_mul_f32_e32 v5, v5, v6
	v_bfe_u32 v6, v5, 16, 1
	v_add3_u32 v5, v5, v6, s52
	global_store_short_d16_hi v4, v5, s[0:1] offset:384
	v_or_b32_e32 v5, 0x200, v4
	v_lshlrev_b32_e32 v5, 16, v223
	v_mul_f32_e32 v2, v2, v224
	v_mul_f32_e32 v6, 0xbfb8aa3b, v5
	v_exp_f32_e32 v6, v6
	s_nop 0
	v_add_f32_e32 v6, 1.0, v6
	v_rcp_f32_e32 v6, v6
	s_nop 0
	v_mul_f32_e32 v5, v6, v5
	v_mul_f32_e32 v2, v2, v5
	v_bfe_u32 v5, v2, 16, 1
	v_add3_u32 v2, v2, v5, s52
	global_store_short_d16_hi v4, v2, s[0:1] offset:512
	v_or_b32_e32 v2, 0x280, v4
	v_lshlrev_b32_e32 v2, 16, v226
	v_mul_f32_e32 v3, v3, v227
	v_mul_f32_e32 v5, 0xbfb8aa3b, v2
	v_exp_f32_e32 v5, v5
	s_nop 0
	v_add_f32_e32 v5, 1.0, v5
	v_rcp_f32_e32 v5, v5
	s_nop 0
	v_mul_f32_e32 v2, v5, v2
	v_mul_f32_e32 v2, v3, v2
	v_bfe_u32 v3, v2, 16, 1
	v_add3_u32 v2, v2, v3, s52
	global_store_short_d16_hi v4, v2, s[0:1] offset:640
	v_or_b32_e32 v2, 0x300, v4
	v_lshlrev_b32_e32 v2, 16, v229
	v_mul_f32_e32 v0, v0, v230
	v_mul_f32_e32 v3, 0xbfb8aa3b, v2
	v_exp_f32_e32 v3, v3
	s_nop 0
	v_add_f32_e32 v3, 1.0, v3
	v_rcp_f32_e32 v3, v3
	s_nop 0
	v_mul_f32_e32 v2, v3, v2
	v_mul_f32_e32 v0, v0, v2
	v_bfe_u32 v2, v0, 16, 1
	v_add3_u32 v0, v0, v2, s52
	global_store_short_d16_hi v4, v0, s[0:1] offset:768
	v_or_b32_e32 v0, 0x380, v4
	v_lshlrev_b32_e32 v0, 16, v232
	v_mul_f32_e32 v1, v1, v233
	v_mul_f32_e32 v2, 0xbfb8aa3b, v0
	v_exp_f32_e32 v2, v2
	s_nop 0
	v_add_f32_e32 v2, 1.0, v2
	v_rcp_f32_e32 v2, v2
	s_nop 0
	v_mul_f32_e32 v0, v2, v0
	v_mul_f32_e32 v0, v1, v0
	v_bfe_u32 v1, v0, 16, 1
	v_add3_u32 v0, v0, v1, s52
	global_store_short_d16_hi v4, v0, s[0:1] offset:896
	v_readlane_b32 s0, v254, 43
	v_readlane_b32 s1, v254, 44
	s_add_u32 s14, s14, s0
	s_addc_u32 s15, s15, s1
	s_waitcnt lgkmcnt(0)
	s_add_u32 s12, s12, s0
	s_addc_u32 s13, s13, s1
	s_cmpk_gt_i32 s18, 0x1ff
	s_barrier
	s_cbranch_scc1 .LBB0_669

; __device__ __forceinline__ float siluf(float x) { return x * __builtin_amdgcn_rcpf(1.0f + __expf(-x)); }
; __device__ __forceinline__ float logsig(float x) { return fminf(x, 0.f) - __logf(1.0f + __expf(-fabsf(x))); }
; template <int TY> __device__ __forceinline__ void sample_item(const Params& p, ldsp lds, int item) {
;     ...
;         float run = 0.f; float bt[8], qv[8], kv[8];
; #pragma unroll
;         for (int t = 0; t < 8; ++t) { float g;
;             if (TY == 0) { float x = bias;
; #pragma unroll
;                 for (int r = 0; r < 16; ++r) x += bf2f(Pb[(size_t)t * NE + E_LR + r]) * w2[r];
;                 g = logsig(x) * 0.0625f; qv[t] = bf2f(Pb[(size_t)t * NE + E_QA + h * 64 + d]) * 0.125f; kv[t] = bf2f(Pb[(size_t)t * NE + E_KA + h * 64 + d]);
;             } else if (TY == 1) { const float xf = bf2f(Pb[(size_t)t * NE + E_FB + h * 128 + d]); const float sig = __builtin_amdgcn_rcpf(1.0f + __expf(-xf));
;                 g = __logf(lbv + (1.0f - lbv) * sig); kv[t] = (1.0f - lbv) * __builtin_amdgcn_rcpf(1.0f + __expf(xf)); qv[t] = siluf(bf2f(Pb[(size_t)t * NE + E_QB + h * 128 + d]));
;             } else { g = lng; qv[t] = bf2f(Pb[(size_t)t * NO + O_Q + h * 256 + d]); kv[t] = bf2f(Pb[(size_t)t * NO + O_K + h * 256 + d]); }
;             run += g; bt[t] = run; }
; #pragma unroll
;         for (int t = 0; t < 8; ++t) { Bs[t * DK + d] = bt[t]; QR[t * DK + d] = qv[t]; KR[t * DK + d] = kv[t];
;             QK[d * 16 + t] = qv[t] * __expf(bt[t]); QK[d * 16 + 8 + t] = kv[t] * __expf(run - bt[t]); }
;         DECs[d] = __expf(run); }
.LBB0_692:
	s_or_b64 exec, exec, s[0:1]
	s_movk_i32 s0, 0x100
	v_cmp_gt_i32_e32 vcc, s0, v0
	v_ashrrev_i32_e32 v1, 31, v0
	v_lshl_add_u32 v2, v0, 2, 0
	s_and_saveexec_b64 s[8:9], vcc
	s_cbranch_execz .LBB0_694
	v_cvt_f32_ubyte0_e32 v3, s38
	v_sub_f32_e32 v3, 0xc0a00000, v3
	s_mov_b32 s0, 0xc2fc0000
	v_cmp_gt_f32_e32 vcc, s0, v3
	v_mov_b32_e32 v5, 0x42800000
	s_and_b64 s[0:1], vcc, exec
	v_cndmask_b32_e32 v5, 0, v5, vcc
	v_add_f32_e32 v3, v3, v5
	v_exp_f32_e32 v3, v3
	s_cselect_b32 s0, 0xffffffc0, 0
	v_ldexp_f32 v3, v3, s0
	v_sub_f32_e32 v3, 1.0, v3
	v_cmp_gt_f32_e32 vcc, s33, v3
	s_and_b64 s[0:1], vcc, exec
	s_cselect_b32 s0, 32, 0
	v_ldexp_f32 v3, v3, s0
	v_log_f32_e32 v3, v3
	s_mov_b32 s0, 0x3f317217
	v_mul_f32_e32 v5, 0x3f317217, v3
	v_fma_f32 v5, v3, s0, -v5
	v_fmac_f32_e32 v5, 0x3377d1cf, v3
	s_mov_b32 s0, 0x7f800000
	v_fmac_f32_e32 v5, 0x3f317217, v3
	v_cmp_lt_f32_e64 s[0:1], |v3|, s0
	s_nop 1
	v_cndmask_b32_e64 v3, v3, v5, s[0:1]
	s_add_u32 s0, s20, s36
	s_addc_u32 s1, s21, 0
	v_cndmask_b32_e32 v5, 0, v185, vcc
	v_lshl_add_u64 v[6:7], v[0:1], 1, s[0:1]
	v_lshlrev_b32_e32 v186, 1, v0
	v_add_u32_e32 v187, 0x3000, v186
	v_add_u32_e32 v188, 0x6000, v186
	v_add_u32_e32 v189, 0x9000, v186
	v_add_u32_e32 v190, 0xc000, v186
	v_add_u32_e32 v191, 0xf000, v186
	v_add_u32_e32 v192, 0x12000, v186
	v_add_u32_e32 v193, 0x15000, v186
	global_load_ushort v194, v186, s[0:1]
	global_load_ushort v202, v186, s[0:1] offset:2048
	global_load_ushort v195, v187, s[0:1]
	global_load_ushort v203, v187, s[0:1] offset:2048
	global_load_ushort v196, v188, s[0:1]
	global_load_ushort v204, v188, s[0:1] offset:2048
	global_load_ushort v197, v189, s[0:1]
	global_load_ushort v205, v189, s[0:1] offset:2048
	global_load_ushort v198, v190, s[0:1]
	global_load_ushort v206, v190, s[0:1] offset:2048
	global_load_ushort v199, v191, s[0:1]
	global_load_ushort v207, v191, s[0:1] offset:2048
	global_load_ushort v200, v192, s[0:1]
	global_load_ushort v208, v192, s[0:1] offset:2048
	global_load_ushort v201, v193, s[0:1]
	global_load_ushort v209, v193, s[0:1] offset:2048
	v_sub_f32_e32 v3, v3, v5
	s_movk_i32 s0, 0x6000
	v_add_f32_e32 v11, 0, v3
	v_add_f32_e32 v14, v3, v11
	v_add_f32_e32 v18, v3, v14
	v_mul_f32_e32 v30, 0x3fb8aa3b, v11
	v_add_f32_e32 v21, v3, v18
	v_exp_f32_e32 v30, v30
	v_add_f32_e32 v24, v3, v21
	v_add_f32_e32 v27, v3, v24
	s_waitcnt vmcnt(1)
	v_lshlrev_b32_e32 v5, 16, v194
	s_waitcnt vmcnt(0)
	v_lshlrev_b32_e32 v10, 16, v202
	v_add_co_u32_e32 v8, vcc, s56, v6
	s_nop 1
	v_addc_co_u32_e32 v9, vcc, 0, v7, vcc
	s_waitcnt vmcnt(0)
	v_lshlrev_b32_e32 v12, 16, v195
	s_waitcnt vmcnt(0)
	v_lshlrev_b32_e32 v13, 16, v203
	v_add_co_u32_e32 v8, vcc, s0, v6
	s_mov_b32 s0, 0x9000
	s_nop 0
	v_addc_co_u32_e32 v9, vcc, 0, v7, vcc
	s_waitcnt vmcnt(0)
	v_lshlrev_b32_e32 v15, 16, v196
	s_waitcnt vmcnt(0)
	v_lshlrev_b32_e32 v16, 16, v204
	v_add_co_u32_e32 v8, vcc, s0, v6
	s_mov_b32 s0, 0xc000
	s_nop 0
	v_addc_co_u32_e32 v9, vcc, 0, v7, vcc
	s_waitcnt vmcnt(0)
	v_lshlrev_b32_e32 v19, 16, v197
	s_waitcnt vmcnt(0)
	v_lshlrev_b32_e32 v20, 16, v205
	v_add_co_u32_e32 v8, vcc, s0, v6
	s_mov_b32 s0, 0xf000
	s_nop 0
	v_addc_co_u32_e32 v9, vcc, 0, v7, vcc
	s_waitcnt vmcnt(0)
	v_lshlrev_b32_e32 v22, 16, v198
	s_waitcnt vmcnt(0)
	v_lshlrev_b32_e32 v23, 16, v206
	v_add_co_u32_e32 v8, vcc, s0, v6
	s_mov_b32 s0, 0x12000
	s_nop 0
	v_addc_co_u32_e32 v9, vcc, 0, v7, vcc
	s_waitcnt vmcnt(0)
	v_lshlrev_b32_e32 v25, 16, v199
	s_waitcnt vmcnt(0)
	v_lshlrev_b32_e32 v26, 16, v207
	v_add_co_u32_e32 v8, vcc, s0, v6
	s_mov_b32 s0, 0x15000
	s_nop 0
	v_addc_co_u32_e32 v9, vcc, 0, v7, vcc
	v_add_co_u32_e32 v6, vcc, s0, v6
	s_nop 0
	v_addc_co_u32_e32 v7, vcc, 0, v7, vcc
	s_waitcnt vmcnt(1)
	v_lshlrev_b32_e32 v28, 16, v200
	s_waitcnt vmcnt(1)
	v_lshlrev_b32_e32 v29, 16, v201
	v_add_f32_e32 v9, v3, v27
	v_add_f32_e32 v3, v3, v9
	v_lshl_add_u32 v7, v0, 6, 0
	ds_write_b32 v2, v11 offset:16384
	ds_write_b32 v2, v5 offset:24576
	ds_write_b32 v2, v10 offset:32768
	v_mul_f32_e32 v5, v30, v5
	ds_write_b32 v7, v5
	v_sub_f32_e32 v5, v3, v11
	v_mul_f32_e32 v5, 0x3fb8aa3b, v5
	v_exp_f32_e32 v5, v5
	s_waitcnt vmcnt(1)
	v_lshlrev_b32_e32 v8, 16, v208
	v_mul_f32_e32 v5, v5, v10
	ds_write_b32 v7, v5 offset:32
	ds_write_b32 v2, v14 offset:17408
	ds_write_b32 v2, v12 offset:25600
	ds_write_b32 v2, v13 offset:33792
	v_mul_f32_e32 v5, 0x3fb8aa3b, v14
	v_exp_f32_e32 v5, v5
	s_waitcnt vmcnt(0)
	v_lshlrev_b32_e32 v6, 16, v209
	v_mul_f32_e32 v5, v5, v12
	ds_write_b32 v7, v5 offset:4
	v_sub_f32_e32 v5, v3, v14
	v_mul_f32_e32 v5, 0x3fb8aa3b, v5
	v_exp_f32_e32 v5, v5
	s_nop 0
	v_mul_f32_e32 v5, v5, v13
	ds_write_b32 v7, v5 offset:36
	ds_write_b32 v2, v18 offset:18432
	ds_write_b32 v2, v15 offset:26624
	ds_write_b32 v2, v16 offset:34816
	v_mul_f32_e32 v5, 0x3fb8aa3b, v18
	v_exp_f32_e32 v5, v5
	s_nop 0
	v_mul_f32_e32 v5, v5, v15
	ds_write_b32 v7, v5 offset:8
	v_sub_f32_e32 v5, v3, v18
	v_mul_f32_e32 v5, 0x3fb8aa3b, v5
	v_exp_f32_e32 v5, v5
	s_nop 0
	v_mul_f32_e32 v5, v5, v16
	ds_write_b32 v7, v5 offset:40
	ds_write_b32 v2, v21 offset:19456
	ds_write_b32 v2, v19 offset:27648
	ds_write_b32 v2, v20 offset:35840
	v_mul_f32_e32 v5, 0x3fb8aa3b, v21
	v_exp_f32_e32 v5, v5
	s_nop 0
	v_mul_f32_e32 v5, v5, v19
	ds_write_b32 v7, v5 offset:12
	v_sub_f32_e32 v5, v3, v21
	v_mul_f32_e32 v5, 0x3fb8aa3b, v5
	v_exp_f32_e32 v5, v5
	s_nop 0
	v_mul_f32_e32 v5, v5, v20
	ds_write_b32 v7, v5 offset:44
	ds_write_b32 v2, v24 offset:20480
	ds_write_b32 v2, v22 offset:28672
	ds_write_b32 v2, v23 offset:36864
	v_mul_f32_e32 v5, 0x3fb8aa3b, v24
	v_exp_f32_e32 v5, v5
	s_nop 0
	v_mul_f32_e32 v5, v5, v22
	ds_write_b32 v7, v5 offset:16
	v_sub_f32_e32 v5, v3, v24
	v_mul_f32_e32 v5, 0x3fb8aa3b, v5
	v_exp_f32_e32 v5, v5
	s_nop 0
	v_mul_f32_e32 v5, v5, v23
	ds_write_b32 v7, v5 offset:48
	ds_write_b32 v2, v27 offset:21504
	ds_write_b32 v2, v25 offset:29696
	ds_write_b32 v2, v26 offset:37888
	v_mul_f32_e32 v5, 0x3fb8aa3b, v27
	v_exp_f32_e32 v5, v5
	s_nop 0
	v_mul_f32_e32 v5, v5, v25
	ds_write_b32 v7, v5 offset:20
	v_sub_f32_e32 v5, v3, v27
	v_mul_f32_e32 v5, 0x3fb8aa3b, v5
	v_exp_f32_e32 v5, v5
	s_nop 0
	v_mul_f32_e32 v5, v5, v26
	ds_write_b32 v7, v5 offset:52
	ds_write_b32 v2, v9 offset:22528
	ds_write_b32 v2, v28 offset:30720
	ds_write_b32 v2, v8 offset:38912
	v_mul_f32_e32 v5, 0x3fb8aa3b, v9
	v_exp_f32_e32 v5, v5
	s_nop 0
	v_mul_f32_e32 v5, v5, v28
	ds_write_b32 v7, v5 offset:24
	v_sub_f32_e32 v5, v3, v9
	v_mul_f32_e32 v5, 0x3fb8aa3b, v5
	v_exp_f32_e32 v5, v5
	s_nop 0
	v_mul_f32_e32 v5, v5, v8
	ds_write_b32 v7, v5 offset:56
	ds_write_b32 v2, v3 offset:23552
	ds_write_b32 v2, v29 offset:31744
	ds_write_b32 v2, v6 offset:39936
	v_mul_f32_e32 v5, 0x3fb8aa3b, v3
	v_sub_f32_e32 v3, v3, v3
	v_mul_f32_e32 v3, 0x3fb8aa3b, v3
	v_exp_f32_e32 v5, v5
	v_exp_f32_e32 v3, v3
	v_mul_f32_e32 v8, v5, v29
	v_mul_f32_e32 v3, v3, v6
	ds_write_b32 v7, v8 offset:28
	ds_write_b32 v7, v3 offset:60
	ds_write_b32 v2, v5 offset:40960

; #define PG8_STAGE(bufoff, gbase, voff) do { _Pragma("unroll") for (int _i = 0; _i < 2; ++_i) \
;         __builtin_amdgcn_global_load_lds((const unsigned*)((const char*)(gbase) + (voff)[_i]), (PG8_LAS unsigned*)(lds + (bufoff) + ldsw + _i * 8192), 16, 0, 0); } while (0)
; #define PG8_LDA(dst, b, h) do { _Pragma("unroll") for (int m = 0; m < 4; ++m) _Pragma("unroll") for (int k = 0; k < 2; ++k) dst[m][k] = *(const PG8_LAS bf16x8*)(lds + PG8_SA(b, h) + aoff + m * 2048 + k * 1024); } while (0)
; #define PG8_LDB(dst, b, h) do { _Pragma("unroll") for (int n = 0; n < 2; ++n) _Pragma("unroll") for (int k = 0; k < 2; ++k) dst[n][k] = *(const PG8_LAS bf16x8*)(lds + PG8_SB(b, h) + boff + n * 2048 + k * 1024); } while (0)
; #define PG8_MMA(ai, bj, At, Bt) do { __builtin_amdgcn_s_setprio(1); _Pragma("unroll") for (int m = 0; m < 4; ++m) _Pragma("unroll") for (int n = 0; n < 2; ++n) _Pragma("unroll") for (int k = 0; k < 2; ++k) \
;         acc[ai][bj][m][n] = __builtin_amdgcn_mfma_f32_16x16x32_bf16(Bt[n][k], At[m][k], acc[ai][bj][m][n], 0, 0, 0); __builtin_amdgcn_s_setprio(0); } while (0)
; #define PG8_WAIT_V(n) asm volatile("s_waitcnt vmcnt(" #n ")" ::: "memory")
; #define PG8_WAIT_L(n) asm volatile("s_waitcnt lgkmcnt(" #n ")" ::: "memory")
; #define PG8_BAR __builtin_amdgcn_s_barrier()
; #define PG8_SCHED __builtin_amdgcn_sched_barrier(0)
; template <class Epi, class Sched, bool ALIGN_EPI = false, bool SP2 = false>
; __device__ __forceinline__ void gemm_phase(PG8_LAS unsigned char* lds, const Gemm g, const Sched& S, const Epi& E) {
;     ...
;             PG8_LDB(B0, 0, 0); PG8_LDB(B1, 0, 1); PG8_SCHED; PG8_LDA(At, 0, 0); PG8_STAGE(PG8_SA(1, 1), a1 + hstep, voffA);
;             PG8_WAIT_V(8); PG8_WAIT_L(0); PG8_BAR; PG8_MMA(0, 0, At, B0); PG8_MMA(0, 1, At, B1); PG8_BAR; PG8_SCHED;
;             PG8_LDA(At, 0, 1); PG8_STAGE(PG8_SB(0, 0), b2, voffB); PG8_STAGE(PG8_SB(0, 1), b2 + hstep, voffB); PG8_STAGE(PG8_SA(0, 0), a2, voffA);
;             PG8_WAIT_V(8); PG8_WAIT_L(0); PG8_BAR; PG8_MMA(1, 0, At, B0); PG8_MMA(1, 1, At, B1); PG8_BAR; PG8_SCHED;
.LBB0_913:
	s_add_u32 s36, s38, 0xfffc0080
	s_addc_u32 s37, s39, -1
	s_add_i32 s86, 0, 0x10000
	s_cmp_eq_u32 s85, 12
	s_cselect_b32 s61, s19, s37
	s_cselect_b32 s60, s83, s36
	s_cselect_b32 s37, s17, s84
	s_cselect_b32 s36, vcc_lo, vcc_hi
	s_add_i32 s88, 0, 0x14000
	v_add_u32_e32 v156, s86, v149
	v_add_u32_e32 v160, s88, v149
	ds_read_b128 v[134:137], v156
	ds_read_b128 v[144:147], v156 offset:1024
	ds_read_b128 v[152:155], v156 offset:2048
	ds_read_b128 v[156:159], v156 offset:3072
	ds_read_b128 v[172:175], v160
	ds_read_b128 v[176:179], v160 offset:1024
	ds_read_b128 v[180:183], v160 offset:2048
	ds_read_b128 v[186:189], v160 offset:3072
	v_lshl_add_u64 v[162:163], s[38:39], 0, v[142:143]
	s_add_i32 m0, s74, 0xc000
	ds_read_b128 v[190:193], v151
	ds_read_b128 v[194:197], v151 offset:1024
	ds_read_b128 v[198:201], v151 offset:2048
	ds_read_b128 v[202:205], v151 offset:3072
	ds_read_b128 v[206:209], v151 offset:4096
	ds_read_b128 v[210:213], v151 offset:5120
	ds_read_b128 v[214:217], v151 offset:6144
	ds_read_b128 v[218:221], v151 offset:7168
	global_load_lds_dwordx4 v[162:163], off
	v_lshl_add_u64 v[162:163], s[38:39], 0, v[140:141]
	s_add_i32 m0, s74, 0xe000
	s_nop 0
	global_load_lds_dwordx4 v[162:163], off
	s_waitcnt vmcnt(8)
	s_waitcnt lgkmcnt(0)
	s_barrier
	s_setprio 1
	s_waitcnt lgkmcnt(0)
	v_mfma_f32_16x16x32_bf16 v[126:129], v[134:137], v[190:193], v[126:129]
	v_mfma_f32_16x16x32_bf16 v[122:125], v[152:155], v[190:193], v[122:125]
	v_mfma_f32_16x16x32_bf16 v[110:113], v[134:137], v[198:201], v[110:113]
	v_mfma_f32_16x16x32_bf16 v[106:109], v[152:155], v[198:201], v[106:109]
	v_mfma_f32_16x16x32_bf16 v[94:97], v[134:137], v[206:209], v[94:97]
	v_mfma_f32_16x16x32_bf16 v[90:93], v[152:155], v[206:209], v[90:93]
	v_mfma_f32_16x16x32_bf16 v[78:81], v[134:137], v[214:217], v[78:81]
	v_mfma_f32_16x16x32_bf16 v[74:77], v[152:155], v[214:217], v[74:77]
	v_mfma_f32_16x16x32_bf16 v[126:129], v[144:147], v[194:197], v[126:129]
	v_mfma_f32_16x16x32_bf16 v[122:125], v[156:159], v[194:197], v[122:125]
	v_mfma_f32_16x16x32_bf16 v[110:113], v[144:147], v[202:205], v[110:113]
	v_mfma_f32_16x16x32_bf16 v[106:109], v[156:159], v[202:205], v[106:109]
	v_mfma_f32_16x16x32_bf16 v[94:97], v[144:147], v[210:213], v[94:97]
	v_mfma_f32_16x16x32_bf16 v[90:93], v[156:159], v[210:213], v[90:93]
	v_mfma_f32_16x16x32_bf16 v[78:81], v[144:147], v[218:221], v[78:81]
	v_mfma_f32_16x16x32_bf16 v[74:77], v[156:159], v[218:221], v[74:77]
	s_setprio 0
	s_setprio 1
	v_mfma_f32_16x16x32_bf16 v[118:121], v[172:175], v[190:193], v[118:121]
	v_mfma_f32_16x16x32_bf16 v[114:117], v[180:183], v[190:193], v[114:117]
	v_mfma_f32_16x16x32_bf16 v[102:105], v[172:175], v[198:201], v[102:105]
	v_mfma_f32_16x16x32_bf16 v[98:101], v[180:183], v[198:201], v[98:101]
	v_mfma_f32_16x16x32_bf16 v[86:89], v[172:175], v[206:209], v[86:89]
	v_mfma_f32_16x16x32_bf16 v[82:85], v[180:183], v[206:209], v[82:85]
	v_mfma_f32_16x16x32_bf16 v[70:73], v[172:175], v[214:217], v[70:73]
	v_mfma_f32_16x16x32_bf16 v[66:69], v[180:183], v[214:217], v[66:69]
	v_mfma_f32_16x16x32_bf16 v[118:121], v[176:179], v[194:197], v[118:121]
	v_mfma_f32_16x16x32_bf16 v[114:117], v[186:189], v[194:197], v[114:117]
	v_mfma_f32_16x16x32_bf16 v[102:105], v[176:179], v[202:205], v[102:105]
	v_mfma_f32_16x16x32_bf16 v[98:101], v[186:189], v[202:205], v[98:101]
	v_mfma_f32_16x16x32_bf16 v[86:89], v[176:179], v[210:213], v[86:89]
	v_mfma_f32_16x16x32_bf16 v[82:85], v[186:189], v[210:213], v[82:85]
	v_mfma_f32_16x16x32_bf16 v[70:73], v[176:179], v[218:221], v[70:73]
	v_mfma_f32_16x16x32_bf16 v[66:69], v[186:189], v[218:221], v[66:69]
	s_setprio 0
	s_barrier
	s_add_i32 s86, s86, s67
	v_lshl_add_u64 v[162:163], s[36:37], 0, v[16:17]
	s_mov_b32 m0, s86
	ds_read_b128 v[190:193], v151 offset:16384
	ds_read_b128 v[194:197], v151 offset:17408
	ds_read_b128 v[198:201], v151 offset:18432
	ds_read_b128 v[202:205], v151 offset:19456
	ds_read_b128 v[206:209], v151 offset:20480
	ds_read_b128 v[210:213], v151 offset:21504
	ds_read_b128 v[214:217], v151 offset:22528
	ds_read_b128 v[218:221], v151 offset:23552
	global_load_lds_dwordx4 v[162:163], off
	s_add_i32 m0, s86, 0x2000
	s_add_u32 s86, s36, 0x40000
	v_lshl_add_u64 v[166:167], s[36:37], 0, v[130:131]
	s_addc_u32 s87, s37, 0
	s_add_i32 s88, s88, s67
	global_load_lds_dwordx4 v[166:167], off
	v_lshl_add_u64 v[168:169], s[86:87], 0, v[16:17]
	s_mov_b32 m0, s88
	v_lshl_add_u64 v[222:223], s[60:61], 0, v[132:133]
	global_load_lds_dwordx4 v[168:169], off
	v_lshl_add_u64 v[168:169], s[86:87], 0, v[130:131]
	s_add_i32 m0, s88, 0x2000
	s_nop 0
	global_load_lds_dwordx4 v[168:169], off
	v_lshl_add_u64 v[168:169], s[60:61], 0, v[138:139]
	s_mov_b32 m0, s74
	s_nop 0
	global_load_lds_dwordx4 v[168:169], off
	s_mov_b32 m0, s75
	s_nop 0
	global_load_lds_dwordx4 v[222:223], off
	s_waitcnt vmcnt(8)
	s_waitcnt lgkmcnt(0)
	s_barrier
; #define PG8_STAGE(bufoff, gbase, voff) do { _Pragma("unroll") for (int _i = 0; _i < 2; ++_i) \
;         __builtin_amdgcn_global_load_lds((const unsigned*)((const char*)(gbase) + (voff)[_i]), (PG8_LAS unsigned*)(lds + (bufoff) + ldsw + _i * 8192), 16, 0, 0); } while (0)
; #define PG8_LDA(dst, b, h) do { _Pragma("unroll") for (int m = 0; m < 4; ++m) _Pragma("unroll") for (int k = 0; k < 2; ++k) dst[m][k] = *(const PG8_LAS bf16x8*)(lds + PG8_SA(b, h) + aoff + m * 2048 + k * 1024); } while (0)
; #define PG8_LDB(dst, b, h) do { _Pragma("unroll") for (int n = 0; n < 2; ++n) _Pragma("unroll") for (int k = 0; k < 2; ++k) dst[n][k] = *(const PG8_LAS bf16x8*)(lds + PG8_SB(b, h) + boff + n * 2048 + k * 1024); } while (0)
; #define PG8_MMA(ai, bj, At, Bt) do { __builtin_amdgcn_s_setprio(1); _Pragma("unroll") for (int m = 0; m < 4; ++m) _Pragma("unroll") for (int n = 0; n < 2; ++n) _Pragma("unroll") for (int k = 0; k < 2; ++k) \
;         acc[ai][bj][m][n] = __builtin_amdgcn_mfma_f32_16x16x32_bf16(Bt[n][k], At[m][k], acc[ai][bj][m][n], 0, 0, 0); __builtin_amdgcn_s_setprio(0); } while (0)
; #define PG8_WAIT_V(n) asm volatile("s_waitcnt vmcnt(" #n ")" ::: "memory")
; #define PG8_WAIT_L(n) asm volatile("s_waitcnt lgkmcnt(" #n ")" ::: "memory")
; #define PG8_BAR __builtin_amdgcn_s_barrier()
; #define PG8_SCHED __builtin_amdgcn_sched_barrier(0)
; template <class Epi, class Sched, bool ALIGN_EPI = false, bool SP2 = false>
; __device__ __forceinline__ void gemm_phase(PG8_LAS unsigned char* lds, const Gemm g, const Sched& S, const Epi& E) {
;     ...
;             PG8_WAIT_V(8); PG8_WAIT_L(0); PG8_BAR; PG8_MMA(1, 0, At, B0); PG8_MMA(1, 1, At, B1); PG8_BAR; PG8_SCHED;
;             PG8_LDB(B0, 1, 0); PG8_LDB(B1, 1, 1); PG8_SCHED; PG8_LDA(At, 1, 0); PG8_STAGE(PG8_SA(0, 1), a2 + hstep, voffA);
;             PG8_WAIT_V(8); PG8_WAIT_L(0); PG8_BAR; PG8_MMA(0, 0, At, B0); PG8_MMA(0, 1, At, B1); PG8_BAR; PG8_SCHED;
	s_setprio 1
	s_waitcnt lgkmcnt(0)
	v_mfma_f32_16x16x32_bf16 v[62:65], v[134:137], v[190:193], v[62:65]
	v_mfma_f32_16x16x32_bf16 v[58:61], v[152:155], v[190:193], v[58:61]
	v_mfma_f32_16x16x32_bf16 v[46:49], v[134:137], v[198:201], v[46:49]
	v_mfma_f32_16x16x32_bf16 v[42:45], v[152:155], v[198:201], v[42:45]
	v_mfma_f32_16x16x32_bf16 v[30:33], v[134:137], v[206:209], v[30:33]
	v_mfma_f32_16x16x32_bf16 v[26:29], v[152:155], v[206:209], v[26:29]
	v_mfma_f32_16x16x32_bf16 v[12:15], v[134:137], v[214:217], v[12:15]
	v_mfma_f32_16x16x32_bf16 v[8:11], v[152:155], v[214:217], v[8:11]
	v_mfma_f32_16x16x32_bf16 v[62:65], v[144:147], v[194:197], v[62:65]
	v_mfma_f32_16x16x32_bf16 v[58:61], v[156:159], v[194:197], v[58:61]
	v_mfma_f32_16x16x32_bf16 v[46:49], v[144:147], v[202:205], v[46:49]
	v_mfma_f32_16x16x32_bf16 v[42:45], v[156:159], v[202:205], v[42:45]
	v_mfma_f32_16x16x32_bf16 v[30:33], v[144:147], v[210:213], v[30:33]
	v_mfma_f32_16x16x32_bf16 v[26:29], v[156:159], v[210:213], v[26:29]
	v_mfma_f32_16x16x32_bf16 v[12:15], v[144:147], v[218:221], v[12:15]
	v_mfma_f32_16x16x32_bf16 v[8:11], v[156:159], v[218:221], v[8:11]
	s_setprio 0
	s_setprio 1
	v_mfma_f32_16x16x32_bf16 v[54:57], v[172:175], v[190:193], v[54:57]
	v_mfma_f32_16x16x32_bf16 v[50:53], v[180:183], v[190:193], v[50:53]
	v_mfma_f32_16x16x32_bf16 v[38:41], v[172:175], v[198:201], v[38:41]
	v_mfma_f32_16x16x32_bf16 v[34:37], v[180:183], v[198:201], v[34:37]
	v_mfma_f32_16x16x32_bf16 v[22:25], v[172:175], v[206:209], v[22:25]
	v_mfma_f32_16x16x32_bf16 v[18:21], v[180:183], v[206:209], v[18:21]
	v_mfma_f32_16x16x32_bf16 v[4:7], v[172:175], v[214:217], v[4:7]
	v_mfma_f32_16x16x32_bf16 v[0:3], v[180:183], v[214:217], v[0:3]
	v_mfma_f32_16x16x32_bf16 v[54:57], v[176:179], v[194:197], v[54:57]
	v_mfma_f32_16x16x32_bf16 v[50:53], v[186:189], v[194:197], v[50:53]
	v_mfma_f32_16x16x32_bf16 v[38:41], v[176:179], v[202:205], v[38:41]
	v_mfma_f32_16x16x32_bf16 v[34:37], v[186:189], v[202:205], v[34:37]
	v_mfma_f32_16x16x32_bf16 v[22:25], v[176:179], v[210:213], v[22:25]
	v_mfma_f32_16x16x32_bf16 v[18:21], v[186:189], v[210:213], v[18:21]
	v_mfma_f32_16x16x32_bf16 v[4:7], v[176:179], v[218:221], v[4:7]
	v_mfma_f32_16x16x32_bf16 v[0:3], v[186:189], v[218:221], v[0:3]
	s_setprio 0
	s_barrier
	s_add_i32 s86, 0, 0x18000
	s_add_i32 s87, 0, 0x1c000
	v_add_u32_e32 v156, s86, v149
	v_add_u32_e32 v160, s87, v149
	ds_read_b128 v[134:137], v156
	ds_read_b128 v[144:147], v156 offset:1024
	ds_read_b128 v[152:155], v156 offset:2048
	ds_read_b128 v[156:159], v156 offset:3072
	ds_read_b128 v[172:175], v160
	ds_read_b128 v[176:179], v160 offset:1024
	ds_read_b128 v[180:183], v160 offset:2048
	ds_read_b128 v[186:189], v160 offset:3072
	s_add_u32 s60, s60, 0x40000
	s_addc_u32 s61, s61, 0
	s_mov_b32 m0, s76
	v_lshl_add_u64 v[224:225], s[60:61], 0, v[138:139]
	ds_read_b128 v[190:193], v151 offset:32768
	ds_read_b128 v[194:197], v151 offset:33792
	ds_read_b128 v[198:201], v151 offset:34816
	ds_read_b128 v[202:205], v151 offset:35840
	ds_read_b128 v[206:209], v151 offset:36864
	ds_read_b128 v[210:213], v151 offset:37888
	ds_read_b128 v[214:217], v151 offset:38912
	ds_read_b128 v[218:221], v151 offset:39936
	global_load_lds_dwordx4 v[224:225], off
	v_lshl_add_u64 v[224:225], s[60:61], 0, v[132:133]
	s_mov_b32 m0, s77
	s_nop 0
	global_load_lds_dwordx4 v[224:225], off
	s_waitcnt vmcnt(8)
	s_waitcnt lgkmcnt(0)
	s_barrier
	s_setprio 1
	s_waitcnt lgkmcnt(0)
	v_mfma_f32_16x16x32_bf16 v[126:129], v[134:137], v[190:193], v[126:129]
	v_mfma_f32_16x16x32_bf16 v[122:125], v[152:155], v[190:193], v[122:125]
	v_mfma_f32_16x16x32_bf16 v[110:113], v[134:137], v[198:201], v[110:113]
	v_mfma_f32_16x16x32_bf16 v[106:109], v[152:155], v[198:201], v[106:109]
	v_mfma_f32_16x16x32_bf16 v[94:97], v[134:137], v[206:209], v[94:97]
	v_mfma_f32_16x16x32_bf16 v[90:93], v[152:155], v[206:209], v[90:93]
	v_mfma_f32_16x16x32_bf16 v[78:81], v[134:137], v[214:217], v[78:81]
	v_mfma_f32_16x16x32_bf16 v[74:77], v[152:155], v[214:217], v[74:77]
	v_mfma_f32_16x16x32_bf16 v[126:129], v[144:147], v[194:197], v[126:129]
	v_mfma_f32_16x16x32_bf16 v[122:125], v[156:159], v[194:197], v[122:125]
	v_mfma_f32_16x16x32_bf16 v[110:113], v[144:147], v[202:205], v[110:113]
	v_mfma_f32_16x16x32_bf16 v[106:109], v[156:159], v[202:205], v[106:109]
	v_mfma_f32_16x16x32_bf16 v[94:97], v[144:147], v[210:213], v[94:97]
	v_mfma_f32_16x16x32_bf16 v[90:93], v[156:159], v[210:213], v[90:93]
	v_mfma_f32_16x16x32_bf16 v[78:81], v[144:147], v[218:221], v[78:81]
	v_mfma_f32_16x16x32_bf16 v[74:77], v[156:159], v[218:221], v[74:77]
	s_setprio 0
	s_setprio 1
	v_mfma_f32_16x16x32_bf16 v[118:121], v[172:175], v[190:193], v[118:121]
	v_mfma_f32_16x16x32_bf16 v[114:117], v[180:183], v[190:193], v[114:117]
	v_mfma_f32_16x16x32_bf16 v[102:105], v[172:175], v[198:201], v[102:105]
	v_mfma_f32_16x16x32_bf16 v[98:101], v[180:183], v[198:201], v[98:101]
	v_mfma_f32_16x16x32_bf16 v[86:89], v[172:175], v[206:209], v[86:89]
	v_mfma_f32_16x16x32_bf16 v[82:85], v[180:183], v[206:209], v[82:85]
	v_mfma_f32_16x16x32_bf16 v[70:73], v[172:175], v[214:217], v[70:73]
	v_mfma_f32_16x16x32_bf16 v[66:69], v[180:183], v[214:217], v[66:69]
	v_mfma_f32_16x16x32_bf16 v[118:121], v[176:179], v[194:197], v[118:121]
	v_mfma_f32_16x16x32_bf16 v[114:117], v[186:189], v[194:197], v[114:117]
	v_mfma_f32_16x16x32_bf16 v[102:105], v[176:179], v[202:205], v[102:105]
	v_mfma_f32_16x16x32_bf16 v[98:101], v[186:189], v[202:205], v[98:101]
	v_mfma_f32_16x16x32_bf16 v[86:89], v[176:179], v[210:213], v[86:89]
	v_mfma_f32_16x16x32_bf16 v[82:85], v[186:189], v[210:213], v[82:85]
	v_mfma_f32_16x16x32_bf16 v[70:73], v[176:179], v[218:221], v[70:73]
	v_mfma_f32_16x16x32_bf16 v[66:69], v[186:189], v[218:221], v[66:69]
	s_setprio 0
	s_barrier
; #define PG8_STAGE(bufoff, gbase, voff) do { _Pragma("unroll") for (int _i = 0; _i < 2; ++_i) \
;         __builtin_amdgcn_global_load_lds((const unsigned*)((const char*)(gbase) + (voff)[_i]), (PG8_LAS unsigned*)(lds + (bufoff) + ldsw + _i * 8192), 16, 0, 0); } while (0)
; #define PG8_LDA(dst, b, h) do { _Pragma("unroll") for (int m = 0; m < 4; ++m) _Pragma("unroll") for (int k = 0; k < 2; ++k) dst[m][k] = *(const PG8_LAS bf16x8*)(lds + PG8_SA(b, h) + aoff + m * 2048 + k * 1024); } while (0)
; #define PG8_MMA(ai, bj, At, Bt) do { __builtin_amdgcn_s_setprio(1); _Pragma("unroll") for (int m = 0; m < 4; ++m) _Pragma("unroll") for (int n = 0; n < 2; ++n) _Pragma("unroll") for (int k = 0; k < 2; ++k) \
;         acc[ai][bj][m][n] = __builtin_amdgcn_mfma_f32_16x16x32_bf16(Bt[n][k], At[m][k], acc[ai][bj][m][n], 0, 0, 0); __builtin_amdgcn_s_setprio(0); } while (0)
; #define PG8_WAIT_V(n) asm volatile("s_waitcnt vmcnt(" #n ")" ::: "memory")
; #define PG8_WAIT_L(n) asm volatile("s_waitcnt lgkmcnt(" #n ")" ::: "memory")
; #define PG8_BAR __builtin_amdgcn_s_barrier()
; #define PG8_SCHED __builtin_amdgcn_sched_barrier(0)
;     __device__ __forceinline__ void operator()(const f32x4 (&acc)[2][2][4][2], const Unit& u, int wr, int wc, int fr, int fq) const {
;     ...
;             for (int m = 0; m < 4; ++m) { const int row = row0 + ai * HALF + m * 16; const float s = rs[row];
; template <class Epi, class Sched, bool ALIGN_EPI = false, bool SP2 = false>
; __device__ __forceinline__ void gemm_phase(PG8_LAS unsigned char* lds, const Gemm g, const Sched& S, const Epi& E) {
;     ...
;             PG8_LDA(At, 1, 1); PG8_STAGE(PG8_SB(1, 0), b3, voffB); PG8_STAGE(PG8_SB(1, 1), b3 + hstep, voffB); PG8_STAGE(PG8_SA(1, 0), a3, voffA);
;             PG8_WAIT_V(8); PG8_WAIT_L(0); PG8_BAR; PG8_MMA(1, 0, At, B0); PG8_MMA(1, 1, At, B1); PG8_BAR; PG8_SCHED;
	s_add_i32 s60, s86, s67
	v_lshl_add_u64 v[162:163], v[162:163], 0, s[42:43]
	s_mov_b32 m0, s60
	ds_read_b128 v[190:193], v151 offset:49152
	ds_read_b128 v[194:197], v151 offset:50176
	ds_read_b128 v[198:201], v151 offset:51200
	ds_read_b128 v[202:205], v151 offset:52224
	ds_read_b128 v[206:209], v151 offset:53248
	ds_read_b128 v[210:213], v151 offset:54272
	ds_read_b128 v[214:217], v151 offset:55296
	ds_read_b128 v[218:221], v151 offset:56320
	global_load_lds_dwordx4 v[162:163], off
	s_add_i32 m0, s60, 0x2000
	s_add_u32 s36, s36, 0x40080
	v_lshl_add_u64 v[162:163], v[166:167], 0, s[42:43]
	s_addc_u32 s37, s37, 0
	s_add_i32 s60, s87, s67
	global_load_lds_dwordx4 v[162:163], off
	v_lshl_add_u64 v[162:163], s[36:37], 0, v[16:17]
	s_mov_b32 m0, s60
	s_nop 0
	global_load_lds_dwordx4 v[162:163], off
	v_lshl_add_u64 v[162:163], s[36:37], 0, v[130:131]
	s_add_i32 m0, s60, 0x2000
	s_nop 0
	global_load_lds_dwordx4 v[162:163], off
	v_lshl_add_u64 v[162:163], v[168:169], 0, s[42:43]
	s_mov_b32 m0, s78
	s_nop 0
	global_load_lds_dwordx4 v[162:163], off
	v_lshl_add_u64 v[162:163], v[222:223], 0, s[42:43]
	s_mov_b32 m0, s79
	s_nop 0
	global_load_lds_dwordx4 v[162:163], off
	s_waitcnt vmcnt(8)
	s_waitcnt lgkmcnt(0)
	s_barrier
	s_setprio 1
	s_waitcnt lgkmcnt(0)
	v_mfma_f32_16x16x32_bf16 v[62:65], v[134:137], v[190:193], v[62:65]
	v_mfma_f32_16x16x32_bf16 v[58:61], v[152:155], v[190:193], v[58:61]
	v_mfma_f32_16x16x32_bf16 v[46:49], v[134:137], v[198:201], v[46:49]
	v_mfma_f32_16x16x32_bf16 v[42:45], v[152:155], v[198:201], v[42:45]
	v_mfma_f32_16x16x32_bf16 v[30:33], v[134:137], v[206:209], v[30:33]
	v_mfma_f32_16x16x32_bf16 v[26:29], v[152:155], v[206:209], v[26:29]
	v_mfma_f32_16x16x32_bf16 v[12:15], v[134:137], v[214:217], v[12:15]
	v_mfma_f32_16x16x32_bf16 v[8:11], v[152:155], v[214:217], v[8:11]
	v_mfma_f32_16x16x32_bf16 v[62:65], v[144:147], v[194:197], v[62:65]
	v_mfma_f32_16x16x32_bf16 v[58:61], v[156:159], v[194:197], v[58:61]
	v_mfma_f32_16x16x32_bf16 v[46:49], v[144:147], v[202:205], v[46:49]
	v_mfma_f32_16x16x32_bf16 v[42:45], v[156:159], v[202:205], v[42:45]
	v_mfma_f32_16x16x32_bf16 v[30:33], v[144:147], v[210:213], v[30:33]
	v_mfma_f32_16x16x32_bf16 v[26:29], v[156:159], v[210:213], v[26:29]
	v_mfma_f32_16x16x32_bf16 v[12:15], v[144:147], v[218:221], v[12:15]
	v_mfma_f32_16x16x32_bf16 v[8:11], v[156:159], v[218:221], v[8:11]
	s_setprio 0
	s_setprio 1
	v_mfma_f32_16x16x32_bf16 v[54:57], v[172:175], v[190:193], v[54:57]
	v_mfma_f32_16x16x32_bf16 v[50:53], v[180:183], v[190:193], v[50:53]
	v_mfma_f32_16x16x32_bf16 v[38:41], v[172:175], v[198:201], v[38:41]
	v_mfma_f32_16x16x32_bf16 v[34:37], v[180:183], v[198:201], v[34:37]
	v_mfma_f32_16x16x32_bf16 v[22:25], v[172:175], v[206:209], v[22:25]
	v_mfma_f32_16x16x32_bf16 v[18:21], v[180:183], v[206:209], v[18:21]
	v_mfma_f32_16x16x32_bf16 v[4:7], v[172:175], v[214:217], v[4:7]
	v_mfma_f32_16x16x32_bf16 v[0:3], v[180:183], v[214:217], v[0:3]
	v_mfma_f32_16x16x32_bf16 v[54:57], v[176:179], v[194:197], v[54:57]
	v_mfma_f32_16x16x32_bf16 v[50:53], v[186:189], v[194:197], v[50:53]
	v_mfma_f32_16x16x32_bf16 v[38:41], v[176:179], v[202:205], v[38:41]
	v_mfma_f32_16x16x32_bf16 v[34:37], v[186:189], v[202:205], v[34:37]
	v_mfma_f32_16x16x32_bf16 v[22:25], v[176:179], v[210:213], v[22:25]
	v_mfma_f32_16x16x32_bf16 v[18:21], v[186:189], v[210:213], v[18:21]
	v_mfma_f32_16x16x32_bf16 v[4:7], v[176:179], v[218:221], v[4:7]
	v_mfma_f32_16x16x32_bf16 v[0:3], v[186:189], v[218:221], v[0:3]
	s_setprio 0
	s_barrier
	s_add_i32 s85, s85, 2
	s_add_u32 vcc_hi, vcc_hi, 0x100
	s_addc_u32 s84, s84, 0
	s_add_u32 s38, s38, 0x100
	s_addc_u32 s39, s39, 0
	s_cmp_gt_u32 s85, 13
	s_cbranch_scc0 .LBB0_913
	v_lshl_add_u32 v144, s82, 8, v148
	v_ashrrev_i32_e32 v145, 31, v144
	v_lshl_add_u64 v[146:147], v[144:145], 2, s[12:13]
	global_load_dword v202, v[146:147], off
	global_load_dword v204, v[146:147], off offset:64
	global_load_dword v206, v[146:147], off offset:128
	global_load_dword v208, v[146:147], off offset:192
	global_load_dword v210, v[146:147], off offset:512
	global_load_dword v212, v[146:147], off offset:576
	global_load_dword v214, v[146:147], off offset:640
	global_load_dword v216, v[146:147], off offset:704
	s_and_b64 vcc, exec, s[14:15]
	v_readlane_b32 s61, v253, 30
	s_movk_i32 s60, 0x1ff
	s_cbranch_vccz .LBB0_916
	s_barrier
; __device__ __forceinline__ unsigned cvt_pk_bf16(float lo, float hi) { unsigned r; asm volatile("v_cvt_pk_bf16_f32 %0, %1, %2" : "=v"(r) : "v"(lo), "v"(hi)); return r; }
;     __device__ __forceinline__ void operator()(const f32x4 (&acc)[2][2][4][2], const Unit& u, int wr, int wc, int fr, int fq) const {
;         const int row0 = u.pm * BM + wr * 64 + fr, col0 = u.pn * BM + wc * 32 + 8 * fq;
; #pragma unroll
;         for (int ai = 0; ai < 2; ++ai)
; #pragma unroll
;             for (int m = 0; m < 4; ++m) { const int row = row0 + ai * HALF + m * 16; const float s = rs[row];
; #pragma unroll
;                 for (int bj = 0; bj < 2; ++bj) { const f32x4 v0 = acc[ai][bj][m][0] * s, v1 = acc[ai][bj][m][1] * s; u32x4 w;
;                     w.x = cvt_pk_bf16(v0[0], v0[1]); w.y = cvt_pk_bf16(v0[2], v0[3]); w.z = cvt_pk_bf16(v1[0], v1[1]); w.w = cvt_pk_bf16(v1[2], v1[3]);
;                     *(u32x4*)(O + (size_t)row * ldc + col0 + bj * HALF) = w; } }
.LBB0_916:
	v_lshl_or_b32 v134, s81, 8, v150
	v_ashrrev_i32_e32 v135, 31, v134
	s_andn2_b64 vcc, exec, s[10:11]
	s_waitcnt vmcnt(7)
	v_pk_mul_f32 v[128:129], v[128:129], v[202:203] op_sel_hi:[1,0]
	v_pk_mul_f32 v[126:127], v[126:127], v[202:203] op_sel_hi:[1,0]
	v_pk_mul_f32 v[122:123], v[122:123], v[202:203] op_sel_hi:[1,0]
	v_pk_mul_f32 v[124:125], v[124:125], v[202:203] op_sel_hi:[1,0]
	v_cvt_pk_bf16_f32 v126, v126, v127
	v_cvt_pk_bf16_f32 v127, v128, v129
	v_cvt_pk_bf16_f32 v128, v122, v123
	v_mov_b64_e32 v[122:123], s[8:9]
	v_cvt_pk_bf16_f32 v129, v124, v125
	v_mad_i64_i32 v[152:153], s[36:37], v144, s55, v[122:123]
	v_lshlrev_b64 v[124:125], 1, v[134:135]
	v_lshl_add_u64 v[134:135], v[152:153], 0, v[124:125]
	global_store_dwordx4 v[134:135], v[126:129], off
	v_pk_mul_f32 v[118:119], v[118:119], v[202:203] op_sel_hi:[1,0]
	v_pk_mul_f32 v[120:121], v[120:121], v[202:203] op_sel_hi:[1,0]
	v_pk_mul_f32 v[126:127], v[116:117], v[202:203] op_sel_hi:[1,0]
	v_pk_mul_f32 v[116:117], v[114:115], v[202:203] op_sel_hi:[1,0]
	v_cvt_pk_bf16_f32 v114, v118, v119
	v_cvt_pk_bf16_f32 v115, v120, v121
	s_nop 0
	v_cvt_pk_bf16_f32 v116, v116, v117
	v_cvt_pk_bf16_f32 v117, v126, v127
	global_store_dwordx4 v[134:135], v[114:117], off offset:256
	s_nop 1
	v_or_b32_e32 v114, 16, v144
	s_waitcnt vmcnt(8)
	v_pk_mul_f32 v[110:111], v[110:111], v[204:205] op_sel_hi:[1,0]
	v_pk_mul_f32 v[118:119], v[108:109], v[204:205] op_sel_hi:[1,0]
	v_pk_mul_f32 v[108:109], v[106:107], v[204:205] op_sel_hi:[1,0]
	v_cvt_pk_bf16_f32 v106, v110, v111
	v_mad_i64_i32 v[110:111], s[36:37], v114, s55, v[122:123]
	v_pk_mul_f32 v[112:113], v[112:113], v[204:205] op_sel_hi:[1,0]
	v_lshl_add_u64 v[110:111], v[110:111], 0, v[124:125]
	v_cvt_pk_bf16_f32 v107, v112, v113
	v_cvt_pk_bf16_f32 v108, v108, v109
	v_cvt_pk_bf16_f32 v109, v118, v119
	global_store_dwordx4 v[110:111], v[106:109], off
	v_pk_mul_f32 v[102:103], v[102:103], v[204:205] op_sel_hi:[1,0]
	v_pk_mul_f32 v[104:105], v[104:105], v[204:205] op_sel_hi:[1,0]
	v_pk_mul_f32 v[106:107], v[100:101], v[204:205] op_sel_hi:[1,0]
	v_pk_mul_f32 v[100:101], v[98:99], v[204:205] op_sel_hi:[1,0]
	v_cvt_pk_bf16_f32 v98, v102, v103
	v_cvt_pk_bf16_f32 v99, v104, v105
	s_nop 0
	v_cvt_pk_bf16_f32 v100, v100, v101
	v_cvt_pk_bf16_f32 v101, v106, v107
	global_store_dwordx4 v[110:111], v[98:101], off offset:256
	s_nop 1
	v_or_b32_e32 v98, 32, v144
	s_waitcnt vmcnt(9)
	v_pk_mul_f32 v[94:95], v[94:95], v[206:207] op_sel_hi:[1,0]
	v_pk_mul_f32 v[102:103], v[92:93], v[206:207] op_sel_hi:[1,0]
	v_pk_mul_f32 v[92:93], v[90:91], v[206:207] op_sel_hi:[1,0]
	v_cvt_pk_bf16_f32 v90, v94, v95
	v_mad_i64_i32 v[94:95], s[36:37], v98, s55, v[122:123]
	v_pk_mul_f32 v[96:97], v[96:97], v[206:207] op_sel_hi:[1,0]
	v_lshl_add_u64 v[94:95], v[94:95], 0, v[124:125]
	v_cvt_pk_bf16_f32 v91, v96, v97
	v_cvt_pk_bf16_f32 v92, v92, v93
	v_cvt_pk_bf16_f32 v93, v102, v103
	global_store_dwordx4 v[94:95], v[90:93], off
	v_pk_mul_f32 v[86:87], v[86:87], v[206:207] op_sel_hi:[1,0]
	v_pk_mul_f32 v[88:89], v[88:89], v[206:207] op_sel_hi:[1,0]
	v_pk_mul_f32 v[90:91], v[84:85], v[206:207] op_sel_hi:[1,0]
	v_pk_mul_f32 v[84:85], v[82:83], v[206:207] op_sel_hi:[1,0]
	v_cvt_pk_bf16_f32 v82, v86, v87
	v_cvt_pk_bf16_f32 v83, v88, v89
	s_nop 0
	v_cvt_pk_bf16_f32 v84, v84, v85
	v_cvt_pk_bf16_f32 v85, v90, v91
	global_store_dwordx4 v[94:95], v[82:85], off offset:256
	s_nop 1
	v_or_b32_e32 v82, 48, v144
	s_waitcnt vmcnt(10)
	v_pk_mul_f32 v[78:79], v[78:79], v[208:209] op_sel_hi:[1,0]
	v_pk_mul_f32 v[86:87], v[76:77], v[208:209] op_sel_hi:[1,0]
	v_pk_mul_f32 v[76:77], v[74:75], v[208:209] op_sel_hi:[1,0]
	v_cvt_pk_bf16_f32 v74, v78, v79
	v_mad_i64_i32 v[78:79], s[36:37], v82, s55, v[122:123]
	v_pk_mul_f32 v[80:81], v[80:81], v[208:209] op_sel_hi:[1,0]
	v_lshl_add_u64 v[78:79], v[78:79], 0, v[124:125]
	v_cvt_pk_bf16_f32 v75, v80, v81
	v_cvt_pk_bf16_f32 v76, v76, v77
	v_cvt_pk_bf16_f32 v77, v86, v87
	global_store_dwordx4 v[78:79], v[74:77], off
	v_pk_mul_f32 v[72:73], v[72:73], v[208:209] op_sel_hi:[1,0]
	v_pk_mul_f32 v[70:71], v[70:71], v[208:209] op_sel_hi:[1,0]
	v_pk_mul_f32 v[74:75], v[68:69], v[208:209] op_sel_hi:[1,0]
	v_pk_mul_f32 v[68:69], v[66:67], v[208:209] op_sel_hi:[1,0]
	v_cvt_pk_bf16_f32 v66, v70, v71
	v_cvt_pk_bf16_f32 v67, v72, v73
	s_nop 0
	v_cvt_pk_bf16_f32 v68, v68, v69
	v_cvt_pk_bf16_f32 v69, v74, v75
	global_store_dwordx4 v[78:79], v[66:69], off offset:256
	s_nop 1
	v_add_u32_e32 v67, 0x80, v144
	s_waitcnt vmcnt(11)
; __device__ __forceinline__ unsigned cvt_pk_bf16(float lo, float hi) { unsigned r; asm volatile("v_cvt_pk_bf16_f32 %0, %1, %2" : "=v"(r) : "v"(lo), "v"(hi)); return r; }
;     __device__ __forceinline__ void operator()(const f32x4 (&acc)[2][2][4][2], const Unit& u, int wr, int wc, int fr, int fq) const {
;     ...
;             for (int m = 0; m < 4; ++m) { const int row = row0 + ai * HALF + m * 16; const float s = rs[row];
; #pragma unroll
;                 for (int bj = 0; bj < 2; ++bj) { const f32x4 v0 = acc[ai][bj][m][0] * s, v1 = acc[ai][bj][m][1] * s; u32x4 w;
;                     w.x = cvt_pk_bf16(v0[0], v0[1]); w.y = cvt_pk_bf16(v0[2], v0[3]); w.z = cvt_pk_bf16(v1[0], v1[1]); w.w = cvt_pk_bf16(v1[2], v1[3]);
;                     *(u32x4*)(O + (size_t)row * ldc + col0 + bj * HALF) = w; } }
	v_pk_mul_f32 v[62:63], v[62:63], v[210:211] op_sel_hi:[1,0]
	v_pk_mul_f32 v[68:69], v[60:61], v[210:211] op_sel_hi:[1,0]
	v_pk_mul_f32 v[60:61], v[58:59], v[210:211] op_sel_hi:[1,0]
	v_cvt_pk_bf16_f32 v58, v62, v63
	v_mad_i64_i32 v[62:63], s[36:37], v67, s55, v[122:123]
	v_pk_mul_f32 v[64:65], v[64:65], v[210:211] op_sel_hi:[1,0]
	v_lshl_add_u64 v[62:63], v[62:63], 0, v[124:125]
	v_cvt_pk_bf16_f32 v59, v64, v65
	v_cvt_pk_bf16_f32 v60, v60, v61
	v_cvt_pk_bf16_f32 v61, v68, v69
	global_store_dwordx4 v[62:63], v[58:61], off
	v_pk_mul_f32 v[56:57], v[56:57], v[210:211] op_sel_hi:[1,0]
	v_pk_mul_f32 v[54:55], v[54:55], v[210:211] op_sel_hi:[1,0]
	v_pk_mul_f32 v[58:59], v[52:53], v[210:211] op_sel_hi:[1,0]
	v_pk_mul_f32 v[52:53], v[50:51], v[210:211] op_sel_hi:[1,0]
	v_cvt_pk_bf16_f32 v50, v54, v55
	v_cvt_pk_bf16_f32 v51, v56, v57
	s_nop 0
	v_cvt_pk_bf16_f32 v52, v52, v53
	v_cvt_pk_bf16_f32 v53, v58, v59
	global_store_dwordx4 v[62:63], v[50:53], off offset:256
	s_nop 1
	v_add_u32_e32 v51, 0x90, v144
	s_waitcnt vmcnt(12)
	v_pk_mul_f32 v[46:47], v[46:47], v[212:213] op_sel_hi:[1,0]
	v_pk_mul_f32 v[52:53], v[44:45], v[212:213] op_sel_hi:[1,0]
	v_pk_mul_f32 v[44:45], v[42:43], v[212:213] op_sel_hi:[1,0]
	v_cvt_pk_bf16_f32 v42, v46, v47
	v_mad_i64_i32 v[46:47], s[36:37], v51, s55, v[122:123]
	v_pk_mul_f32 v[48:49], v[48:49], v[212:213] op_sel_hi:[1,0]
	v_lshl_add_u64 v[46:47], v[46:47], 0, v[124:125]
	v_cvt_pk_bf16_f32 v43, v48, v49
	v_cvt_pk_bf16_f32 v44, v44, v45
	v_cvt_pk_bf16_f32 v45, v52, v53
	global_store_dwordx4 v[46:47], v[42:45], off
	v_pk_mul_f32 v[40:41], v[40:41], v[212:213] op_sel_hi:[1,0]
	v_pk_mul_f32 v[38:39], v[38:39], v[212:213] op_sel_hi:[1,0]
	v_pk_mul_f32 v[42:43], v[36:37], v[212:213] op_sel_hi:[1,0]
	v_pk_mul_f32 v[36:37], v[34:35], v[212:213] op_sel_hi:[1,0]
	v_cvt_pk_bf16_f32 v34, v38, v39
	v_cvt_pk_bf16_f32 v35, v40, v41
	s_nop 0
	v_cvt_pk_bf16_f32 v36, v36, v37
	v_cvt_pk_bf16_f32 v37, v42, v43
	global_store_dwordx4 v[46:47], v[34:37], off offset:256
	s_nop 1
	v_add_u32_e32 v35, 0xa0, v144
	s_waitcnt vmcnt(13)
	v_pk_mul_f32 v[30:31], v[30:31], v[214:215] op_sel_hi:[1,0]
	v_pk_mul_f32 v[36:37], v[28:29], v[214:215] op_sel_hi:[1,0]
	v_pk_mul_f32 v[28:29], v[26:27], v[214:215] op_sel_hi:[1,0]
	v_cvt_pk_bf16_f32 v26, v30, v31
	v_mad_i64_i32 v[30:31], s[36:37], v35, s55, v[122:123]
	v_pk_mul_f32 v[32:33], v[32:33], v[214:215] op_sel_hi:[1,0]
	v_lshl_add_u64 v[30:31], v[30:31], 0, v[124:125]
	v_cvt_pk_bf16_f32 v27, v32, v33
	v_cvt_pk_bf16_f32 v28, v28, v29
	v_cvt_pk_bf16_f32 v29, v36, v37
	global_store_dwordx4 v[30:31], v[26:29], off
	v_pk_mul_f32 v[24:25], v[24:25], v[214:215] op_sel_hi:[1,0]
	v_pk_mul_f32 v[22:23], v[22:23], v[214:215] op_sel_hi:[1,0]
	v_pk_mul_f32 v[26:27], v[20:21], v[214:215] op_sel_hi:[1,0]
	v_pk_mul_f32 v[20:21], v[18:19], v[214:215] op_sel_hi:[1,0]
	v_cvt_pk_bf16_f32 v18, v22, v23
	v_cvt_pk_bf16_f32 v19, v24, v25
	s_nop 0
	v_cvt_pk_bf16_f32 v20, v20, v21
	v_cvt_pk_bf16_f32 v21, v26, v27
	global_store_dwordx4 v[30:31], v[18:21], off offset:256
	s_nop 1
	v_add_u32_e32 v19, 0xb0, v144
	s_waitcnt vmcnt(14)
	v_pk_mul_f32 v[12:13], v[12:13], v[216:217] op_sel_hi:[1,0]
	v_pk_mul_f32 v[20:21], v[10:11], v[216:217] op_sel_hi:[1,0]
	v_pk_mul_f32 v[10:11], v[8:9], v[216:217] op_sel_hi:[1,0]
	v_cvt_pk_bf16_f32 v8, v12, v13
	v_mad_i64_i32 v[12:13], s[36:37], v19, s55, v[122:123]
	v_pk_mul_f32 v[14:15], v[14:15], v[216:217] op_sel_hi:[1,0]
	v_lshl_add_u64 v[12:13], v[12:13], 0, v[124:125]
	v_cvt_pk_bf16_f32 v9, v14, v15
	v_cvt_pk_bf16_f32 v10, v10, v11
	v_cvt_pk_bf16_f32 v11, v20, v21
	global_store_dwordx4 v[12:13], v[8:11], off
	s_mov_b64 s[36:37], -1
	v_pk_mul_f32 v[6:7], v[6:7], v[216:217] op_sel_hi:[1,0]
	v_pk_mul_f32 v[8:9], v[2:3], v[216:217] op_sel_hi:[1,0]
	v_pk_mul_f32 v[2:3], v[0:1], v[216:217] op_sel_hi:[1,0]
	v_pk_mul_f32 v[4:5], v[4:5], v[216:217] op_sel_hi:[1,0]
	s_nop 0
	v_cvt_pk_bf16_f32 v0, v4, v5
	v_cvt_pk_bf16_f32 v1, v6, v7
	v_cvt_pk_bf16_f32 v2, v2, v3
	v_cvt_pk_bf16_f32 v3, v8, v9
	global_store_dwordx4 v[12:13], v[0:3], off offset:256
	s_cbranch_vccnz .LBB0_905
	s_andn2_b64 vcc, exec, s[0:1]
	s_cbranch_vccnz .LBB0_904
	s_barrier
	s_branch .LBB0_904

; __device__ __forceinline__ float siluf(float x) { return x * __builtin_amdgcn_rcpf(1.0f + __expf(-x)); }
; __device__ __forceinline__ float logsig(float x) { return fminf(x, 0.f) - __logf(1.0f + __expf(-fabsf(x))); }
; template <int TY> __device__ __forceinline__ void sample_item(const Params& p, ldsp lds, int item) {
;     ...
;         } else if (TY == 1) { const float t0 = p.in[13][h * 128 + d], t1 = p.in[13][512 + h * 128 + d], t2 = p.in[13][1024 + h * 128 + d];
;             const float mx = fmaxf(t0, fmaxf(t1, t2)); const float e0 = __expf(t0 - mx), e1 = __expf(t1 - mx), e2 = __expf(t2 - mx); lbv = e0 / (e0 + e1 + e2);
;         } else lng = __logf(1.0f - exp2f(-5.0f - (float)h));
;         float run = 0.f; float bt[8], qv[8], kv[8];
; #pragma unroll
;         for (int t = 0; t < 8; ++t) { float g;
;             if (TY == 0) { float x = bias;
; #pragma unroll
;                 for (int r = 0; r < 16; ++r) x += bf2f(Pb[(size_t)t * NE + E_LR + r]) * w2[r];
;                 g = logsig(x) * 0.0625f; qv[t] = bf2f(Pb[(size_t)t * NE + E_QA + h * 64 + d]) * 0.125f; kv[t] = bf2f(Pb[(size_t)t * NE + E_KA + h * 64 + d]);
;             } else if (TY == 1) { const float xf = bf2f(Pb[(size_t)t * NE + E_FB + h * 128 + d]); const float sig = __builtin_amdgcn_rcpf(1.0f + __expf(-xf));
;                 g = __logf(lbv + (1.0f - lbv) * sig); kv[t] = (1.0f - lbv) * __builtin_amdgcn_rcpf(1.0f + __expf(xf)); qv[t] = siluf(bf2f(Pb[(size_t)t * NE + E_QB + h * 128 + d]));
;             } else { g = lng; qv[t] = bf2f(Pb[(size_t)t * NO + O_Q + h * 256 + d]); kv[t] = bf2f(Pb[(size_t)t * NO + O_K + h * 256 + d]); }
;             run += g; bt[t] = run; }
.LBB0_990:
	s_or_b64 exec, exec, s[0:1]
	s_movk_i32 s0, 0x80
	v_cmp_gt_i32_e32 vcc, s0, v0
	v_ashrrev_i32_e32 v1, 31, v0
	v_lshl_add_u32 v5, v0, 2, 0
	s_and_saveexec_b64 s[8:9], vcc
	s_cbranch_execz .LBB0_992
	v_readlane_b32 s76, v252, 20
	v_readlane_b32 s77, v252, 21
	v_readlane_b32 s78, v252, 22
	v_readlane_b32 s79, v252, 23
	v_readlane_b32 s80, v252, 24
	v_readlane_b32 s81, v252, 25
	v_readlane_b32 s82, v252, 26
	v_readlane_b32 s83, v252, 27
	v_readlane_b32 s84, v252, 28
	v_readlane_b32 s85, v252, 29
	v_add_u32_e32 v2, s36, v0
	v_readlane_b32 s86, v252, 30
	v_readlane_b32 s87, v252, 31
	v_readlane_b32 s88, v252, 32
	v_readlane_b32 s89, v252, 33
	s_mov_b64 s[76:77], s[80:81]
	v_ashrrev_i32_e32 v3, 31, v2
	s_mov_b64 s[78:79], s[82:83]
	s_mov_b64 s[80:81], s[84:85]
	s_mov_b64 s[82:83], s[86:87]
	v_lshl_add_u64 v[6:7], v[2:3], 2, s[82:83]
	v_add_u32_e32 v2, 0x400, v2
	v_ashrrev_i32_e32 v3, 31, v2
	v_lshl_add_u64 v[2:3], v[2:3], 2, s[82:83]
	global_load_dword v8, v[6:7], off
	s_nop 0
	global_load_dword v6, v[6:7], off offset:2048
	s_mov_b32 s10, 0x3f317217
	global_load_dword v2, v[2:3], off
	s_mov_b32 s11, 0x7f800000
	v_readlane_b32 s90, v252, 34
	v_readlane_b32 s91, v252, 35
	s_mov_b64 s[84:85], s[88:89]
	s_waitcnt vmcnt(0)
	v_max3_f32 v3, v8, v6, v2
	v_sub_f32_e32 v7, v8, v3
	v_sub_f32_e32 v6, v6, v3
	v_mul_f32_e32 v7, 0x3fb8aa3b, v7
	v_mul_f32_e32 v6, 0x3fb8aa3b, v6
	v_sub_f32_e32 v2, v2, v3
	v_exp_f32_e32 v7, v7
	v_exp_f32_e32 v6, v6
	v_mul_f32_e32 v2, 0x3fb8aa3b, v2
	v_exp_f32_e32 v2, v2
	v_add_f32_e32 v3, v7, v6
	v_add_f32_e32 v2, v2, v3
	v_div_scale_f32 v3, s[0:1], v2, v2, v7
	v_rcp_f32_e32 v6, v3
	s_lshl_b32 s0, s36, 1
	s_add_u32 s0, s19, s0
	s_addc_u32 s1, s21, 0
	v_fma_f32 v8, -v3, v6, 1.0
	v_fmac_f32_e32 v6, v8, v6
	v_div_scale_f32 v8, vcc, v7, v2, v7
	v_mul_f32_e32 v9, v8, v6
	v_fma_f32 v10, -v3, v9, v8
	v_fmac_f32_e32 v9, v10, v6
	v_fma_f32 v3, -v3, v9, v8
	v_div_fmas_f32 v3, v3, v6, v9
	v_div_fixup_f32 v20, v3, v2, v7
	v_lshl_add_u64 v[2:3], v[0:1], 1, s[0:1]
	v_lshlrev_b32_e32 v186, 1, v0
	v_add_u32_e32 v187, 0xc00, v186
	v_add_u32_e32 v188, 0x2a00, v186
	v_add_u32_e32 v189, 0x4800, v186
	v_add_u32_e32 v190, 0x6600, v186
	v_add_u32_e32 v191, 0x8400, v186
	v_add_u32_e32 v192, 0xa200, v186
	v_add_u32_e32 v193, 0xc000, v186
	v_add_u32_e32 v194, 0xde00, v186
	global_load_ushort v203, v187, s[0:1] offset:1024
	global_load_ushort v195, v187, s[0:1]
	global_load_ushort v204, v188, s[0:1] offset:1024
	global_load_ushort v196, v188, s[0:1]
	global_load_ushort v205, v189, s[0:1] offset:1024
	global_load_ushort v197, v189, s[0:1]
	global_load_ushort v206, v190, s[0:1] offset:1024
	global_load_ushort v198, v190, s[0:1]
	global_load_ushort v207, v191, s[0:1] offset:1024
	global_load_ushort v199, v191, s[0:1]
	global_load_ushort v208, v192, s[0:1] offset:1024
	global_load_ushort v200, v192, s[0:1]
	global_load_ushort v209, v193, s[0:1] offset:1024
	global_load_ushort v201, v193, s[0:1]
	global_load_ushort v210, v194, s[0:1] offset:1024
	global_load_ushort v202, v194, s[0:1]
	v_add_co_u32_e32 v6, vcc, s57, v2
	v_sub_f32_e32 v19, 1.0, v20
	s_nop 0
	v_addc_co_u32_e32 v7, vcc, 0, v3, vcc
	s_waitcnt vmcnt(0)
	v_lshlrev_b32_e32 v6, 16, v203
	v_mul_f32_e32 v7, 0xbfb8aa3b, v6
	v_exp_f32_e32 v7, v7
	v_mul_f32_e32 v6, 0x3fb8aa3b, v6
	v_exp_f32_e32 v6, v6
	v_add_f32_e32 v7, 1.0, v7
	v_rcp_f32_e32 v7, v7
	v_add_f32_e32 v6, 1.0, v6
	v_rcp_f32_e32 v6, v6
	v_fma_f32 v7, v7, v19, v20
	v_cmp_gt_f32_e32 vcc, s33, v7
	v_mul_f32_e32 v6, v6, v19
	s_nop 0
	v_cndmask_b32_e64 v8, 0, 32, vcc
	v_ldexp_f32 v7, v7, v8
	v_log_f32_e32 v7, v7
	s_nop 0
	v_mul_f32_e32 v8, 0x3f317217, v7
	v_fma_f32 v8, v7, s10, -v8
	v_fmac_f32_e32 v8, 0x3377d1cf, v7
	v_fmac_f32_e32 v8, 0x3f317217, v7
	v_cmp_lt_f32_e64 s[0:1], |v7|, s11
	s_nop 1
	v_cndmask_b32_e64 v7, v7, v8, s[0:1]
	v_cndmask_b32_e32 v8, 0, v185, vcc
	v_sub_f32_e32 v7, v7, v8
	s_movk_i32 s0, 0x2000
	v_add_co_u32_e32 v10, vcc, s0, v2
	v_add_f32_e32 v7, 0, v7
	s_nop 0
	v_addc_co_u32_e32 v11, vcc, 0, v3, vcc
	s_waitcnt vmcnt(0)
	v_lshlrev_b32_e32 v8, 16, v195
	v_mul_f32_e32 v9, 0xbfb8aa3b, v8
	v_exp_f32_e32 v9, v9
	s_nop 0
	v_add_f32_e32 v9, 1.0, v9
	v_rcp_f32_e32 v9, v9
	s_nop 0
	v_mul_f32_e32 v8, v9, v8
	s_waitcnt vmcnt(0)
	v_lshlrev_b32_e32 v9, 16, v204
	v_mul_f32_e32 v12, 0xbfb8aa3b, v9
	v_exp_f32_e32 v12, v12
	v_mul_f32_e32 v9, 0x3fb8aa3b, v9
	v_exp_f32_e32 v9, v9
	v_add_f32_e32 v12, 1.0, v12
	v_rcp_f32_e32 v12, v12
	v_add_f32_e32 v9, 1.0, v9
	v_rcp_f32_e32 v9, v9
	v_fma_f32 v12, v19, v12, v20
	v_cmp_gt_f32_e32 vcc, s33, v12
	v_mul_f32_e32 v9, v19, v9
	s_waitcnt vmcnt(0)
	v_lshlrev_b32_e32 v10, 16, v196
	v_cndmask_b32_e64 v13, 0, 32, vcc
	v_ldexp_f32 v12, v12, v13
	v_log_f32_e32 v12, v12
	v_mul_f32_e32 v11, 0xbfb8aa3b, v10
	v_exp_f32_e32 v11, v11
	v_mul_f32_e32 v13, 0x3f317217, v12
	v_fma_f32 v13, v12, s10, -v13
	v_fmac_f32_e32 v13, 0x3377d1cf, v12
	v_add_f32_e32 v11, 1.0, v11
	v_fmac_f32_e32 v13, 0x3f317217, v12
	v_cmp_lt_f32_e64 s[0:1], |v12|, s11
	v_rcp_f32_e32 v11, v11
	s_nop 0
	v_cndmask_b32_e64 v12, v12, v13, s[0:1]
	s_movk_i32 s0, 0x4000
	v_cndmask_b32_e32 v13, 0, v185, vcc
	v_add_co_u32_e32 v14, vcc, s0, v2
	v_sub_f32_e32 v12, v12, v13
	s_nop 0
	v_addc_co_u32_e32 v15, vcc, 0, v3, vcc
	v_mul_f32_e32 v11, v11, v10
	v_add_f32_e32 v10, v7, v12
	s_waitcnt vmcnt(0)
	v_lshlrev_b32_e32 v12, 16, v205
	v_mul_f32_e32 v13, 0xbfb8aa3b, v12
	v_exp_f32_e32 v13, v13
	v_mul_f32_e32 v12, 0x3fb8aa3b, v12
	v_exp_f32_e32 v12, v12
	v_add_f32_e32 v13, 1.0, v13
	v_rcp_f32_e32 v13, v13
	v_add_f32_e32 v12, 1.0, v12
	v_rcp_f32_e32 v12, v12
	v_fma_f32 v13, v19, v13, v20
	v_cmp_gt_f32_e32 vcc, s33, v13
	v_mul_f32_e32 v12, v19, v12
	s_waitcnt vmcnt(0)
; __device__ __forceinline__ float siluf(float x) { return x * __builtin_amdgcn_rcpf(1.0f + __expf(-x)); }
; __device__ __forceinline__ float logsig(float x) { return fminf(x, 0.f) - __logf(1.0f + __expf(-fabsf(x))); }
; template <int TY> __device__ __forceinline__ void sample_item(const Params& p, ldsp lds, int item) {
;     ...
;         for (int t = 0; t < 8; ++t) { float g;
;             if (TY == 0) { float x = bias;
; #pragma unroll
;                 for (int r = 0; r < 16; ++r) x += bf2f(Pb[(size_t)t * NE + E_LR + r]) * w2[r];
;                 g = logsig(x) * 0.0625f; qv[t] = bf2f(Pb[(size_t)t * NE + E_QA + h * 64 + d]) * 0.125f; kv[t] = bf2f(Pb[(size_t)t * NE + E_KA + h * 64 + d]);
;             } else if (TY == 1) { const float xf = bf2f(Pb[(size_t)t * NE + E_FB + h * 128 + d]); const float sig = __builtin_amdgcn_rcpf(1.0f + __expf(-xf));
;                 g = __logf(lbv + (1.0f - lbv) * sig); kv[t] = (1.0f - lbv) * __builtin_amdgcn_rcpf(1.0f + __expf(xf)); qv[t] = siluf(bf2f(Pb[(size_t)t * NE + E_QB + h * 128 + d]));
;             } else { g = lng; qv[t] = bf2f(Pb[(size_t)t * NO + O_Q + h * 256 + d]); kv[t] = bf2f(Pb[(size_t)t * NO + O_K + h * 256 + d]); }
;             run += g; bt[t] = run; }
	v_lshlrev_b32_e32 v14, 16, v197
	v_cndmask_b32_e64 v16, 0, 32, vcc
	v_ldexp_f32 v13, v13, v16
	v_log_f32_e32 v13, v13
	v_mul_f32_e32 v15, 0xbfb8aa3b, v14
	v_exp_f32_e32 v15, v15
	v_mul_f32_e32 v16, 0x3f317217, v13
	v_fma_f32 v16, v13, s10, -v16
	v_fmac_f32_e32 v16, 0x3377d1cf, v13
	v_add_f32_e32 v15, 1.0, v15
	v_fmac_f32_e32 v16, 0x3f317217, v13
	v_cmp_lt_f32_e64 s[0:1], |v13|, s11
	v_rcp_f32_e32 v15, v15
	s_nop 0
	v_cndmask_b32_e64 v13, v13, v16, s[0:1]
	s_movk_i32 s0, 0x6000
	v_cndmask_b32_e32 v16, 0, v185, vcc
	v_add_co_u32_e32 v22, vcc, s0, v2
	v_mul_f32_e32 v14, v15, v14
	s_nop 0
	v_addc_co_u32_e32 v23, vcc, 0, v3, vcc
	v_sub_f32_e32 v13, v13, v16
	v_add_f32_e32 v13, v10, v13
	s_waitcnt vmcnt(0)
	v_lshlrev_b32_e32 v15, 16, v206
	v_mul_f32_e32 v16, 0xbfb8aa3b, v15
	v_exp_f32_e32 v16, v16
	v_mul_f32_e32 v15, 0x3fb8aa3b, v15
	v_exp_f32_e32 v15, v15
	v_add_f32_e32 v16, 1.0, v16
	v_rcp_f32_e32 v16, v16
	v_add_f32_e32 v15, 1.0, v15
	v_rcp_f32_e32 v15, v15
	v_fma_f32 v16, v19, v16, v20
	v_cmp_gt_f32_e32 vcc, s33, v16
	v_mul_f32_e32 v15, v19, v15
	s_nop 0
	v_cndmask_b32_e64 v18, 0, 32, vcc
	v_ldexp_f32 v16, v16, v18
	v_log_f32_e32 v16, v16
	s_nop 0
	v_mul_f32_e32 v18, 0x3f317217, v16
	v_fma_f32 v18, v16, s10, -v18
	v_fmac_f32_e32 v18, 0x3377d1cf, v16
	v_fmac_f32_e32 v18, 0x3f317217, v16
	v_cmp_lt_f32_e64 s[0:1], |v16|, s11
	s_nop 1
	v_cndmask_b32_e64 v16, v16, v18, s[0:1]
	v_cndmask_b32_e32 v18, 0, v185, vcc
	v_sub_f32_e32 v16, v16, v18
	s_mov_b32 s0, 0x8000
	v_add_co_u32_e32 v22, vcc, s0, v2
	v_add_f32_e32 v16, v13, v16
	s_nop 0
	v_addc_co_u32_e32 v23, vcc, 0, v3, vcc
	s_waitcnt vmcnt(0)
	v_lshlrev_b32_e32 v18, 16, v198
	v_mul_f32_e32 v21, 0xbfb8aa3b, v18
	v_exp_f32_e32 v21, v21
	s_nop 0
	v_add_f32_e32 v21, 1.0, v21
	v_rcp_f32_e32 v21, v21
	s_nop 0
	v_mul_f32_e32 v18, v21, v18
	s_waitcnt vmcnt(0)
	v_lshlrev_b32_e32 v21, 16, v207
	v_mul_f32_e32 v24, 0xbfb8aa3b, v21
	v_exp_f32_e32 v24, v24
	v_mul_f32_e32 v21, 0x3fb8aa3b, v21
	v_exp_f32_e32 v21, v21
	v_add_f32_e32 v24, 1.0, v24
	v_rcp_f32_e32 v24, v24
	v_add_f32_e32 v21, 1.0, v21
	v_rcp_f32_e32 v21, v21
	v_fma_f32 v24, v19, v24, v20
	v_cmp_gt_f32_e32 vcc, s33, v24
	v_mul_f32_e32 v21, v19, v21
	s_waitcnt vmcnt(0)
	v_lshlrev_b32_e32 v22, 16, v199
	v_cndmask_b32_e64 v25, 0, 32, vcc
	v_ldexp_f32 v24, v24, v25
	v_log_f32_e32 v24, v24
	v_mul_f32_e32 v23, 0xbfb8aa3b, v22
	v_exp_f32_e32 v23, v23
	v_mul_f32_e32 v25, 0x3f317217, v24
	v_fma_f32 v25, v24, s10, -v25
	v_fmac_f32_e32 v25, 0x3377d1cf, v24
	v_add_f32_e32 v23, 1.0, v23
	v_fmac_f32_e32 v25, 0x3f317217, v24
	v_cmp_lt_f32_e64 s[0:1], |v24|, s11
	v_rcp_f32_e32 v23, v23
	s_nop 0
	v_cndmask_b32_e64 v24, v24, v25, s[0:1]
	s_mov_b32 s0, 0xa000
	v_cndmask_b32_e32 v25, 0, v185, vcc
	v_add_co_u32_e32 v26, vcc, s0, v2
	v_sub_f32_e32 v24, v24, v25
	s_nop 0
	v_addc_co_u32_e32 v27, vcc, 0, v3, vcc
	v_mul_f32_e32 v23, v23, v22
	v_add_f32_e32 v22, v16, v24
	s_waitcnt vmcnt(0)
	v_lshlrev_b32_e32 v24, 16, v208
	v_mul_f32_e32 v25, 0xbfb8aa3b, v24
	v_exp_f32_e32 v25, v25
	v_mul_f32_e32 v24, 0x3fb8aa3b, v24
	v_exp_f32_e32 v24, v24
	v_add_f32_e32 v25, 1.0, v25
	v_rcp_f32_e32 v25, v25
	v_add_f32_e32 v24, 1.0, v24
	v_rcp_f32_e32 v24, v24
	v_fma_f32 v25, v19, v25, v20
	v_cmp_gt_f32_e32 vcc, s33, v25
	v_mul_f32_e32 v24, v19, v24
	s_waitcnt vmcnt(0)
	v_lshlrev_b32_e32 v26, 16, v200
	v_cndmask_b32_e64 v28, 0, 32, vcc
	v_ldexp_f32 v25, v25, v28
	v_log_f32_e32 v25, v25
	v_mul_f32_e32 v27, 0xbfb8aa3b, v26
	v_exp_f32_e32 v27, v27
	v_mul_f32_e32 v28, 0x3f317217, v25
	v_fma_f32 v28, v25, s10, -v28
	v_fmac_f32_e32 v28, 0x3377d1cf, v25
	v_add_f32_e32 v27, 1.0, v27
	v_fmac_f32_e32 v28, 0x3f317217, v25
	v_cmp_lt_f32_e64 s[0:1], |v25|, s11
	v_rcp_f32_e32 v27, v27
	s_nop 0
	v_cndmask_b32_e64 v25, v25, v28, s[0:1]
	v_cndmask_b32_e32 v28, 0, v185, vcc
	s_mov_b32 s0, 0xc000
	v_sub_f32_e32 v25, v25, v28
	v_add_co_u32_e32 v28, vcc, s0, v2
	v_mul_f32_e32 v26, v27, v26
	s_nop 0
	v_addc_co_u32_e32 v29, vcc, 0, v3, vcc
	v_add_f32_e32 v25, v22, v25
	s_waitcnt vmcnt(1)
	v_lshlrev_b32_e32 v27, 16, v209
	v_mul_f32_e32 v30, 0xbfb8aa3b, v27
	v_exp_f32_e32 v30, v30
	s_waitcnt vmcnt(0)
	v_lshlrev_b32_e32 v28, 16, v201
	v_mul_f32_e32 v29, 0xbfb8aa3b, v28
	v_exp_f32_e32 v29, v29
	v_add_f32_e32 v30, 1.0, v30
	v_rcp_f32_e32 v30, v30
	v_mul_f32_e32 v27, 0x3fb8aa3b, v27
	v_add_f32_e32 v29, 1.0, v29
	v_rcp_f32_e32 v29, v29
	v_fma_f32 v30, v19, v30, v20
	v_cmp_gt_f32_e32 vcc, s33, v30
	v_exp_f32_e32 v27, v27
	v_mul_f32_e32 v29, v29, v28
	v_cndmask_b32_e64 v31, 0, 32, vcc
	v_ldexp_f32 v30, v30, v31
	v_log_f32_e32 v30, v30
	v_add_f32_e32 v27, 1.0, v27
	v_rcp_f32_e32 v27, v27
	v_mul_f32_e32 v31, 0x3f317217, v30
	v_fma_f32 v31, v30, s10, -v31
	v_fmac_f32_e32 v31, 0x3377d1cf, v30
	v_fmac_f32_e32 v31, 0x3f317217, v30
	v_cmp_lt_f32_e64 s[0:1], |v30|, s11
	v_mul_f32_e32 v27, v19, v27
	s_nop 0
	v_cndmask_b32_e64 v30, v30, v31, s[0:1]
	v_cndmask_b32_e32 v31, 0, v185, vcc
	v_sub_f32_e32 v30, v30, v31
	s_mov_b32 s0, 0xe000
	v_add_f32_e32 v28, v25, v30
	v_add_co_u32_e32 v30, vcc, s0, v2
	s_nop 1
	v_addc_co_u32_e32 v31, vcc, 0, v3, vcc
	s_waitcnt vmcnt(0)
; __device__ __forceinline__ float siluf(float x) { return x * __builtin_amdgcn_rcpf(1.0f + __expf(-x)); }
; template <int TY> __device__ __forceinline__ void sample_item(const Params& p, ldsp lds, int item) {
;     ...
;             } else if (TY == 1) { const float xf = bf2f(Pb[(size_t)t * NE + E_FB + h * 128 + d]); const float sig = __builtin_amdgcn_rcpf(1.0f + __expf(-xf));
;                 g = __logf(lbv + (1.0f - lbv) * sig); kv[t] = (1.0f - lbv) * __builtin_amdgcn_rcpf(1.0f + __expf(xf)); qv[t] = siluf(bf2f(Pb[(size_t)t * NE + E_QB + h * 128 + d]));
;             } else { g = lng; qv[t] = bf2f(Pb[(size_t)t * NO + O_Q + h * 256 + d]); kv[t] = bf2f(Pb[(size_t)t * NO + O_K + h * 256 + d]); }
;             run += g; bt[t] = run; }
; #pragma unroll
;         for (int t = 0; t < 8; ++t) { Bs[t * DK + d] = bt[t]; QR[t * DK + d] = qv[t]; KR[t * DK + d] = kv[t];
;             QK[d * 16 + t] = qv[t] * __expf(bt[t]); QK[d * 16 + 8 + t] = kv[t] * __expf(run - bt[t]); }
;         DECs[d] = __expf(run); }
	v_lshlrev_b32_e32 v30, 16, v210
	v_mul_f32_e32 v31, 0xbfb8aa3b, v30
	v_exp_f32_e32 v31, v31
	v_mul_f32_e32 v30, 0x3fb8aa3b, v30
	v_exp_f32_e32 v30, v30
	v_add_f32_e32 v31, 1.0, v31
	v_rcp_f32_e32 v31, v31
	v_add_f32_e32 v30, 1.0, v30
	v_rcp_f32_e32 v30, v30
	v_fmac_f32_e32 v20, v19, v31
	v_cmp_gt_f32_e32 vcc, s33, v20
	v_mul_f32_e32 v19, v19, v30
	v_mul_f32_e32 v30, 0x3fb8aa3b, v7
	v_cndmask_b32_e64 v31, 0, 32, vcc
	v_ldexp_f32 v20, v20, v31
	v_log_f32_e32 v20, v20
	v_exp_f32_e32 v30, v30
	v_mul_f32_e32 v31, 0x3f317217, v20
	v_fma_f32 v31, v20, s10, -v31
	v_fmac_f32_e32 v31, 0x3377d1cf, v20
	v_fmac_f32_e32 v31, 0x3f317217, v20
	v_cmp_lt_f32_e64 s[0:1], |v20|, s11
	s_nop 1
	v_cndmask_b32_e64 v20, v20, v31, s[0:1]
	s_mov_b32 s0, 0xd000
	v_cndmask_b32_e32 v31, 0, v185, vcc
	v_add_co_u32_e32 v2, vcc, s0, v2
	v_sub_f32_e32 v20, v20, v31
	s_nop 0
	v_addc_co_u32_e32 v3, vcc, 0, v3, vcc
	ds_write_b32 v5, v7 offset:16384
	ds_write_b32 v5, v8 offset:24576
	ds_write_b32 v5, v6 offset:32768
	v_mul_f32_e32 v8, v8, v30
	s_waitcnt vmcnt(0)
	v_lshlrev_b32_e32 v2, 16, v202
	v_mul_f32_e32 v3, 0xbfb8aa3b, v2
	v_exp_f32_e32 v3, v3
	s_nop 0
	v_add_f32_e32 v3, 1.0, v3
	v_rcp_f32_e32 v3, v3
	s_nop 0
	v_mul_f32_e32 v2, v3, v2
	v_add_f32_e32 v3, v28, v20
	v_sub_f32_e32 v7, v3, v7
	v_mul_f32_e32 v7, 0x3fb8aa3b, v7
	v_exp_f32_e32 v7, v7
	v_lshl_add_u32 v20, v0, 6, 0
	ds_write_b32 v20, v8
	v_mul_f32_e32 v6, v6, v7
	ds_write_b32 v20, v6 offset:32
	ds_write_b32 v5, v10 offset:16896
	ds_write_b32 v5, v11 offset:25088
	ds_write_b32 v5, v9 offset:33280
	v_mul_f32_e32 v6, 0x3fb8aa3b, v10
	v_exp_f32_e32 v6, v6
	s_nop 0
	v_mul_f32_e32 v6, v11, v6
	ds_write_b32 v20, v6 offset:4
	v_sub_f32_e32 v6, v3, v10
	v_mul_f32_e32 v6, 0x3fb8aa3b, v6
	v_exp_f32_e32 v6, v6
	s_nop 0
	v_mul_f32_e32 v6, v9, v6
	ds_write_b32 v20, v6 offset:36
	ds_write_b32 v5, v13 offset:17408
	ds_write_b32 v5, v14 offset:25600
	ds_write_b32 v5, v12 offset:33792
	v_mul_f32_e32 v6, 0x3fb8aa3b, v13
	v_exp_f32_e32 v6, v6
	s_nop 0
	v_mul_f32_e32 v6, v14, v6
	ds_write_b32 v20, v6 offset:8
	v_sub_f32_e32 v6, v3, v13
	v_mul_f32_e32 v6, 0x3fb8aa3b, v6
	v_exp_f32_e32 v6, v6
	s_nop 0
	v_mul_f32_e32 v6, v12, v6
	ds_write_b32 v20, v6 offset:40
	ds_write_b32 v5, v16 offset:17920
	ds_write_b32 v5, v18 offset:26112
	ds_write_b32 v5, v15 offset:34304
	v_mul_f32_e32 v6, 0x3fb8aa3b, v16
	v_exp_f32_e32 v6, v6
	s_nop 0
	v_mul_f32_e32 v6, v18, v6
	ds_write_b32 v20, v6 offset:12
	v_sub_f32_e32 v6, v3, v16
	v_mul_f32_e32 v6, 0x3fb8aa3b, v6
	v_exp_f32_e32 v6, v6
	s_nop 0
	v_mul_f32_e32 v6, v15, v6
	ds_write_b32 v20, v6 offset:44
	ds_write_b32 v5, v22 offset:18432
	ds_write_b32 v5, v23 offset:26624
	ds_write_b32 v5, v21 offset:34816
	v_mul_f32_e32 v6, 0x3fb8aa3b, v22
	v_exp_f32_e32 v6, v6
	s_nop 0
	v_mul_f32_e32 v6, v23, v6
	ds_write_b32 v20, v6 offset:16
	v_sub_f32_e32 v6, v3, v22
	v_mul_f32_e32 v6, 0x3fb8aa3b, v6
	v_exp_f32_e32 v6, v6
	s_nop 0
	v_mul_f32_e32 v6, v21, v6
	ds_write_b32 v20, v6 offset:48
	ds_write_b32 v5, v25 offset:18944
	ds_write_b32 v5, v26 offset:27136
	ds_write_b32 v5, v24 offset:35328
	v_mul_f32_e32 v6, 0x3fb8aa3b, v25
	v_exp_f32_e32 v6, v6
	s_nop 0
	v_mul_f32_e32 v6, v26, v6
	ds_write_b32 v20, v6 offset:20
	v_sub_f32_e32 v6, v3, v25
	v_mul_f32_e32 v6, 0x3fb8aa3b, v6
	v_exp_f32_e32 v6, v6
	s_nop 0
	v_mul_f32_e32 v6, v24, v6
	ds_write_b32 v20, v6 offset:52
	ds_write_b32 v5, v28 offset:19456
	ds_write_b32 v5, v29 offset:27648
	ds_write_b32 v5, v27 offset:35840
	v_mul_f32_e32 v6, 0x3fb8aa3b, v28
	v_exp_f32_e32 v6, v6
	s_nop 0
	v_mul_f32_e32 v6, v29, v6
	ds_write_b32 v20, v6 offset:24
	v_sub_f32_e32 v6, v3, v28
	v_mul_f32_e32 v6, 0x3fb8aa3b, v6
	v_exp_f32_e32 v6, v6
	s_nop 0
	v_mul_f32_e32 v6, v27, v6
	ds_write_b32 v20, v6 offset:56
	ds_write_b32 v5, v3 offset:19968
	ds_write_b32 v5, v2 offset:28160
	ds_write_b32 v5, v19 offset:36352
	v_mul_f32_e32 v6, 0x3fb8aa3b, v3
	v_exp_f32_e32 v6, v6
	s_nop 0
	v_mul_f32_e32 v2, v2, v6
	ds_write_b32 v20, v2 offset:28
	v_sub_f32_e32 v2, v3, v3
	v_mul_f32_e32 v2, 0x3fb8aa3b, v2
	v_exp_f32_e32 v2, v2
	s_nop 0
	v_mul_f32_e32 v2, v19, v2
	ds_write_b32 v20, v2 offset:60
	ds_write_b32 v5, v6 offset:40960

; #define LAS __attribute__((address_space(3)))
; template <int TY> __device__ __forceinline__ void sample_item(const Params& p, ldsp lds, int item) {
;     ...
; #pragma unroll 8
;     for (int d = dg; d < DK; d += NG) { const f32x4 s0 = __builtin_nontemporal_load((const f32x4*)(S0 + (size_t)d * DV + e4 * 4));
;         const f32x4 qa = *(const LAS f32x4*)(QK + d * 16), qb = *(const LAS f32x4*)(QK + d * 16 + 4), ka = *(const LAS f32x4*)(QK + d * 16 + 8), kb = *(const LAS f32x4*)(QK + d * 16 + 12);
;         const float dc = DECs[d];
;         o[0] += s0 * qa[0]; o[1] += s0 * qa[1]; o[2] += s0 * qa[2]; o[3] += s0 * qa[3]; o[4] += s0 * qb[0]; o[5] += s0 * qb[1]; o[6] += s0 * qb[2]; o[7] += s0 * qb[3];
;         f32x4 sn = s0 * dc; sn += v[0] * ka[0]; sn += v[1] * ka[1]; sn += v[2] * ka[2]; sn += v[3] * ka[3]; sn += v[4] * kb[0]; sn += v[5] * kb[1]; sn += v[6] * kb[2]; sn += v[7] * kb[3];
;         __builtin_nontemporal_store(sn, (f32x4*)(S1 + (size_t)d * DV + e4 * 4)); }
.LBB0_1005:
	v_lshl_add_u64 v[100:101], v[96:97], 0, s[8:9]
	global_load_dwordx4 v[186:189], v[100:101], off nt
	v_lshl_add_u64 v[190:191], v[94:95], 0, s[8:9]
	global_load_dwordx4 v[192:195], v[190:191], off nt
	v_lshl_add_u64 v[196:197], v[90:91], 0, s[8:9]
	global_load_dwordx4 v[198:201], v[196:197], off nt
	v_lshl_add_u64 v[202:203], v[86:87], 0, s[8:9]
	global_load_dwordx4 v[204:207], v[202:203], off nt
	v_lshl_add_u64 v[208:209], v[82:83], 0, s[8:9]
	global_load_dwordx4 v[210:213], v[208:209], off nt
	v_lshl_add_u64 v[214:215], v[78:79], 0, s[8:9]
	global_load_dwordx4 v[216:219], v[214:215], off nt
	v_lshl_add_u64 v[220:221], v[74:75], 0, s[8:9]
	global_load_dwordx4 v[222:225], v[220:221], off nt
	v_lshl_add_u64 v[226:227], v[70:71], 0, s[8:9]
	global_load_dwordx4 v[228:231], v[226:227], off nt
	ds_read_b128 v[108:111], v116
	ds_read_b128 v[118:121], v116 offset:16
	ds_read_b128 v[122:125], v116 offset:32
	ds_read_b128 v[126:129], v116 offset:48
	ds_read2_b32 v[100:101], v16 offset1:16
	s_waitcnt lgkmcnt(0)
	v_mov_b32_e32 v102, v111
	v_add_u32_e32 v69, 0x80, v69
	v_cmp_lt_i32_e32 vcc, -1, v69
	v_lshl_add_u64 v[96:97], v[96:97], 0, s[44:45]
	s_or_b64 s[16:17], vcc, s[16:17]
	s_waitcnt vmcnt(0)
	v_pk_fma_f32 v[64:65], v[186:187], v[108:109], v[64:65] op_sel_hi:[1,0,1]
	v_pk_fma_f32 v[66:67], v[188:189], v[108:109], v[66:67] op_sel_hi:[1,0,1]
	v_pk_fma_f32 v[60:61], v[186:187], v[108:109], v[60:61] op_sel:[0,1,0]
	v_pk_fma_f32 v[62:63], v[188:189], v[108:109], v[62:63] op_sel:[0,1,0]
	v_mov_b32_e32 v108, v121
	v_pk_fma_f32 v[56:57], v[186:187], v[110:111], v[56:57] op_sel_hi:[1,0,1]
	v_pk_fma_f32 v[52:53], v[186:187], v[102:103], v[52:53] op_sel_hi:[1,0,1]
	v_pk_fma_f32 v[54:55], v[188:189], v[102:103], v[54:55] op_sel_hi:[1,0,1]
	v_pk_fma_f32 v[48:49], v[186:187], v[118:119], v[48:49] op_sel_hi:[1,0,1]
	v_pk_fma_f32 v[40:41], v[186:187], v[118:119], v[40:41] op_sel:[0,1,0]
	v_pk_fma_f32 v[36:37], v[186:187], v[120:121], v[36:37] op_sel_hi:[1,0,1]
	v_pk_fma_f32 v[102:103], v[188:189], v[120:121], v[38:39] op_sel_hi:[1,0,1]
	v_pk_fma_f32 v[38:39], v[186:187], v[108:109], v[44:45] op_sel_hi:[1,0,1]
	v_pk_fma_f32 v[44:45], v[188:189], v[108:109], v[46:47] op_sel_hi:[1,0,1]
	v_pk_mul_f32 v[46:47], v[186:187], v[100:101] op_sel_hi:[1,0]
	v_pk_mul_f32 v[104:105], v[188:189], v[100:101] op_sel_hi:[1,0]
	v_pk_fma_f32 v[46:47], v[0:1], v[122:123], v[46:47] op_sel_hi:[1,0,1]
	v_pk_fma_f32 v[104:105], v[2:3], v[122:123], v[104:105] op_sel_hi:[1,0,1]
	v_pk_fma_f32 v[46:47], v[4:5], v[122:123], v[46:47] op_sel:[0,1,0]
	v_pk_fma_f32 v[104:105], v[6:7], v[122:123], v[104:105] op_sel:[0,1,0]
	v_pk_fma_f32 v[46:47], v[8:9], v[124:125], v[46:47] op_sel_hi:[1,0,1]
	v_pk_fma_f32 v[104:105], v[10:11], v[124:125], v[104:105] op_sel_hi:[1,0,1]
	v_mov_b32_e32 v100, v125
	v_pk_fma_f32 v[46:47], v[12:13], v[100:101], v[46:47] op_sel_hi:[1,0,1]
	v_pk_fma_f32 v[104:105], v[14:15], v[100:101], v[104:105] op_sel_hi:[1,0,1]
	v_pk_fma_f32 v[46:47], v[20:21], v[126:127], v[46:47] op_sel_hi:[1,0,1]
	v_pk_fma_f32 v[104:105], v[22:23], v[126:127], v[104:105] op_sel_hi:[1,0,1]
	v_pk_fma_f32 v[46:47], v[24:25], v[126:127], v[46:47] op_sel:[0,1,0]
	v_pk_fma_f32 v[104:105], v[26:27], v[126:127], v[104:105] op_sel:[0,1,0]
	v_pk_fma_f32 v[58:59], v[188:189], v[110:111], v[58:59] op_sel_hi:[1,0,1]
	v_pk_fma_f32 v[50:51], v[188:189], v[118:119], v[50:51] op_sel_hi:[1,0,1]
	v_pk_fma_f32 v[42:43], v[188:189], v[118:119], v[42:43] op_sel:[0,1,0]
	v_pk_fma_f32 v[106:107], v[30:31], v[128:129], v[104:105] op_sel_hi:[1,0,1]
	v_pk_fma_f32 v[46:47], v[28:29], v[128:129], v[46:47] op_sel_hi:[1,0,1]
	v_mov_b32_e32 v100, v129
	v_pk_fma_f32 v[104:105], v[32:33], v[100:101], v[46:47] op_sel_hi:[1,0,1]
	v_pk_fma_f32 v[106:107], v[34:35], v[100:101], v[106:107] op_sel_hi:[1,0,1]
	v_lshl_add_u64 v[46:47], v[98:99], 0, s[8:9]
	global_store_dwordx4 v[46:47], v[104:107], off nt
	v_lshl_add_u64 v[46:47], v[94:95], 0, s[8:9]
	ds_read_b128 v[108:111], v116 offset:1024
	ds_read_b128 v[118:121], v116 offset:1040
	ds_read_b128 v[122:125], v116 offset:1056
	ds_read_b128 v[126:129], v116 offset:1072
	v_lshl_add_u64 v[94:95], v[94:95], 0, s[44:45]
	s_waitcnt lgkmcnt(3)
	v_mov_b32_e32 v46, v111
	v_lshl_add_u64 v[98:99], v[98:99], 0, s[44:45]
	s_waitcnt lgkmcnt(2)
	v_pk_fma_f32 v[134:135], v[192:193], v[120:121], v[36:37] op_sel_hi:[1,0,1]
	v_mov_b32_e32 v36, v121
	v_pk_fma_f32 v[102:103], v[194:195], v[120:121], v[102:103] op_sel_hi:[1,0,1]
	v_pk_fma_f32 v[120:121], v[194:195], v[36:37], v[44:45] op_sel_hi:[1,0,1]
	v_pk_fma_f32 v[136:137], v[192:193], v[36:37], v[38:39] op_sel_hi:[1,0,1]
	v_mov_b32_e32 v36, v101
	v_pk_mul_f32 v[38:39], v[192:193], v[36:37] op_sel_hi:[1,0]
	v_pk_mul_f32 v[36:37], v[194:195], v[36:37] op_sel_hi:[1,0]
	s_waitcnt lgkmcnt(1)
	v_pk_fma_f32 v[38:39], v[0:1], v[122:123], v[38:39] op_sel_hi:[1,0,1]
	v_pk_fma_f32 v[36:37], v[2:3], v[122:123], v[36:37] op_sel_hi:[1,0,1]
	v_pk_fma_f32 v[38:39], v[4:5], v[122:123], v[38:39] op_sel:[0,1,0]
	v_pk_fma_f32 v[36:37], v[6:7], v[122:123], v[36:37] op_sel:[0,1,0]
	v_pk_fma_f32 v[112:113], v[194:195], v[118:119], v[50:51] op_sel_hi:[1,0,1]
	v_pk_fma_f32 v[130:131], v[192:193], v[118:119], v[48:49] op_sel_hi:[1,0,1]
	v_pk_fma_f32 v[132:133], v[194:195], v[118:119], v[42:43] op_sel:[0,1,0]
	v_pk_fma_f32 v[118:119], v[192:193], v[118:119], v[40:41] op_sel:[0,1,0]
	v_pk_fma_f32 v[36:37], v[10:11], v[124:125], v[36:37] op_sel_hi:[1,0,1]
	v_pk_fma_f32 v[38:39], v[8:9], v[124:125], v[38:39] op_sel_hi:[1,0,1]
	v_mov_b32_e32 v40, v125
	v_pk_fma_f32 v[38:39], v[12:13], v[40:41], v[38:39] op_sel_hi:[1,0,1]
	v_pk_fma_f32 v[36:37], v[14:15], v[40:41], v[36:37] op_sel_hi:[1,0,1]
	s_waitcnt lgkmcnt(0)
; #define LAS __attribute__((address_space(3)))
; template <int TY> __device__ __forceinline__ void sample_item(const Params& p, ldsp lds, int item) {
;     ...
; #pragma unroll 8
;     for (int d = dg; d < DK; d += NG) { const f32x4 s0 = __builtin_nontemporal_load((const f32x4*)(S0 + (size_t)d * DV + e4 * 4));
;         const f32x4 qa = *(const LAS f32x4*)(QK + d * 16), qb = *(const LAS f32x4*)(QK + d * 16 + 4), ka = *(const LAS f32x4*)(QK + d * 16 + 8), kb = *(const LAS f32x4*)(QK + d * 16 + 12);
;         const float dc = DECs[d];
;         o[0] += s0 * qa[0]; o[1] += s0 * qa[1]; o[2] += s0 * qa[2]; o[3] += s0 * qa[3]; o[4] += s0 * qb[0]; o[5] += s0 * qb[1]; o[6] += s0 * qb[2]; o[7] += s0 * qb[3];
;         f32x4 sn = s0 * dc; sn += v[0] * ka[0]; sn += v[1] * ka[1]; sn += v[2] * ka[2]; sn += v[3] * ka[3]; sn += v[4] * kb[0]; sn += v[5] * kb[1]; sn += v[6] * kb[2]; sn += v[7] * kb[3];
;         __builtin_nontemporal_store(sn, (f32x4*)(S1 + (size_t)d * DV + e4 * 4)); }
	v_pk_fma_f32 v[38:39], v[20:21], v[126:127], v[38:39] op_sel_hi:[1,0,1]
	v_pk_fma_f32 v[36:37], v[22:23], v[126:127], v[36:37] op_sel_hi:[1,0,1]
	v_pk_fma_f32 v[38:39], v[24:25], v[126:127], v[38:39] op_sel:[0,1,0]
	v_pk_fma_f32 v[36:37], v[26:27], v[126:127], v[36:37] op_sel:[0,1,0]
	v_pk_fma_f32 v[66:67], v[194:195], v[108:109], v[66:67] op_sel_hi:[1,0,1]
	v_pk_fma_f32 v[40:41], v[30:31], v[128:129], v[36:37] op_sel_hi:[1,0,1]
	v_pk_fma_f32 v[36:37], v[28:29], v[128:129], v[38:39] op_sel_hi:[1,0,1]
	v_mov_b32_e32 v38, v129
	v_pk_fma_f32 v[36:37], v[32:33], v[38:39], v[36:37] op_sel_hi:[1,0,1]
	v_pk_fma_f32 v[38:39], v[34:35], v[38:39], v[40:41] op_sel_hi:[1,0,1]
	v_lshl_add_u64 v[40:41], v[92:93], 0, s[8:9]
	global_store_dwordx4 v[40:41], v[36:39], off nt
	v_pk_fma_f32 v[64:65], v[192:193], v[108:109], v[64:65] op_sel_hi:[1,0,1]
	v_pk_fma_f32 v[62:63], v[194:195], v[108:109], v[62:63] op_sel:[0,1,0]
	v_lshl_add_u64 v[36:37], v[90:91], 0, s[8:9]
	v_pk_fma_f32 v[60:61], v[192:193], v[108:109], v[60:61] op_sel:[0,1,0]
	v_pk_fma_f32 v[58:59], v[194:195], v[110:111], v[58:59] op_sel_hi:[1,0,1]
	v_pk_fma_f32 v[56:57], v[192:193], v[110:111], v[56:57] op_sel_hi:[1,0,1]
	v_pk_fma_f32 v[108:109], v[194:195], v[46:47], v[54:55] op_sel_hi:[1,0,1]
	v_pk_fma_f32 v[110:111], v[192:193], v[46:47], v[52:53] op_sel_hi:[1,0,1]
	ds_read_b128 v[40:43], v116 offset:2048
	ds_read_b128 v[44:47], v116 offset:2064
	ds_read_b128 v[48:51], v116 offset:2080
	ds_read_b128 v[52:55], v116 offset:2096
	ds_read2_b32 v[100:101], v16 offset0:32 offset1:48
	v_lshl_add_u64 v[90:91], v[90:91], 0, s[44:45]
	v_lshl_add_u64 v[92:93], v[92:93], 0, s[44:45]
	s_waitcnt lgkmcnt(4)
	v_pk_fma_f32 v[66:67], v[200:201], v[40:41], v[66:67] op_sel_hi:[1,0,1]
	v_pk_fma_f32 v[64:65], v[198:199], v[40:41], v[64:65] op_sel_hi:[1,0,1]
	v_pk_fma_f32 v[62:63], v[200:201], v[40:41], v[62:63] op_sel:[0,1,0]
	v_pk_fma_f32 v[60:61], v[198:199], v[40:41], v[60:61] op_sel:[0,1,0]
	v_mov_b32_e32 v40, v43
	v_pk_fma_f32 v[104:105], v[198:199], v[40:41], v[110:111] op_sel_hi:[1,0,1]
	v_pk_fma_f32 v[106:107], v[200:201], v[40:41], v[108:109] op_sel_hi:[1,0,1]
	s_waitcnt lgkmcnt(3)
	v_mov_b32_e32 v40, v47
	v_pk_fma_f32 v[56:57], v[198:199], v[42:43], v[56:57] op_sel_hi:[1,0,1]
	v_pk_fma_f32 v[58:59], v[200:201], v[42:43], v[58:59] op_sel_hi:[1,0,1]
	v_pk_fma_f32 v[108:109], v[200:201], v[44:45], v[112:113] op_sel_hi:[1,0,1]
	v_pk_fma_f32 v[110:111], v[198:199], v[44:45], v[130:131] op_sel_hi:[1,0,1]
	v_pk_fma_f32 v[112:113], v[200:201], v[44:45], v[132:133] op_sel:[0,1,0]
	v_pk_fma_f32 v[118:119], v[198:199], v[44:45], v[118:119] op_sel:[0,1,0]
	v_pk_fma_f32 v[122:123], v[198:199], v[46:47], v[134:135] op_sel_hi:[1,0,1]
	v_pk_fma_f32 v[102:103], v[200:201], v[46:47], v[102:103] op_sel_hi:[1,0,1]
	v_pk_fma_f32 v[120:121], v[200:201], v[40:41], v[120:121] op_sel_hi:[1,0,1]
	v_pk_fma_f32 v[124:125], v[198:199], v[40:41], v[136:137] op_sel_hi:[1,0,1]
	s_waitcnt lgkmcnt(0)
	v_pk_mul_f32 v[36:37], v[198:199], v[100:101] op_sel_hi:[1,0]
	v_pk_mul_f32 v[38:39], v[200:201], v[100:101] op_sel_hi:[1,0]
	v_pk_fma_f32 v[36:37], v[0:1], v[48:49], v[36:37] op_sel_hi:[1,0,1]
	v_pk_fma_f32 v[38:39], v[2:3], v[48:49], v[38:39] op_sel_hi:[1,0,1]
	v_pk_fma_f32 v[36:37], v[4:5], v[48:49], v[36:37] op_sel:[0,1,0]
	v_pk_fma_f32 v[38:39], v[6:7], v[48:49], v[38:39] op_sel:[0,1,0]
	v_pk_fma_f32 v[36:37], v[8:9], v[50:51], v[36:37] op_sel_hi:[1,0,1]
	v_pk_fma_f32 v[38:39], v[10:11], v[50:51], v[38:39] op_sel_hi:[1,0,1]
	v_mov_b32_e32 v40, v51
	v_pk_fma_f32 v[36:37], v[12:13], v[40:41], v[36:37] op_sel_hi:[1,0,1]
	v_pk_fma_f32 v[38:39], v[14:15], v[40:41], v[38:39] op_sel_hi:[1,0,1]
	v_pk_fma_f32 v[36:37], v[20:21], v[52:53], v[36:37] op_sel_hi:[1,0,1]
	v_pk_fma_f32 v[38:39], v[22:23], v[52:53], v[38:39] op_sel_hi:[1,0,1]
	v_pk_fma_f32 v[36:37], v[24:25], v[52:53], v[36:37] op_sel:[0,1,0]
	v_pk_fma_f32 v[38:39], v[26:27], v[52:53], v[38:39] op_sel:[0,1,0]
	v_pk_fma_f32 v[36:37], v[28:29], v[54:55], v[36:37] op_sel_hi:[1,0,1]
	v_pk_fma_f32 v[38:39], v[30:31], v[54:55], v[38:39] op_sel_hi:[1,0,1]
	v_mov_b32_e32 v40, v55
	v_pk_fma_f32 v[36:37], v[32:33], v[40:41], v[36:37] op_sel_hi:[1,0,1]
	v_pk_fma_f32 v[38:39], v[34:35], v[40:41], v[38:39] op_sel_hi:[1,0,1]
	v_lshl_add_u64 v[40:41], v[88:89], 0, s[8:9]
	global_store_dwordx4 v[40:41], v[36:39], off nt
	v_lshl_add_u64 v[88:89], v[88:89], 0, s[44:45]
	s_nop 0
	v_lshl_add_u64 v[36:37], v[86:87], 0, s[8:9]
	ds_read_b128 v[40:43], v116 offset:3072
	ds_read_b128 v[44:47], v116 offset:3088
	ds_read_b128 v[48:51], v116 offset:3104
	ds_read_b128 v[52:55], v116 offset:3120
	v_lshl_add_u64 v[86:87], v[86:87], 0, s[44:45]
	s_waitcnt lgkmcnt(3)
	v_pk_fma_f32 v[66:67], v[206:207], v[40:41], v[66:67] op_sel_hi:[1,0,1]
	v_pk_fma_f32 v[64:65], v[204:205], v[40:41], v[64:65] op_sel_hi:[1,0,1]
	v_pk_fma_f32 v[62:63], v[206:207], v[40:41], v[62:63] op_sel:[0,1,0]
	v_pk_fma_f32 v[60:61], v[204:205], v[40:41], v[60:61] op_sel:[0,1,0]
	v_mov_b32_e32 v40, v43
	v_pk_fma_f32 v[106:107], v[206:207], v[40:41], v[106:107] op_sel_hi:[1,0,1]
	v_pk_fma_f32 v[104:105], v[204:205], v[40:41], v[104:105] op_sel_hi:[1,0,1]
	s_waitcnt lgkmcnt(2)
	v_mov_b32_e32 v40, v47
	v_pk_fma_f32 v[120:121], v[206:207], v[40:41], v[120:121] op_sel_hi:[1,0,1]
	v_pk_fma_f32 v[124:125], v[204:205], v[40:41], v[124:125] op_sel_hi:[1,0,1]
	v_mov_b32_e32 v40, v101
	v_pk_fma_f32 v[58:59], v[206:207], v[42:43], v[58:59] op_sel_hi:[1,0,1]
	v_pk_fma_f32 v[56:57], v[204:205], v[42:43], v[56:57] op_sel_hi:[1,0,1]
	v_pk_fma_f32 v[108:109], v[206:207], v[44:45], v[108:109] op_sel_hi:[1,0,1]
	v_pk_fma_f32 v[110:111], v[204:205], v[44:45], v[110:111] op_sel_hi:[1,0,1]
	v_pk_fma_f32 v[112:113], v[206:207], v[44:45], v[112:113] op_sel:[0,1,0]
	v_pk_fma_f32 v[118:119], v[204:205], v[44:45], v[118:119] op_sel:[0,1,0]
	v_pk_fma_f32 v[102:103], v[206:207], v[46:47], v[102:103] op_sel_hi:[1,0,1]
	v_pk_fma_f32 v[122:123], v[204:205], v[46:47], v[122:123] op_sel_hi:[1,0,1]
	v_pk_mul_f32 v[36:37], v[204:205], v[40:41] op_sel_hi:[1,0]
	v_pk_mul_f32 v[38:39], v[206:207], v[40:41] op_sel_hi:[1,0]
	s_waitcnt lgkmcnt(1)
; #define LAS __attribute__((address_space(3)))
; template <int TY> __device__ __forceinline__ void sample_item(const Params& p, ldsp lds, int item) {
;     ...
; #pragma unroll 8
;     for (int d = dg; d < DK; d += NG) { const f32x4 s0 = __builtin_nontemporal_load((const f32x4*)(S0 + (size_t)d * DV + e4 * 4));
;         const f32x4 qa = *(const LAS f32x4*)(QK + d * 16), qb = *(const LAS f32x4*)(QK + d * 16 + 4), ka = *(const LAS f32x4*)(QK + d * 16 + 8), kb = *(const LAS f32x4*)(QK + d * 16 + 12);
;         const float dc = DECs[d];
;         o[0] += s0 * qa[0]; o[1] += s0 * qa[1]; o[2] += s0 * qa[2]; o[3] += s0 * qa[3]; o[4] += s0 * qb[0]; o[5] += s0 * qb[1]; o[6] += s0 * qb[2]; o[7] += s0 * qb[3];
;         f32x4 sn = s0 * dc; sn += v[0] * ka[0]; sn += v[1] * ka[1]; sn += v[2] * ka[2]; sn += v[3] * ka[3]; sn += v[4] * kb[0]; sn += v[5] * kb[1]; sn += v[6] * kb[2]; sn += v[7] * kb[3];
;         __builtin_nontemporal_store(sn, (f32x4*)(S1 + (size_t)d * DV + e4 * 4)); }
	v_pk_fma_f32 v[36:37], v[0:1], v[48:49], v[36:37] op_sel_hi:[1,0,1]
	v_pk_fma_f32 v[38:39], v[2:3], v[48:49], v[38:39] op_sel_hi:[1,0,1]
	v_pk_fma_f32 v[36:37], v[4:5], v[48:49], v[36:37] op_sel:[0,1,0]
	v_pk_fma_f32 v[38:39], v[6:7], v[48:49], v[38:39] op_sel:[0,1,0]
	v_pk_fma_f32 v[36:37], v[8:9], v[50:51], v[36:37] op_sel_hi:[1,0,1]
	v_pk_fma_f32 v[38:39], v[10:11], v[50:51], v[38:39] op_sel_hi:[1,0,1]
	v_mov_b32_e32 v40, v51
	v_pk_fma_f32 v[36:37], v[12:13], v[40:41], v[36:37] op_sel_hi:[1,0,1]
	v_pk_fma_f32 v[38:39], v[14:15], v[40:41], v[38:39] op_sel_hi:[1,0,1]
	s_waitcnt lgkmcnt(0)
	v_pk_fma_f32 v[36:37], v[20:21], v[52:53], v[36:37] op_sel_hi:[1,0,1]
	v_pk_fma_f32 v[38:39], v[22:23], v[52:53], v[38:39] op_sel_hi:[1,0,1]
	v_pk_fma_f32 v[36:37], v[24:25], v[52:53], v[36:37] op_sel:[0,1,0]
	v_pk_fma_f32 v[38:39], v[26:27], v[52:53], v[38:39] op_sel:[0,1,0]
	v_pk_fma_f32 v[36:37], v[28:29], v[54:55], v[36:37] op_sel_hi:[1,0,1]
	v_pk_fma_f32 v[38:39], v[30:31], v[54:55], v[38:39] op_sel_hi:[1,0,1]
	v_mov_b32_e32 v40, v55
	v_pk_fma_f32 v[36:37], v[32:33], v[40:41], v[36:37] op_sel_hi:[1,0,1]
	v_pk_fma_f32 v[38:39], v[34:35], v[40:41], v[38:39] op_sel_hi:[1,0,1]
	v_lshl_add_u64 v[40:41], v[84:85], 0, s[8:9]
	global_store_dwordx4 v[40:41], v[36:39], off nt
	v_lshl_add_u64 v[84:85], v[84:85], 0, s[44:45]
	s_nop 0
	v_lshl_add_u64 v[36:37], v[82:83], 0, s[8:9]
	ds_read_b128 v[40:43], v116 offset:4096
	ds_read_b128 v[44:47], v116 offset:4112
	ds_read_b128 v[48:51], v116 offset:4128
	ds_read_b128 v[52:55], v116 offset:4144
	ds_read2_b32 v[100:101], v16 offset0:64 offset1:80
	v_lshl_add_u64 v[82:83], v[82:83], 0, s[44:45]
	s_waitcnt lgkmcnt(4)
	v_pk_fma_f32 v[66:67], v[212:213], v[40:41], v[66:67] op_sel_hi:[1,0,1]
	v_pk_fma_f32 v[64:65], v[210:211], v[40:41], v[64:65] op_sel_hi:[1,0,1]
	v_pk_fma_f32 v[62:63], v[212:213], v[40:41], v[62:63] op_sel:[0,1,0]
	v_pk_fma_f32 v[60:61], v[210:211], v[40:41], v[60:61] op_sel:[0,1,0]
	v_mov_b32_e32 v40, v43
	v_pk_fma_f32 v[104:105], v[210:211], v[40:41], v[104:105] op_sel_hi:[1,0,1]
	v_pk_fma_f32 v[106:107], v[212:213], v[40:41], v[106:107] op_sel_hi:[1,0,1]
	s_waitcnt lgkmcnt(3)
	v_mov_b32_e32 v40, v47
	v_pk_fma_f32 v[56:57], v[210:211], v[42:43], v[56:57] op_sel_hi:[1,0,1]
	v_pk_fma_f32 v[58:59], v[212:213], v[42:43], v[58:59] op_sel_hi:[1,0,1]
	v_pk_fma_f32 v[108:109], v[212:213], v[44:45], v[108:109] op_sel_hi:[1,0,1]
	v_pk_fma_f32 v[110:111], v[210:211], v[44:45], v[110:111] op_sel_hi:[1,0,1]
	v_pk_fma_f32 v[112:113], v[212:213], v[44:45], v[112:113] op_sel:[0,1,0]
	v_pk_fma_f32 v[118:119], v[210:211], v[44:45], v[118:119] op_sel:[0,1,0]
	v_pk_fma_f32 v[122:123], v[210:211], v[46:47], v[122:123] op_sel_hi:[1,0,1]
	v_pk_fma_f32 v[102:103], v[212:213], v[46:47], v[102:103] op_sel_hi:[1,0,1]
	v_pk_fma_f32 v[120:121], v[212:213], v[40:41], v[120:121] op_sel_hi:[1,0,1]
	v_pk_fma_f32 v[124:125], v[210:211], v[40:41], v[124:125] op_sel_hi:[1,0,1]
	s_waitcnt lgkmcnt(0)
	v_pk_mul_f32 v[36:37], v[210:211], v[100:101] op_sel_hi:[1,0]
	v_pk_mul_f32 v[38:39], v[212:213], v[100:101] op_sel_hi:[1,0]
	v_pk_fma_f32 v[36:37], v[0:1], v[48:49], v[36:37] op_sel_hi:[1,0,1]
	v_pk_fma_f32 v[38:39], v[2:3], v[48:49], v[38:39] op_sel_hi:[1,0,1]
	v_pk_fma_f32 v[36:37], v[4:5], v[48:49], v[36:37] op_sel:[0,1,0]
	v_pk_fma_f32 v[38:39], v[6:7], v[48:49], v[38:39] op_sel:[0,1,0]
	v_pk_fma_f32 v[36:37], v[8:9], v[50:51], v[36:37] op_sel_hi:[1,0,1]
	v_pk_fma_f32 v[38:39], v[10:11], v[50:51], v[38:39] op_sel_hi:[1,0,1]
	v_mov_b32_e32 v40, v51
	v_pk_fma_f32 v[36:37], v[12:13], v[40:41], v[36:37] op_sel_hi:[1,0,1]
	v_pk_fma_f32 v[38:39], v[14:15], v[40:41], v[38:39] op_sel_hi:[1,0,1]
	v_pk_fma_f32 v[36:37], v[20:21], v[52:53], v[36:37] op_sel_hi:[1,0,1]
	v_pk_fma_f32 v[38:39], v[22:23], v[52:53], v[38:39] op_sel_hi:[1,0,1]
	v_pk_fma_f32 v[36:37], v[24:25], v[52:53], v[36:37] op_sel:[0,1,0]
	v_pk_fma_f32 v[38:39], v[26:27], v[52:53], v[38:39] op_sel:[0,1,0]
	v_pk_fma_f32 v[36:37], v[28:29], v[54:55], v[36:37] op_sel_hi:[1,0,1]
	v_pk_fma_f32 v[38:39], v[30:31], v[54:55], v[38:39] op_sel_hi:[1,0,1]
	v_mov_b32_e32 v40, v55
	v_pk_fma_f32 v[36:37], v[32:33], v[40:41], v[36:37] op_sel_hi:[1,0,1]
	v_pk_fma_f32 v[38:39], v[34:35], v[40:41], v[38:39] op_sel_hi:[1,0,1]
	v_lshl_add_u64 v[40:41], v[80:81], 0, s[8:9]
	global_store_dwordx4 v[40:41], v[36:39], off nt
	v_lshl_add_u64 v[80:81], v[80:81], 0, s[44:45]
	s_nop 0
	v_lshl_add_u64 v[36:37], v[78:79], 0, s[8:9]
	ds_read_b128 v[40:43], v116 offset:5120
	ds_read_b128 v[44:47], v116 offset:5136
	ds_read_b128 v[48:51], v116 offset:5152
	ds_read_b128 v[52:55], v116 offset:5168
	v_lshl_add_u64 v[78:79], v[78:79], 0, s[44:45]
	s_waitcnt lgkmcnt(3)
	v_pk_fma_f32 v[126:127], v[218:219], v[40:41], v[66:67] op_sel_hi:[1,0,1]
	v_pk_fma_f32 v[128:129], v[216:217], v[40:41], v[64:65] op_sel_hi:[1,0,1]
	v_pk_fma_f32 v[130:131], v[218:219], v[40:41], v[62:63] op_sel:[0,1,0]
	v_pk_fma_f32 v[132:133], v[216:217], v[40:41], v[60:61] op_sel:[0,1,0]
	v_mov_b32_e32 v40, v43
	v_pk_fma_f32 v[106:107], v[218:219], v[40:41], v[106:107] op_sel_hi:[1,0,1]
	v_pk_fma_f32 v[104:105], v[216:217], v[40:41], v[104:105] op_sel_hi:[1,0,1]
	s_waitcnt lgkmcnt(2)
; #define LAS __attribute__((address_space(3)))
; template <int TY> __device__ __forceinline__ void sample_item(const Params& p, ldsp lds, int item) {
;     ...
; #pragma unroll 8
;     for (int d = dg; d < DK; d += NG) { const f32x4 s0 = __builtin_nontemporal_load((const f32x4*)(S0 + (size_t)d * DV + e4 * 4));
;         const f32x4 qa = *(const LAS f32x4*)(QK + d * 16), qb = *(const LAS f32x4*)(QK + d * 16 + 4), ka = *(const LAS f32x4*)(QK + d * 16 + 8), kb = *(const LAS f32x4*)(QK + d * 16 + 12);
;         const float dc = DECs[d];
;         o[0] += s0 * qa[0]; o[1] += s0 * qa[1]; o[2] += s0 * qa[2]; o[3] += s0 * qa[3]; o[4] += s0 * qb[0]; o[5] += s0 * qb[1]; o[6] += s0 * qb[2]; o[7] += s0 * qb[3];
;         f32x4 sn = s0 * dc; sn += v[0] * ka[0]; sn += v[1] * ka[1]; sn += v[2] * ka[2]; sn += v[3] * ka[3]; sn += v[4] * kb[0]; sn += v[5] * kb[1]; sn += v[6] * kb[2]; sn += v[7] * kb[3];
;         __builtin_nontemporal_store(sn, (f32x4*)(S1 + (size_t)d * DV + e4 * 4)); }
	v_mov_b32_e32 v40, v47
	v_pk_fma_f32 v[140:141], v[218:219], v[40:41], v[120:121] op_sel_hi:[1,0,1]
	v_pk_fma_f32 v[124:125], v[216:217], v[40:41], v[124:125] op_sel_hi:[1,0,1]
	v_mov_b32_e32 v40, v101
	v_pk_fma_f32 v[134:135], v[218:219], v[42:43], v[58:59] op_sel_hi:[1,0,1]
	v_pk_fma_f32 v[136:137], v[216:217], v[42:43], v[56:57] op_sel_hi:[1,0,1]
	v_pk_fma_f32 v[108:109], v[218:219], v[44:45], v[108:109] op_sel_hi:[1,0,1]
	v_pk_fma_f32 v[110:111], v[216:217], v[44:45], v[110:111] op_sel_hi:[1,0,1]
	v_pk_fma_f32 v[112:113], v[218:219], v[44:45], v[112:113] op_sel:[0,1,0]
	v_pk_fma_f32 v[44:45], v[216:217], v[44:45], v[118:119] op_sel:[0,1,0]
	v_pk_fma_f32 v[138:139], v[218:219], v[46:47], v[102:103] op_sel_hi:[1,0,1]
	v_pk_fma_f32 v[122:123], v[216:217], v[46:47], v[122:123] op_sel_hi:[1,0,1]
	v_pk_mul_f32 v[36:37], v[216:217], v[40:41] op_sel_hi:[1,0]
	v_pk_mul_f32 v[38:39], v[218:219], v[40:41] op_sel_hi:[1,0]
	s_waitcnt lgkmcnt(1)
	v_pk_fma_f32 v[36:37], v[0:1], v[48:49], v[36:37] op_sel_hi:[1,0,1]
	v_pk_fma_f32 v[38:39], v[2:3], v[48:49], v[38:39] op_sel_hi:[1,0,1]
	v_pk_fma_f32 v[36:37], v[4:5], v[48:49], v[36:37] op_sel:[0,1,0]
	v_pk_fma_f32 v[38:39], v[6:7], v[48:49], v[38:39] op_sel:[0,1,0]
	v_pk_fma_f32 v[36:37], v[8:9], v[50:51], v[36:37] op_sel_hi:[1,0,1]
	v_pk_fma_f32 v[38:39], v[10:11], v[50:51], v[38:39] op_sel_hi:[1,0,1]
	v_mov_b32_e32 v40, v51
	v_pk_fma_f32 v[36:37], v[12:13], v[40:41], v[36:37] op_sel_hi:[1,0,1]
	v_pk_fma_f32 v[38:39], v[14:15], v[40:41], v[38:39] op_sel_hi:[1,0,1]
	s_waitcnt lgkmcnt(0)
	v_pk_fma_f32 v[36:37], v[20:21], v[52:53], v[36:37] op_sel_hi:[1,0,1]
	v_pk_fma_f32 v[38:39], v[22:23], v[52:53], v[38:39] op_sel_hi:[1,0,1]
	v_pk_fma_f32 v[36:37], v[24:25], v[52:53], v[36:37] op_sel:[0,1,0]
	v_pk_fma_f32 v[38:39], v[26:27], v[52:53], v[38:39] op_sel:[0,1,0]
	v_pk_fma_f32 v[36:37], v[28:29], v[54:55], v[36:37] op_sel_hi:[1,0,1]
	v_pk_fma_f32 v[38:39], v[30:31], v[54:55], v[38:39] op_sel_hi:[1,0,1]
	v_mov_b32_e32 v40, v55
	v_pk_fma_f32 v[36:37], v[32:33], v[40:41], v[36:37] op_sel_hi:[1,0,1]
	v_pk_fma_f32 v[38:39], v[34:35], v[40:41], v[38:39] op_sel_hi:[1,0,1]
	v_lshl_add_u64 v[40:41], v[76:77], 0, s[8:9]
	global_store_dwordx4 v[40:41], v[36:39], off nt
	v_lshl_add_u64 v[76:77], v[76:77], 0, s[44:45]
	s_nop 0
	v_lshl_add_u64 v[36:37], v[74:75], 0, s[8:9]
	ds_read_b128 v[36:39], v116 offset:6144
	ds_read_b128 v[60:63], v116 offset:6160
	ds_read_b128 v[64:67], v116 offset:6176
	ds_read_b128 v[118:121], v116 offset:6192
	ds_read2_b32 v[100:101], v16 offset0:96 offset1:112
	s_waitcnt lgkmcnt(4)
	v_mov_b32_e32 v50, v39
	v_add_u32_e32 v16, 0x200, v16
	v_lshl_add_u64 v[74:75], v[74:75], 0, s[44:45]
	v_pk_fma_f32 v[40:41], v[224:225], v[36:37], v[126:127] op_sel_hi:[1,0,1]
	v_pk_fma_f32 v[42:43], v[222:223], v[36:37], v[128:129] op_sel_hi:[1,0,1]
	v_pk_fma_f32 v[46:47], v[224:225], v[36:37], v[130:131] op_sel:[0,1,0]
	v_pk_fma_f32 v[48:49], v[222:223], v[36:37], v[132:133] op_sel:[0,1,0]
	v_pk_fma_f32 v[36:37], v[222:223], v[38:39], v[136:137] op_sel_hi:[1,0,1]
	v_pk_fma_f32 v[52:53], v[224:225], v[38:39], v[134:135] op_sel_hi:[1,0,1]
	v_pk_fma_f32 v[38:39], v[222:223], v[50:51], v[104:105] op_sel_hi:[1,0,1]
	v_pk_fma_f32 v[54:55], v[224:225], v[50:51], v[106:107] op_sel_hi:[1,0,1]
	s_waitcnt lgkmcnt(3)
	v_pk_fma_f32 v[50:51], v[224:225], v[60:61], v[108:109] op_sel_hi:[1,0,1]
	v_pk_fma_f32 v[102:103], v[222:223], v[60:61], v[110:111] op_sel_hi:[1,0,1]
	v_pk_fma_f32 v[104:105], v[224:225], v[60:61], v[112:113] op_sel:[0,1,0]
	v_pk_fma_f32 v[106:107], v[222:223], v[60:61], v[44:45] op_sel:[0,1,0]
	v_mov_b32_e32 v60, v63
	v_pk_fma_f32 v[44:45], v[222:223], v[62:63], v[122:123] op_sel_hi:[1,0,1]
	v_pk_fma_f32 v[112:113], v[224:225], v[62:63], v[138:139] op_sel_hi:[1,0,1]
	v_pk_fma_f32 v[108:109], v[224:225], v[60:61], v[140:141] op_sel_hi:[1,0,1]
	v_pk_fma_f32 v[110:111], v[222:223], v[60:61], v[124:125] op_sel_hi:[1,0,1]
	s_waitcnt lgkmcnt(0)
; #define LAS __attribute__((address_space(3)))
; template <int TY> __device__ __forceinline__ void sample_item(const Params& p, ldsp lds, int item) {
;     ...
; #pragma unroll 8
;     for (int d = dg; d < DK; d += NG) { const f32x4 s0 = __builtin_nontemporal_load((const f32x4*)(S0 + (size_t)d * DV + e4 * 4));
;         const f32x4 qa = *(const LAS f32x4*)(QK + d * 16), qb = *(const LAS f32x4*)(QK + d * 16 + 4), ka = *(const LAS f32x4*)(QK + d * 16 + 8), kb = *(const LAS f32x4*)(QK + d * 16 + 12);
;         const float dc = DECs[d];
;         o[0] += s0 * qa[0]; o[1] += s0 * qa[1]; o[2] += s0 * qa[2]; o[3] += s0 * qa[3]; o[4] += s0 * qb[0]; o[5] += s0 * qb[1]; o[6] += s0 * qb[2]; o[7] += s0 * qb[3];
;         f32x4 sn = s0 * dc; sn += v[0] * ka[0]; sn += v[1] * ka[1]; sn += v[2] * ka[2]; sn += v[3] * ka[3]; sn += v[4] * kb[0]; sn += v[5] * kb[1]; sn += v[6] * kb[2]; sn += v[7] * kb[3];
;         __builtin_nontemporal_store(sn, (f32x4*)(S1 + (size_t)d * DV + e4 * 4)); }
	v_pk_mul_f32 v[56:57], v[222:223], v[100:101] op_sel_hi:[1,0]
	v_pk_mul_f32 v[58:59], v[224:225], v[100:101] op_sel_hi:[1,0]
	v_pk_fma_f32 v[56:57], v[0:1], v[64:65], v[56:57] op_sel_hi:[1,0,1]
	v_pk_fma_f32 v[58:59], v[2:3], v[64:65], v[58:59] op_sel_hi:[1,0,1]
	v_pk_fma_f32 v[56:57], v[4:5], v[64:65], v[56:57] op_sel:[0,1,0]
	v_pk_fma_f32 v[58:59], v[6:7], v[64:65], v[58:59] op_sel:[0,1,0]
	v_pk_fma_f32 v[56:57], v[8:9], v[66:67], v[56:57] op_sel_hi:[1,0,1]
	v_pk_fma_f32 v[58:59], v[10:11], v[66:67], v[58:59] op_sel_hi:[1,0,1]
	v_mov_b32_e32 v60, v67
	v_pk_fma_f32 v[56:57], v[12:13], v[60:61], v[56:57] op_sel_hi:[1,0,1]
	v_pk_fma_f32 v[58:59], v[14:15], v[60:61], v[58:59] op_sel_hi:[1,0,1]
	v_pk_fma_f32 v[56:57], v[20:21], v[118:119], v[56:57] op_sel_hi:[1,0,1]
	v_pk_fma_f32 v[58:59], v[22:23], v[118:119], v[58:59] op_sel_hi:[1,0,1]
	v_pk_fma_f32 v[56:57], v[24:25], v[118:119], v[56:57] op_sel:[0,1,0]
	v_pk_fma_f32 v[58:59], v[26:27], v[118:119], v[58:59] op_sel:[0,1,0]
	v_pk_fma_f32 v[56:57], v[28:29], v[120:121], v[56:57] op_sel_hi:[1,0,1]
	v_pk_fma_f32 v[58:59], v[30:31], v[120:121], v[58:59] op_sel_hi:[1,0,1]
	v_mov_b32_e32 v60, v121
	v_pk_fma_f32 v[56:57], v[32:33], v[60:61], v[56:57] op_sel_hi:[1,0,1]
	v_pk_fma_f32 v[58:59], v[34:35], v[60:61], v[58:59] op_sel_hi:[1,0,1]
	v_lshl_add_u64 v[60:61], v[72:73], 0, s[8:9]
	global_store_dwordx4 v[60:61], v[56:59], off nt
	v_mov_b32_e32 v100, v101
	v_lshl_add_u64 v[72:73], v[72:73], 0, s[44:45]
	v_lshl_add_u64 v[56:57], v[70:71], 0, s[8:9]
	ds_read_b128 v[122:125], v116 offset:7168
	ds_read_b128 v[126:129], v116 offset:7184
	ds_read_b128 v[130:133], v116 offset:7200
	ds_read_b128 v[134:137], v116 offset:7216
	v_add_u32_e32 v116, 0x2000, v116
	v_lshl_add_u64 v[70:71], v[70:71], 0, s[44:45]
	s_waitcnt lgkmcnt(3)
	v_pk_fma_f32 v[60:61], v[228:229], v[122:123], v[48:49] op_sel:[0,1,0]
	s_waitcnt lgkmcnt(2)
	v_pk_fma_f32 v[48:49], v[228:229], v[126:127], v[102:103] op_sel_hi:[1,0,1]
	v_pk_mul_f32 v[102:103], v[228:229], v[100:101] op_sel_hi:[1,0]
	v_pk_mul_f32 v[100:101], v[230:231], v[100:101] op_sel_hi:[1,0]
	s_waitcnt lgkmcnt(1)
	v_pk_fma_f32 v[102:103], v[0:1], v[130:131], v[102:103] op_sel_hi:[1,0,1]
	v_pk_fma_f32 v[100:101], v[2:3], v[130:131], v[100:101] op_sel_hi:[1,0,1]
	v_pk_fma_f32 v[102:103], v[4:5], v[130:131], v[102:103] op_sel:[0,1,0]
	v_pk_fma_f32 v[100:101], v[6:7], v[130:131], v[100:101] op_sel:[0,1,0]
	v_pk_fma_f32 v[64:65], v[228:229], v[122:123], v[42:43] op_sel_hi:[1,0,1]
	v_pk_fma_f32 v[42:43], v[230:231], v[126:127], v[104:105] op_sel:[0,1,0]
	v_pk_fma_f32 v[100:101], v[10:11], v[132:133], v[100:101] op_sel_hi:[1,0,1]
	v_pk_fma_f32 v[102:103], v[8:9], v[132:133], v[102:103] op_sel_hi:[1,0,1]
	v_mov_b32_e32 v104, v133
	v_pk_fma_f32 v[102:103], v[12:13], v[104:105], v[102:103] op_sel_hi:[1,0,1]
	v_pk_fma_f32 v[100:101], v[14:15], v[104:105], v[100:101] op_sel_hi:[1,0,1]
	s_waitcnt lgkmcnt(0)
	v_pk_fma_f32 v[102:103], v[20:21], v[134:135], v[102:103] op_sel_hi:[1,0,1]
	v_pk_fma_f32 v[100:101], v[22:23], v[134:135], v[100:101] op_sel_hi:[1,0,1]
	v_pk_fma_f32 v[56:57], v[228:229], v[124:125], v[36:37] op_sel_hi:[1,0,1]
	v_mov_b32_e32 v36, v125
	v_pk_fma_f32 v[102:103], v[24:25], v[134:135], v[102:103] op_sel:[0,1,0]
	v_pk_fma_f32 v[100:101], v[26:27], v[134:135], v[100:101] op_sel:[0,1,0]
	v_pk_fma_f32 v[58:59], v[230:231], v[124:125], v[52:53] op_sel_hi:[1,0,1]
	v_pk_fma_f32 v[54:55], v[230:231], v[36:37], v[54:55] op_sel_hi:[1,0,1]
	v_pk_fma_f32 v[52:53], v[228:229], v[36:37], v[38:39] op_sel_hi:[1,0,1]
	v_pk_fma_f32 v[36:37], v[228:229], v[128:129], v[44:45] op_sel_hi:[1,0,1]
	v_mov_b32_e32 v44, v129
	v_pk_fma_f32 v[104:105], v[30:31], v[136:137], v[100:101] op_sel_hi:[1,0,1]
	v_pk_fma_f32 v[100:101], v[28:29], v[136:137], v[102:103] op_sel_hi:[1,0,1]
	v_mov_b32_e32 v102, v137
	v_pk_fma_f32 v[66:67], v[230:231], v[122:123], v[40:41] op_sel_hi:[1,0,1]
	v_pk_fma_f32 v[62:63], v[230:231], v[122:123], v[46:47] op_sel:[0,1,0]
	v_pk_fma_f32 v[50:51], v[230:231], v[126:127], v[50:51] op_sel_hi:[1,0,1]
	v_pk_fma_f32 v[40:41], v[228:229], v[126:127], v[106:107] op_sel:[0,1,0]
	v_pk_fma_f32 v[38:39], v[230:231], v[128:129], v[112:113] op_sel_hi:[1,0,1]
	v_pk_fma_f32 v[46:47], v[230:231], v[44:45], v[108:109] op_sel_hi:[1,0,1]
	v_pk_fma_f32 v[44:45], v[228:229], v[44:45], v[110:111] op_sel_hi:[1,0,1]
	v_pk_fma_f32 v[100:101], v[32:33], v[102:103], v[100:101] op_sel_hi:[1,0,1]
	v_pk_fma_f32 v[102:103], v[34:35], v[102:103], v[104:105] op_sel_hi:[1,0,1]
	v_lshl_add_u64 v[104:105], v[18:19], 0, s[8:9]
	v_lshl_add_u64 v[18:19], v[18:19], 0, s[44:45]
	global_store_dwordx4 v[104:105], v[100:103], off nt
	s_andn2_b64 exec, exec, s[16:17]
	v_mov_b32_e32 v118, v228
	v_mov_b32_e32 v119, v229
	v_mov_b32_e32 v120, v230
	v_mov_b32_e32 v121, v231
	s_cbranch_execnz .LBB0_1005
	s_or_b64 exec, exec, s[16:17]

; __device__ __forceinline__ int otid() { int t = threadIdx.x; asm volatile("" : "+v"(t)); return t; }
; #define LAS __attribute__((address_space(3)))
; __device__ __forceinline__ float logsig(float x) { return fminf(x, 0.f) - __logf(1.0f + __expf(-fabsf(x))); }
; #define BSYNC() do { asm volatile("s_waitcnt vmcnt(0) lgkmcnt(0)" ::: "memory"); __syncthreads(); } while (0)
; template <int TY> __device__ __forceinline__ void ma_even_item(const Params& p, ldsp lds, int item) {
;     constexpr int DK = TY ? 128 : 64, NSEG = NTHREADS / DK, SEGL = 64 / NSEG;
;     const int tid = otid(), lane = tid & 63, wave = __builtin_amdgcn_readfirstlane(tid >> 6), l15 = lane & 15, q4 = lane >> 4;
;     const int bh = item >> 5, c = item & 31, b = bh >> 2, h = bh & 3, row0 = b * 2048 + c * 64;
;     const int d = tid % DK, sg = tid / DK;
;     LAS float* Bl = (LAS float*)lds; LAS float* SEG = (LAS float*)(lds + 32768); LAS float* LRs = (LAS float*)(lds + 36864);
;     ldsp KHT = lds + 40960; ldsp VT = lds + 59392;
;     const bf16_t* Pb = (const bf16_t*)(p.ws + WS_P) + (size_t)row0 * NE;
;     if (TY == 0) { for (int idx = tid; idx < 1024; idx += NTHREADS) LRs[idx] = bf2f(Pb[(size_t)(idx >> 4) * NE + E_LR + (idx & 15)]); }
;     stage_T<128>(VT, 72, Pb + (TY ? E_IB : E_VA) + h * 128, NE, wave, lane);
;     float w2[16]; float bias = 0.f, lbv = 0.f;
;     if (TY == 0) {
; #pragma unroll
;         for (int r = 0; r < 16; ++r) w2[r] = p.in[10][r * 256 + h * 64 + d];
;         bias = p.in[11][h * 64 + d];
;     } else { const float t0 = p.in[13][h * 128 + d], t1 = p.in[13][512 + h * 128 + d], t2 = p.in[13][1024 + h * 128 + d];
;         const float mx = fmaxf(t0, fmaxf(t1, t2)); const float e0 = __expf(t0 - mx), e1 = __expf(t1 - mx), e2 = __expf(t2 - mx); lbv = e0 / (e0 + e1 + e2); }
;     BSYNC();
;     float run = 0.f;
; #pragma unroll
;     for (int i = 0; i < SEGL; ++i) { const int s = sg * SEGL + i; float g;
;         if (TY == 0) { float x = bias;
; #pragma unroll
;             for (int r = 0; r < 16; ++r) x += LRs[s * 16 + r] * w2[r];
;             g = logsig(x) * 0.0625f;
;         } else { const float x = bf2f(Pb[(size_t)s * NE + E_FB + h * 128 + d]); const float sig = __builtin_amdgcn_rcpf(1.0f + __expf(-x)); g = __logf(lbv + (1.0f - lbv) * sig); }
.LBB0_1052:
	v_mov_b32_e32 v74, v161
	v_readlane_b32 s1, v253, 59
	v_readfirstlane_b32 s0, v74
	s_ashr_i32 s8, s0, 6
	s_lshl_b32 s0, s12, 4
	s_and_b32 s0, s0, 0xfffff800
	s_or_b32 s9, s0, s1
	s_mul_i32 s0, s9, 0x1e00
	s_mul_hi_i32 s1, s9, 0x1e00
	s_add_u32 s0, s26, s0
	s_addc_u32 s1, s27, s1
	s_lshl_b32 s13, s12, 2
	s_and_b32 s13, s13, 0x180
	s_lshl_b32 s40, s13, 1
	s_add_u32 s14, s0, s40
	s_addc_u32 s15, s1, 0
	s_lshl_b32 s16, s8, 5
	v_and_b32_e32 v0, 31, v74
	v_and_or_b32 v13, s16, 32, v0
	v_bfe_u32 v2, v74, 5, 1
	v_mul_u32_u24_e32 v0, 0xf00, v13
	v_and_or_b32 v8, s8, -2, v2
	v_lshlrev_b32_e32 v16, 1, v0
	v_lshlrev_b32_e32 v2, 3, v8
	v_lshl_add_u64 v[0:1], s[14:15], 0, v[16:17]
	v_ashrrev_i32_e32 v3, 31, v2
	v_lshl_add_u64 v[4:5], v[2:3], 1, v[0:1]
	v_add_co_u32_e32 v0, vcc, s57, v4
	s_mov_b64 s[14:15], 0x1400
	s_nop 0
	v_addc_co_u32_e32 v1, vcc, 0, v5, vcc
	global_load_dwordx4 v[0:3], v[0:1], off offset:1024
	v_lshl_add_u64 v[4:5], v[4:5], 0, s[14:15]
	global_load_dwordx4 v[4:7], v[4:5], off offset:128
	v_ashrrev_i32_e32 v9, 31, v74
	v_lshrrev_b32_e32 v9, 25, v9
	v_add_u32_e32 v9, v74, v9
	v_ashrrev_i32_e32 v12, 7, v9
	v_and_b32_e32 v9, 0xffffff80, v9
	s_movk_i32 s14, 0x240
	v_mul_lo_u32 v16, v8, s14
	v_sub_u32_e32 v8, v74, v9
	v_add_u32_e32 v64, s13, v8
	v_readlane_b32 s76, v252, 20
	v_ashrrev_i32_e32 v65, 31, v64
	v_readlane_b32 s86, v252, 30
	v_readlane_b32 s87, v252, 31
	v_lshlrev_b32_e32 v75, 4, v12
	v_mov_b64_e32 v[44:45], s[0:1]
	v_lshl_add_u64 v[20:21], v[64:65], 2, s[86:87]
	v_add_co_u32_e32 v22, vcc, s57, v20
	v_ashrrev_i32_e32 v9, 31, v8
	s_nop 0
	v_addc_co_u32_e32 v23, vcc, 0, v21, vcc
	global_load_dword v26, v[20:21], off
	s_nop 0
	global_load_dword v20, v[20:21], off offset:2048
	s_nop 0
	global_load_dword v21, v[22:23], off
	v_mad_i64_i32 v[10:11], s[0:1], v75, s55, v[44:45]
	v_lshlrev_b64 v[46:47], 1, v[8:9]
	v_lshl_add_u64 v[10:11], v[10:11], 0, s[40:41]
	v_lshl_add_u64 v[72:73], v[10:11], 0, v[46:47]
	v_or_b32_e32 v10, v13, v16
	v_add_co_u32_e32 v70, vcc, s57, v72
	v_lshl_add_u32 v10, v10, 1, 0
	s_nop 0
	v_addc_co_u32_e32 v71, vcc, 0, v73, vcc
	v_add_u32_e32 v11, 0xe800, v10
	v_or_b32_e32 v87, 1, v75
	v_mad_i64_i32 v[14:15], s[0:1], v87, s55, v[44:45]
	v_lshl_add_u64 v[14:15], v[14:15], 0, s[40:41]
	v_lshl_add_u64 v[60:61], v[14:15], 0, v[46:47]
	v_add_co_u32_e32 v62, vcc, s57, v60
	v_or_b32_e32 v86, 2, v75
	s_nop 0
	v_addc_co_u32_e32 v63, vcc, 0, v61, vcc
	v_mad_i64_i32 v[18:19], s[0:1], v86, s55, v[44:45]
	v_lshl_add_u64 v[18:19], v[18:19], 0, s[40:41]
	v_or_b32_e32 v84, 3, v75
	v_lshl_add_u64 v[56:57], v[18:19], 0, v[46:47]
	v_add_co_u32_e32 v58, vcc, s57, v56
	v_or_b32_e32 v82, 5, v75
	s_nop 0
	v_addc_co_u32_e32 v59, vcc, 0, v57, vcc
	v_or_b32_e32 v83, 4, v75
	v_or_b32_e32 v81, 6, v75
	v_or_b32_e32 v79, 7, v75
	s_mov_b32 s13, 0x3f317217
	s_mov_b32 s14, 0x7f800000
	v_lshlrev_b32_e32 v92, 2, v8
	v_add_u32_e32 v65, 0, v92
	v_lshlrev_b32_e32 v106, 13, v12
	v_add_u32_e32 v93, v65, v106
	s_waitcnt vmcnt(0)
	ds_write_b16 v10, v0 offset:59392
	ds_write_b16_d16_hi v10, v0 offset:59536
	ds_write_b16 v10, v1 offset:59680
	ds_write_b16_d16_hi v10, v1 offset:59824
	ds_write_b16 v10, v2 offset:59968
	ds_write_b16_d16_hi v10, v2 offset:60112
	ds_write_b16 v10, v3 offset:60256
	ds_write_b16_d16_hi v10, v3 offset:60400
	ds_write_b16 v11, v4 offset:9216
	ds_write_b16_d16_hi v11, v4 offset:9360
	ds_write_b16 v11, v5 offset:9504
	ds_write_b16_d16_hi v11, v5 offset:9648
	ds_write_b16 v11, v6 offset:9792
	ds_write_b16_d16_hi v11, v6 offset:9936
	ds_write_b16 v11, v7 offset:10080
	ds_write_b16_d16_hi v11, v7 offset:10224
	s_waitcnt vmcnt(0) lgkmcnt(0)
	s_waitcnt lgkmcnt(0)
	s_barrier
	global_load_ushort v13, v[70:71], off
	global_load_ushort v14, v[62:63], off
	v_mad_i64_i32 v[0:1], s[0:1], v84, s55, v[44:45]
	v_lshl_add_u64 v[0:1], v[0:1], 0, s[40:41]
	v_lshl_add_u64 v[52:53], v[0:1], 0, v[46:47]
	global_load_ushort v0, v[58:59], off
	v_mad_i64_i32 v[4:5], s[0:1], v82, s55, v[44:45]
	v_add_co_u32_e32 v54, vcc, s57, v52
	v_lshl_add_u64 v[4:5], v[4:5], 0, s[40:41]
	s_nop 0
	v_addc_co_u32_e32 v55, vcc, 0, v53, vcc
	v_lshl_add_u64 v[40:41], v[4:5], 0, v[46:47]
	global_load_ushort v4, v[54:55], off
	v_mad_i64_i32 v[2:3], s[0:1], v83, s55, v[44:45]
	v_lshl_add_u64 v[2:3], v[2:3], 0, s[40:41]
	v_lshl_add_u64 v[48:49], v[2:3], 0, v[46:47]
	v_add_co_u32_e32 v50, vcc, s57, v48
	v_mad_i64_i32 v[6:7], s[0:1], v81, s55, v[44:45]
	s_nop 0
	v_addc_co_u32_e32 v51, vcc, 0, v49, vcc
	v_lshl_add_u64 v[6:7], v[6:7], 0, s[40:41]
	v_add_co_u32_e32 v42, vcc, s57, v40
	v_mad_i64_i32 v[10:11], s[0:1], v79, s55, v[44:45]
	v_lshl_add_u64 v[24:25], v[6:7], 0, v[46:47]
	v_addc_co_u32_e32 v43, vcc, 0, v41, vcc
	v_lshl_add_u64 v[10:11], v[10:11], 0, s[40:41]
	v_add_co_u32_e32 v30, vcc, s57, v24
	v_lshl_add_u64 v[10:11], v[10:11], 0, v[46:47]
	s_nop 0
	v_addc_co_u32_e32 v31, vcc, 0, v25, vcc
	v_max3_f32 v1, v26, v20, v21
	v_add_co_u32_e32 v18, vcc, s57, v10
	v_sub_f32_e32 v3, v20, v1
	s_nop 0
	v_addc_co_u32_e32 v19, vcc, 0, v11, vcc
	global_load_ushort v6, v[50:51], off
	global_load_ushort v7, v[42:43], off
	global_load_ushort v15, v[30:31], off
	global_load_ushort v20, v[18:19], off
	v_sub_f32_e32 v2, v26, v1
	v_sub_f32_e32 v1, v21, v1
	v_mul_f32_e32 v2, 0x3fb8aa3b, v2
	v_mul_f32_e32 v3, 0x3fb8aa3b, v3
	v_mul_f32_e32 v1, 0x3fb8aa3b, v1
	v_exp_f32_e32 v2, v2
	v_exp_f32_e32 v3, v3
	v_exp_f32_e32 v1, v1
	v_lshl_add_u32 v94, v87, 9, v65
	v_lshl_add_u32 v95, v86, 9, v65
	v_add_f32_e32 v3, v2, v3
	v_add_f32_e32 v1, v1, v3
	v_div_scale_f32 v3, s[0:1], v1, v1, v2
	v_rcp_f32_e32 v5, v3
	v_div_scale_f32 v16, vcc, v2, v1, v2
	v_lshl_add_u32 v96, v84, 9, v65
	v_fma_f32 v21, -v3, v5, 1.0
	v_fmac_f32_e32 v5, v21, v5
	v_mul_f32_e32 v21, v16, v5
	v_fma_f32 v22, -v3, v21, v16
	v_fmac_f32_e32 v21, v22, v5
	v_fma_f32 v3, -v3, v21, v16
	v_div_fmas_f32 v3, v3, v5, v21
	v_div_fixup_f32 v16, v3, v1, v2
	v_sub_f32_e32 v76, 1.0, v16
	v_lshl_add_u32 v105, v83, 9, v65
	v_or_b32_e32 v77, 8, v75
	v_or_b32_e32 v91, 9, v75
	v_or_b32_e32 v90, 10, v75
	v_or_b32_e32 v89, 11, v75
	v_lshl_add_u32 v107, v82, 9, v65
	s_waitcnt vmcnt(7)
; __device__ __forceinline__ float logsig(float x) { return fminf(x, 0.f) - __logf(1.0f + __expf(-fabsf(x))); }
; template <int TY> __device__ __forceinline__ void ma_even_item(const Params& p, ldsp lds, int item) {
;     ...
; #pragma unroll
;     for (int i = 0; i < SEGL; ++i) { const int s = sg * SEGL + i; float g;
;         if (TY == 0) { float x = bias;
; #pragma unroll
;             for (int r = 0; r < 16; ++r) x += LRs[s * 16 + r] * w2[r];
;             g = logsig(x) * 0.0625f;
;         } else { const float x = bf2f(Pb[(size_t)s * NE + E_FB + h * 128 + d]); const float sig = __builtin_amdgcn_rcpf(1.0f + __expf(-x)); g = __logf(lbv + (1.0f - lbv) * sig); }
;         run += g; Bl[s * DK + d] = run; }
	v_lshlrev_b32_e32 v13, 16, v13
	v_mul_f32_e32 v13, 0xbfb8aa3b, v13
	v_exp_f32_e32 v13, v13
	s_waitcnt vmcnt(6)
	v_lshlrev_b32_e32 v3, 16, v14
	v_mul_f32_e32 v3, 0xbfb8aa3b, v3
	v_exp_f32_e32 v3, v3
	v_add_f32_e32 v13, 1.0, v13
	v_rcp_f32_e32 v13, v13
	s_waitcnt vmcnt(5)
	v_lshlrev_b32_e32 v0, 16, v0
	v_mul_f32_e32 v0, 0xbfb8aa3b, v0
	v_exp_f32_e32 v0, v0
	v_fma_f32 v1, v76, v13, v16
	v_cmp_gt_f32_e32 vcc, s33, v1
	v_lshl_add_u32 v108, v81, 9, v65
	v_add_f32_e32 v0, 1.0, v0
	v_cndmask_b32_e64 v2, 0, 32, vcc
	v_ldexp_f32 v1, v1, v2
	v_log_f32_e32 v1, v1
	v_rcp_f32_e32 v0, v0
	v_or_b32_e32 v88, 12, v75
	v_or_b32_e32 v85, 13, v75
	v_mul_f32_e32 v2, 0x3f317217, v1
	v_fma_f32 v2, v1, s13, -v2
	v_fmac_f32_e32 v2, 0x3377d1cf, v1
	v_fmac_f32_e32 v2, 0x3f317217, v1
	v_cmp_lt_f32_e64 s[0:1], |v1|, s14
	v_fma_f32 v0, v76, v0, v16
	v_or_b32_e32 v78, 14, v75
	v_cndmask_b32_e64 v1, v1, v2, s[0:1]
	v_add_f32_e32 v2, 1.0, v3
	v_rcp_f32_e32 v2, v2
	v_cndmask_b32_e32 v3, 0, v185, vcc
	v_sub_f32_e32 v1, v1, v3
	v_add_f32_e32 v1, 0, v1
	v_fma_f32 v2, v76, v2, v16
	v_cmp_gt_f32_e32 vcc, s33, v2
	ds_write_b32 v93, v1
	v_or_b32_e32 v80, 15, v75
	v_cndmask_b32_e64 v3, 0, 32, vcc
	v_ldexp_f32 v2, v2, v3
	v_log_f32_e32 v2, v2
	v_lshl_add_u32 v109, v79, 9, v65
	v_lshl_add_u32 v104, v80, 9, v65
	v_add3_u32 v92, 0, v106, v92
	v_mul_f32_e32 v3, 0x3f317217, v2
	v_fma_f32 v3, v2, s13, -v3
	v_fmac_f32_e32 v3, 0x3377d1cf, v2
	v_fmac_f32_e32 v3, 0x3f317217, v2
	v_cmp_lt_f32_e64 s[0:1], |v2|, s14
	v_readlane_b32 s77, v252, 21
	v_readlane_b32 s78, v252, 22
	v_cndmask_b32_e64 v2, v2, v3, s[0:1]
	v_cndmask_b32_e32 v3, 0, v185, vcc
	v_cmp_gt_f32_e32 vcc, s33, v0
	v_sub_f32_e32 v2, v2, v3
	v_add_f32_e32 v1, v1, v2
	v_cndmask_b32_e64 v3, 0, 32, vcc
	v_ldexp_f32 v0, v0, v3
	s_waitcnt vmcnt(4)
	v_lshlrev_b32_e32 v3, 16, v4
	v_mul_f32_e32 v3, 0xbfb8aa3b, v3
	v_log_f32_e32 v0, v0
	v_exp_f32_e32 v3, v3
	ds_write_b32 v94, v1
	v_readlane_b32 s79, v252, 23
	v_mul_f32_e32 v2, 0x3f317217, v0
	v_add_f32_e32 v3, 1.0, v3
	v_fma_f32 v2, v0, s13, -v2
	v_rcp_f32_e32 v3, v3
	v_fmac_f32_e32 v2, 0x3377d1cf, v0
	v_fmac_f32_e32 v2, 0x3f317217, v0
	v_cmp_lt_f32_e64 s[0:1], |v0|, s14
	v_readlane_b32 s80, v252, 24
	v_readlane_b32 s81, v252, 25
	v_cndmask_b32_e64 v0, v0, v2, s[0:1]
	v_cndmask_b32_e32 v2, 0, v185, vcc
	v_sub_f32_e32 v0, v0, v2
	v_fma_f32 v2, v76, v3, v16
	v_cmp_gt_f32_e32 vcc, s33, v2
	v_add_f32_e32 v0, v1, v0
	ds_write_b32 v95, v0
	v_cndmask_b32_e64 v3, 0, 32, vcc
	v_ldexp_f32 v2, v2, v3
	s_waitcnt vmcnt(3)
	v_lshlrev_b32_e32 v3, 16, v6
	v_mul_f32_e32 v3, 0xbfb8aa3b, v3
	v_log_f32_e32 v2, v2
	v_exp_f32_e32 v3, v3
	v_readlane_b32 s82, v252, 26
	v_readlane_b32 s83, v252, 27
	v_mul_f32_e32 v1, 0x3f317217, v2
	v_add_f32_e32 v3, 1.0, v3
	v_fma_f32 v1, v2, s13, -v1
	v_rcp_f32_e32 v3, v3
	v_fmac_f32_e32 v1, 0x3377d1cf, v2
	v_fmac_f32_e32 v1, 0x3f317217, v2
	v_cmp_lt_f32_e64 s[0:1], |v2|, s14
	v_readlane_b32 s84, v252, 28
	v_readlane_b32 s85, v252, 29
	v_cndmask_b32_e64 v1, v2, v1, s[0:1]
	v_cndmask_b32_e32 v2, 0, v185, vcc
	v_sub_f32_e32 v1, v1, v2
	v_fma_f32 v2, v76, v3, v16
	v_cmp_gt_f32_e32 vcc, s33, v2
	v_add_f32_e32 v0, v0, v1
	ds_write_b32 v96, v0
	v_cndmask_b32_e64 v3, 0, 32, vcc
	v_ldexp_f32 v2, v2, v3
	s_waitcnt vmcnt(2)
	v_lshlrev_b32_e32 v3, 16, v7
	v_mul_f32_e32 v3, 0xbfb8aa3b, v3
	v_log_f32_e32 v2, v2
	v_exp_f32_e32 v3, v3
	v_readlane_b32 s88, v252, 32
	v_readlane_b32 s89, v252, 33
	v_mul_f32_e32 v1, 0x3f317217, v2
	v_add_f32_e32 v3, 1.0, v3
	v_fma_f32 v1, v2, s13, -v1
	v_rcp_f32_e32 v3, v3
	v_fmac_f32_e32 v1, 0x3377d1cf, v2
	v_fmac_f32_e32 v1, 0x3f317217, v2
	v_cmp_lt_f32_e64 s[0:1], |v2|, s14
	v_readlane_b32 s90, v252, 34
	v_readlane_b32 s91, v252, 35
	v_cndmask_b32_e64 v1, v2, v1, s[0:1]
	v_cndmask_b32_e32 v2, 0, v185, vcc
	v_sub_f32_e32 v1, v1, v2
	v_fma_f32 v2, v76, v3, v16
	v_cmp_gt_f32_e32 vcc, s33, v2
	v_add_f32_e32 v0, v0, v1
	ds_write_b32 v105, v0
	v_cndmask_b32_e64 v3, 0, 32, vcc
	v_ldexp_f32 v2, v2, v3
	s_waitcnt vmcnt(1)
	v_lshlrev_b32_e32 v3, 16, v15
	v_mul_f32_e32 v3, 0xbfb8aa3b, v3
	v_log_f32_e32 v2, v2
	v_exp_f32_e32 v3, v3
	v_mul_f32_e32 v1, 0x3f317217, v2
	v_add_f32_e32 v3, 1.0, v3
	v_fma_f32 v1, v2, s13, -v1
	v_rcp_f32_e32 v3, v3
	v_fmac_f32_e32 v1, 0x3377d1cf, v2
	v_fmac_f32_e32 v1, 0x3f317217, v2
	v_cmp_lt_f32_e64 s[0:1], |v2|, s14
	s_nop 1
	v_cndmask_b32_e64 v1, v2, v1, s[0:1]
	v_cndmask_b32_e32 v2, 0, v185, vcc
	v_sub_f32_e32 v1, v1, v2
	v_fma_f32 v2, v76, v3, v16
	v_cmp_gt_f32_e32 vcc, s33, v2
	s_nop 1
	v_cndmask_b32_e64 v3, 0, 32, vcc
	v_ldexp_f32 v2, v2, v3
	v_log_f32_e32 v2, v2
	v_add_f32_e32 v3, v0, v1
	s_waitcnt vmcnt(0)
; __device__ __forceinline__ float logsig(float x) { return fminf(x, 0.f) - __logf(1.0f + __expf(-fabsf(x))); }
; template <int TY> __device__ __forceinline__ void ma_even_item(const Params& p, ldsp lds, int item) {
;     ...
; #pragma unroll
;     for (int i = 0; i < SEGL; ++i) { const int s = sg * SEGL + i; float g;
;         if (TY == 0) { float x = bias;
; #pragma unroll
;             for (int r = 0; r < 16; ++r) x += LRs[s * 16 + r] * w2[r];
;             g = logsig(x) * 0.0625f;
;         } else { const float x = bf2f(Pb[(size_t)s * NE + E_FB + h * 128 + d]); const float sig = __builtin_amdgcn_rcpf(1.0f + __expf(-x)); g = __logf(lbv + (1.0f - lbv) * sig); }
;         run += g; Bl[s * DK + d] = run; }
	v_lshlrev_b32_e32 v1, 16, v20
	v_mul_f32_e32 v1, 0xbfb8aa3b, v1
	v_mul_f32_e32 v0, 0x3f317217, v2
	v_fma_f32 v0, v2, s13, -v0
	v_exp_f32_e32 v1, v1
	v_fmac_f32_e32 v0, 0x3377d1cf, v2
	v_fmac_f32_e32 v0, 0x3f317217, v2
	v_cmp_lt_f32_e64 s[0:1], |v2|, s14
	ds_write_b32 v107, v3
	s_nop 0
	v_cndmask_b32_e64 v0, v2, v0, s[0:1]
	v_cndmask_b32_e32 v2, 0, v185, vcc
	v_sub_f32_e32 v2, v0, v2
	v_add_f32_e32 v0, 1.0, v1
	v_rcp_f32_e32 v4, v0
	v_mad_i64_i32 v[0:1], s[0:1], v77, s55, v[44:45]
	v_lshl_add_u64 v[0:1], v[0:1], 0, s[40:41]
	v_lshl_add_u64 v[68:69], v[0:1], 0, v[46:47]
	v_add_co_u32_e32 v66, vcc, s57, v68
	v_fma_f32 v0, v76, v4, v16
	s_nop 0
	v_addc_co_u32_e32 v67, vcc, 0, v69, vcc
	global_load_ushort v97, v[66:67], off
	v_cmp_gt_f32_e32 vcc, s33, v0
	v_add_f32_e32 v99, v3, v2
	ds_write_b32 v108, v99
	v_cndmask_b32_e64 v1, 0, 32, vcc
	v_ldexp_f32 v0, v0, v1
	v_log_f32_e32 v98, v0
	v_mad_i64_i32 v[0:1], s[0:1], v91, s55, v[44:45]
	v_lshl_add_u64 v[0:1], v[0:1], 0, s[40:41]
	v_lshl_add_u64 v[36:37], v[0:1], 0, v[46:47]
	v_add_co_u32_e64 v38, s[0:1], s57, v36
	v_mul_f32_e32 v100, 0x3f317217, v98
	s_nop 0
	v_addc_co_u32_e64 v39, s[0:1], 0, v37, s[0:1]
	global_load_ushort v101, v[38:39], off
	v_mad_i64_i32 v[0:1], s[0:1], v90, s55, v[44:45]
	v_lshl_add_u64 v[0:1], v[0:1], 0, s[40:41]
	v_lshl_add_u64 v[32:33], v[0:1], 0, v[46:47]
	v_add_co_u32_e64 v34, s[0:1], s57, v32
	v_fma_f32 v100, v98, s13, -v100
	s_nop 0
	v_addc_co_u32_e64 v35, s[0:1], 0, v33, s[0:1]
	v_mad_i64_i32 v[0:1], s[0:1], v89, s55, v[44:45]
	v_lshl_add_u64 v[0:1], v[0:1], 0, s[40:41]
	v_lshl_add_u64 v[26:27], v[0:1], 0, v[46:47]
	v_add_co_u32_e64 v28, s[0:1], s57, v26
	v_fmac_f32_e32 v100, 0x3377d1cf, v98
	s_nop 0
	v_addc_co_u32_e64 v29, s[0:1], 0, v27, s[0:1]
	global_load_ushort v102, v[34:35], off
	global_load_ushort v103, v[28:29], off
	v_mad_i64_i32 v[0:1], s[0:1], v88, s55, v[44:45]
	v_lshl_add_u64 v[0:1], v[0:1], 0, s[40:41]
	v_lshl_add_u64 v[20:21], v[0:1], 0, v[46:47]
	v_add_co_u32_e64 v22, s[0:1], s57, v20
	v_fmac_f32_e32 v100, 0x3f317217, v98
	s_nop 0
	v_addc_co_u32_e64 v23, s[0:1], 0, v21, s[0:1]
	v_mad_i64_i32 v[0:1], s[0:1], v85, s55, v[44:45]
	v_lshl_add_u64 v[0:1], v[0:1], 0, s[40:41]
	v_lshl_add_u64 v[14:15], v[0:1], 0, v[46:47]
	v_add_co_u32_e64 v12, s[0:1], s57, v14
	s_waitcnt vmcnt(3)
	v_lshlrev_b32_e32 v97, 16, v97
	v_addc_co_u32_e64 v13, s[0:1], 0, v15, s[0:1]
	v_mad_i64_i32 v[0:1], s[0:1], v78, s55, v[44:45]
	v_lshl_add_u64 v[0:1], v[0:1], 0, s[40:41]
	v_lshl_add_u64 v[6:7], v[0:1], 0, v[46:47]
	v_add_co_u32_e64 v4, s[0:1], s57, v6
	v_mul_f32_e32 v97, 0xbfb8aa3b, v97
	s_nop 0
	v_addc_co_u32_e64 v5, s[0:1], 0, v7, s[0:1]
	v_mad_i64_i32 v[0:1], s[0:1], v80, s55, v[44:45]
	v_lshl_add_u64 v[0:1], v[0:1], 0, s[40:41]
	v_lshl_add_u64 v[0:1], v[0:1], 0, v[46:47]
	v_add_co_u32_e64 v2, s[0:1], s57, v0
	v_exp_f32_e32 v97, v97
	s_nop 0
	v_addc_co_u32_e64 v3, s[0:1], 0, v1, s[0:1]
	global_load_ushort v44, v[22:23], off
	global_load_ushort v45, v[12:13], off
	global_load_ushort v46, v[4:5], off
	global_load_ushort v47, v[2:3], off
	v_add_f32_e32 v97, 1.0, v97
	v_rcp_f32_e32 v97, v97
	v_cmp_lt_f32_e64 s[0:1], |v98|, s14
	v_fma_f32 v97, v76, v97, v16
	s_nop 0
	v_cndmask_b32_e64 v98, v98, v100, s[0:1]
	v_cndmask_b32_e32 v100, 0, v185, vcc
	v_cmp_gt_f32_e32 vcc, s33, v97
	v_sub_f32_e32 v98, v98, v100
	v_add_f32_e32 v98, v99, v98
	v_cndmask_b32_e64 v100, 0, 32, vcc
	v_ldexp_f32 v97, v97, v100
	s_waitcnt vmcnt(6)
	v_lshlrev_b32_e32 v100, 16, v101
	v_mul_f32_e32 v100, 0xbfb8aa3b, v100
	v_log_f32_e32 v97, v97
	v_exp_f32_e32 v100, v100
	s_waitcnt vmcnt(5)
	v_lshlrev_b32_e32 v101, 16, v102
	v_mul_f32_e32 v101, 0xbfb8aa3b, v101
	v_mul_f32_e32 v99, 0x3f317217, v97
	v_add_f32_e32 v100, 1.0, v100
	v_fma_f32 v99, v97, s13, -v99
	v_rcp_f32_e32 v100, v100
	v_fmac_f32_e32 v99, 0x3377d1cf, v97
	v_fmac_f32_e32 v99, 0x3f317217, v97
	v_cmp_lt_f32_e64 s[0:1], |v97|, s14
	v_exp_f32_e32 v101, v101
	s_waitcnt vmcnt(4)
	v_lshlrev_b32_e32 v102, 16, v103
	v_cndmask_b32_e64 v97, v97, v99, s[0:1]
	v_cndmask_b32_e32 v99, 0, v185, vcc
	v_sub_f32_e32 v97, v97, v99
	v_fma_f32 v99, v76, v100, v16
	v_cmp_gt_f32_e32 vcc, s33, v99
	v_add_f32_e32 v101, 1.0, v101
	v_rcp_f32_e32 v101, v101
	v_cndmask_b32_e64 v100, 0, 32, vcc
	v_ldexp_f32 v99, v99, v100
	v_log_f32_e32 v99, v99
	v_mul_f32_e32 v102, 0xbfb8aa3b, v102
	v_exp_f32_e32 v102, v102
	ds_write_b32 v109, v98
	v_mul_f32_e32 v100, 0x3f317217, v99
	v_fma_f32 v100, v99, s13, -v100
	v_fmac_f32_e32 v100, 0x3377d1cf, v99
	v_fmac_f32_e32 v100, 0x3f317217, v99
	v_cmp_lt_f32_e64 s[0:1], |v99|, s14
	v_add_f32_e32 v102, 1.0, v102
	v_rcp_f32_e32 v102, v102
	v_cndmask_b32_e64 v99, v99, v100, s[0:1]
	v_cndmask_b32_e32 v100, 0, v185, vcc
	v_sub_f32_e32 v99, v99, v100
	v_fma_f32 v100, v76, v101, v16
	v_cmp_gt_f32_e32 vcc, s33, v100
	v_add_f32_e32 v98, v98, v97
	v_lshl_add_u32 v97, v77, 9, v65
	v_cndmask_b32_e64 v101, 0, 32, vcc
	v_ldexp_f32 v100, v100, v101
	v_log_f32_e32 v100, v100
	ds_write_b32 v97, v98
	v_add_f32_e32 v99, v98, v99
	v_lshl_add_u32 v98, v91, 9, v65
	v_mul_f32_e32 v101, 0x3f317217, v100
	v_fma_f32 v101, v100, s13, -v101
	v_fmac_f32_e32 v101, 0x3377d1cf, v100
	v_fmac_f32_e32 v101, 0x3f317217, v100
	v_cmp_lt_f32_e64 s[0:1], |v100|, s14
	ds_write_b32 v98, v99
	v_lshl_add_u32 v103, v78, 9, v65
	v_cndmask_b32_e64 v100, v100, v101, s[0:1]
	v_cndmask_b32_e32 v101, 0, v185, vcc
	v_sub_f32_e32 v100, v100, v101
	v_fma_f32 v101, v76, v102, v16
	v_cmp_gt_f32_e32 vcc, s33, v101
	v_add_f32_e32 v100, v99, v100
	v_lshl_add_u32 v99, v90, 9, v65
	v_cndmask_b32_e64 v102, 0, 32, vcc
	s_waitcnt vmcnt(3)
; __device__ __forceinline__ float logsig(float x) { return fminf(x, 0.f) - __logf(1.0f + __expf(-fabsf(x))); }
; #define BSYNC() do { asm volatile("s_waitcnt vmcnt(0) lgkmcnt(0)" ::: "memory"); __syncthreads(); } while (0)
; template <int TY> __device__ __forceinline__ void ma_even_item(const Params& p, ldsp lds, int item) {
;     ...
; #pragma unroll
;     for (int i = 0; i < SEGL; ++i) { const int s = sg * SEGL + i; float g;
;         if (TY == 0) { float x = bias;
; #pragma unroll
;             for (int r = 0; r < 16; ++r) x += LRs[s * 16 + r] * w2[r];
;             g = logsig(x) * 0.0625f;
;         } else { const float x = bf2f(Pb[(size_t)s * NE + E_FB + h * 128 + d]); const float sig = __builtin_amdgcn_rcpf(1.0f + __expf(-x)); g = __logf(lbv + (1.0f - lbv) * sig); }
;         run += g; Bl[s * DK + d] = run; }
;     SEG[sg * 128 + d] = run;
;     BSYNC();
;     float off = 0.f, tot = 0.f;
; #pragma unroll
;     for (int s2 = 0; s2 < NSEG; ++s2) { const float v = SEG[s2 * 128 + d]; if (s2 < sg) off += v; tot += v; }
; #pragma unroll
;     for (int i = 0; i < SEGL; ++i) Bl[(sg * SEGL + i) * DK + d] += off;
;     BSYNC();
	v_lshlrev_b32_e32 v44, 16, v44
	v_mul_f32_e32 v44, 0xbfb8aa3b, v44
	v_exp_f32_e32 v44, v44
	v_ldexp_f32 v101, v101, v102
	v_log_f32_e32 v101, v101
	s_waitcnt vmcnt(2)
	v_lshlrev_b32_e32 v45, 16, v45
	v_add_f32_e32 v44, 1.0, v44
	v_rcp_f32_e32 v44, v44
	v_mul_f32_e32 v102, 0x3f317217, v101
	v_fma_f32 v102, v101, s13, -v102
	v_fmac_f32_e32 v102, 0x3377d1cf, v101
	v_fmac_f32_e32 v102, 0x3f317217, v101
	v_cmp_lt_f32_e64 s[0:1], |v101|, s14
	v_fma_f32 v44, v76, v44, v16
	v_mul_f32_e32 v45, 0xbfb8aa3b, v45
	v_cndmask_b32_e64 v101, v101, v102, s[0:1]
	v_cndmask_b32_e32 v102, 0, v185, vcc
	v_cmp_gt_f32_e32 vcc, s33, v44
	v_sub_f32_e32 v101, v101, v102
	v_exp_f32_e32 v45, v45
	v_cndmask_b32_e64 v102, 0, 32, vcc
	v_ldexp_f32 v44, v44, v102
	v_log_f32_e32 v44, v44
	v_add_f32_e32 v45, 1.0, v45
	v_rcp_f32_e32 v45, v45
	s_waitcnt vmcnt(1)
	v_lshlrev_b32_e32 v46, 16, v46
	v_mul_f32_e32 v102, 0x3f317217, v44
	v_fma_f32 v102, v44, s13, -v102
	v_fmac_f32_e32 v102, 0x3377d1cf, v44
	v_fmac_f32_e32 v102, 0x3f317217, v44
	v_cmp_lt_f32_e64 s[0:1], |v44|, s14
	v_fma_f32 v45, v76, v45, v16
	v_mul_f32_e32 v46, 0xbfb8aa3b, v46
	v_cndmask_b32_e64 v44, v44, v102, s[0:1]
	v_cndmask_b32_e32 v102, 0, v185, vcc
	v_cmp_gt_f32_e32 vcc, s33, v45
	v_sub_f32_e32 v44, v44, v102
	v_exp_f32_e32 v46, v46
	v_cndmask_b32_e64 v102, 0, 32, vcc
	v_ldexp_f32 v45, v45, v102
	v_log_f32_e32 v45, v45
	v_add_f32_e32 v46, 1.0, v46
	v_rcp_f32_e32 v46, v46
	s_waitcnt vmcnt(0)
	v_lshlrev_b32_e32 v47, 16, v47
	v_mul_f32_e32 v102, 0x3f317217, v45
	v_fma_f32 v102, v45, s13, -v102
	v_fmac_f32_e32 v102, 0x3377d1cf, v45
	v_fmac_f32_e32 v102, 0x3f317217, v45
	v_cmp_lt_f32_e64 s[0:1], |v45|, s14
	v_fma_f32 v46, v76, v46, v16
	v_mul_f32_e32 v47, 0xbfb8aa3b, v47
	v_cndmask_b32_e64 v45, v45, v102, s[0:1]
	v_cndmask_b32_e32 v102, 0, v185, vcc
	v_cmp_gt_f32_e32 vcc, s33, v46
	v_sub_f32_e32 v45, v45, v102
	v_exp_f32_e32 v47, v47
	v_cndmask_b32_e64 v102, 0, 32, vcc
	v_ldexp_f32 v46, v46, v102
	v_log_f32_e32 v46, v46
	ds_write_b32 v99, v100
	v_add_f32_e32 v101, v100, v101
	v_lshl_add_u32 v100, v89, 9, v65
	v_add_f32_e32 v47, 1.0, v47
	ds_write_b32 v100, v101
	v_add_f32_e32 v44, v101, v44
	v_lshl_add_u32 v101, v88, 9, v65
	v_rcp_f32_e32 v47, v47
	ds_write_b32 v101, v44
	v_add_f32_e32 v44, v44, v45
	v_mul_f32_e32 v45, 0x3f317217, v46
	v_fma_f32 v45, v46, s13, -v45
	v_fmac_f32_e32 v45, 0x3377d1cf, v46
	v_fmac_f32_e32 v45, 0x3f317217, v46
	v_cmp_lt_f32_e64 s[0:1], |v46|, s14
	v_fmac_f32_e32 v16, v76, v47
	v_lshl_add_u32 v102, v85, 9, v65
	v_cndmask_b32_e64 v45, v46, v45, s[0:1]
	v_cndmask_b32_e32 v46, 0, v185, vcc
	v_cmp_gt_f32_e32 vcc, s33, v16
	v_sub_f32_e32 v45, v45, v46
	ds_write_b32 v102, v44
	v_cndmask_b32_e64 v46, 0, 32, vcc
	v_ldexp_f32 v16, v16, v46
	v_log_f32_e32 v16, v16
	v_add_f32_e32 v44, v44, v45
	ds_write_b32 v103, v44
	v_mul_f32_e32 v45, 0x3f317217, v16
	v_fma_f32 v45, v16, s13, -v45
	v_fmac_f32_e32 v45, 0x3377d1cf, v16
	v_fmac_f32_e32 v45, 0x3f317217, v16
	v_cmp_lt_f32_e64 s[0:1], |v16|, s14
	s_movk_i32 s13, 0x300
	s_nop 0
	v_cndmask_b32_e64 v16, v16, v45, s[0:1]
	v_cndmask_b32_e32 v45, 0, v185, vcc
	v_sub_f32_e32 v16, v16, v45
	v_add_f32_e32 v16, v44, v16
	v_lshl_add_u32 v44, v74, 2, 0
	ds_write_b32 v104, v16
	ds_write_b32 v44, v16 offset:32768
	s_waitcnt vmcnt(0) lgkmcnt(0)
	s_waitcnt lgkmcnt(0)
	s_barrier
	ds_read2st64_b32 v[44:45], v65 offset0:128 offset1:130
	ds_read2st64_b32 v[46:47], v65 offset0:132 offset1:134
	s_movk_i32 s0, 0x7f
	v_cmp_lt_i32_e32 vcc, s0, v74
	s_movk_i32 s0, 0xff
	s_waitcnt lgkmcnt(1)
	v_add_f32_e32 v44, 0, v44
	v_cndmask_b32_e32 v16, 0, v44, vcc
	v_add_f32_e32 v110, v45, v16
	v_cmp_lt_i32_e32 vcc, s0, v74
	s_movk_i32 s0, 0x17f
	ds_read2st64_b32 v[112:113], v92 offset0:4 offset1:6
	v_cndmask_b32_e32 v16, v16, v110, vcc
	s_waitcnt lgkmcnt(1)
	v_add_f32_e32 v110, v46, v16
	v_cmp_lt_i32_e32 vcc, s0, v74
	s_nop 1
	v_cndmask_b32_e32 v16, v16, v110, vcc
	ds_read2st64_b32 v[110:111], v92 offset1:2
	v_add_f32_e32 v106, v47, v16
	v_cmp_lt_i32_e32 vcc, s60, v74
	s_nop 1
	v_cndmask_b32_e32 v16, v16, v106, vcc
	s_waitcnt lgkmcnt(0)
	v_add_f32_e32 v106, v110, v16
	v_add_f32_e32 v110, v111, v16
	ds_write2st64_b32 v92, v106, v110 offset1:2
	ds_read2st64_b32 v[110:111], v92 offset0:8 offset1:10
	v_add_f32_e32 v106, v16, v112
	v_add_f32_e32 v112, v16, v113
	ds_write2st64_b32 v92, v106, v112 offset0:4 offset1:6
	ds_read2st64_b32 v[112:113], v92 offset0:12 offset1:14
	s_waitcnt lgkmcnt(2)
	v_add_f32_e32 v106, v16, v110
	v_add_f32_e32 v110, v16, v111
	ds_write2st64_b32 v92, v106, v110 offset0:8 offset1:10
	ds_read2st64_b32 v[110:111], v92 offset0:16 offset1:18
	s_waitcnt lgkmcnt(2)
	v_add_f32_e32 v106, v16, v112
	v_add_f32_e32 v112, v16, v113
	ds_write2st64_b32 v92, v106, v112 offset0:12 offset1:14
	ds_read2st64_b32 v[112:113], v92 offset0:20 offset1:22
	s_waitcnt lgkmcnt(2)
	v_add_f32_e32 v106, v16, v110
	v_add_f32_e32 v110, v16, v111
	ds_write2st64_b32 v92, v106, v110 offset0:16 offset1:18
	ds_read2st64_b32 v[110:111], v92 offset0:24 offset1:26
	s_waitcnt lgkmcnt(2)
	v_add_f32_e32 v106, v16, v112
	v_add_f32_e32 v114, v16, v113
	ds_read2st64_b32 v[112:113], v92 offset0:28 offset1:30
	ds_write2st64_b32 v92, v106, v114 offset0:20 offset1:22
	s_waitcnt lgkmcnt(2)
	v_add_f32_e32 v106, v16, v110
	v_add_f32_e32 v110, v16, v111
	ds_write2st64_b32 v92, v106, v110 offset0:24 offset1:26
	s_waitcnt lgkmcnt(2)
	v_add_f32_e32 v106, v16, v112
	v_add_f32_e32 v16, v16, v113
	ds_write2st64_b32 v92, v106, v16 offset0:28 offset1:30
	s_waitcnt vmcnt(0) lgkmcnt(0)
	s_waitcnt lgkmcnt(0)
	s_barrier
; #define LAS __attribute__((address_space(3)))
; __device__ __forceinline__ unsigned f2bf(float f) { unsigned u = __builtin_bit_cast(unsigned, f); return (u + 0x7fffu + ((u >> 16) & 1u)) >> 16; }
; __device__ __forceinline__ float siluf(float x) { return x * __builtin_amdgcn_rcpf(1.0f + __expf(-x)); }
; template <int TY> __device__ __forceinline__ void ma_even_item(const Params& p, ldsp lds, int item) {
;     ...
;     const float bmid = Bl[31 * DK + d], blast = tot;
;     bf16_t* QT = (bf16_t*)(p.ws + WS_QT); bf16_t* QH = (bf16_t*)(p.ws + WS_QH); bf16_t* KT = (bf16_t*)(p.ws + WS_KT);
;     const int col = TY ? 256 + h * 128 + d : h * 64 + d;
; #pragma unroll
;     for (int i = 0; i < SEGL; ++i) { const int s = sg * SEGL + i; const float bs = Bl[s * DK + d]; float qv, kv;
;         if (TY == 0) { qv = bf2f(Pb[(size_t)s * NE + E_QA + h * 64 + d]) * 0.125f; kv = bf2f(Pb[(size_t)s * NE + E_KA + h * 64 + d]); }
;         else { qv = siluf(bf2f(Pb[(size_t)s * NE + E_QB + h * 128 + d])); const float xf = bf2f(Pb[(size_t)s * NE + E_FB + h * 128 + d]); kv = (1.0f - lbv) * __builtin_amdgcn_rcpf(1.0f + __expf(xf)); }
;         const size_t g = (size_t)(row0 + s) * 768 + col;
;         QT[g] = (bf16_t)f2bf(qv * __expf(fminf(bs - bmid, 80.f))); QH[g] = (bf16_t)f2bf(qv * __expf(bs)); KT[g] = (bf16_t)f2bf(kv * __expf(fminf(bmid - bs, 80.f)));
;         *(LAS bf16_t*)(KHT + (size_t)(d * 72 + s) * 2) = (bf16_t)f2bf(kv * __expf(blast - bs)); }
	global_load_ushort v186, v[72:73], off offset:3072
	global_load_ushort v187, v[70:71], off
	global_load_ushort v188, v[60:61], off offset:3072
	global_load_ushort v189, v[62:63], off
	global_load_ushort v190, v[56:57], off offset:3072
	global_load_ushort v191, v[58:59], off
	global_load_ushort v192, v[52:53], off offset:3072
	global_load_ushort v193, v[54:55], off
	global_load_ushort v194, v[48:49], off offset:3072
	global_load_ushort v195, v[50:51], off
	global_load_ushort v196, v[40:41], off offset:3072
	global_load_ushort v197, v[42:43], off
	global_load_ushort v198, v[24:25], off offset:3072
	global_load_ushort v199, v[30:31], off
	global_load_ushort v200, v[10:11], off offset:3072
	global_load_ushort v201, v[18:19], off
	global_load_ushort v202, v[68:69], off offset:3072
	global_load_ushort v203, v[66:67], off
	global_load_ushort v204, v[36:37], off offset:3072
	global_load_ushort v205, v[38:39], off
	global_load_ushort v206, v[32:33], off offset:3072
	global_load_ushort v207, v[34:35], off
	global_load_ushort v208, v[26:27], off offset:3072
	global_load_ushort v209, v[28:29], off
	global_load_ushort v210, v[20:21], off offset:3072
	global_load_ushort v211, v[22:23], off
	global_load_ushort v212, v[14:15], off offset:3072
	global_load_ushort v213, v[12:13], off
	global_load_ushort v214, v[6:7], off offset:3072
	global_load_ushort v215, v[4:5], off
	global_load_ushort v216, v[0:1], off offset:3072
	global_load_ushort v217, v[2:3], off
	s_nop 0
	s_waitcnt vmcnt(0)
	v_lshlrev_b32_e32 v71, 16, v186
	v_mul_f32_e32 v16, 0xbfb8aa3b, v71
	v_exp_f32_e32 v16, v16
	s_nop 0
	v_add_f32_e32 v16, 1.0, v16
	v_rcp_f32_e32 v72, v16
	v_lshlrev_b32_e32 v16, 16, v187
	v_mul_f32_e32 v16, 0x3fb8aa3b, v16
	v_exp_f32_e32 v73, v16
	ds_read_b32 v70, v65 offset:15872
	v_add_u32_e32 v16, 0x100, v64
	v_mul_f32_e32 v110, v72, v71
	v_add_f32_e32 v64, 1.0, v73
	v_rcp_f32_e32 v111, v64
	ds_read_b32 v71, v93
	ds_read_b32 v72, v94
	ds_read_b32 v73, v95
	ds_read_b32 v92, v96
	ds_read_b32 v93, v105
	ds_read_b32 v94, v107
	ds_read_b32 v95, v108
	ds_read_b32 v96, v109
	s_waitcnt lgkmcnt(7)
	v_sub_f32_e32 v64, v71, v70
	v_min_f32_e32 v64, 0x42a00000, v64
	v_mul_f32_e32 v64, 0x3fb8aa3b, v64
	v_exp_f32_e32 v105, v64
	v_add_u32_e32 v64, s9, v75
	v_mad_i64_i32 v[64:65], s[0:1], v64, s13, v[16:17]
	v_mul_f32_e32 v105, v105, v110
	v_bfe_u32 v106, v105, 16, 1
	v_add3_u32 v105, v105, v106, s52
	v_mul_f32_e32 v106, 0x3fb8aa3b, v71
	v_exp_f32_e32 v108, v106
	v_lshlrev_b64 v[64:65], 1, v[64:65]
	v_lshl_add_u64 v[106:107], s[28:29], 0, v[64:65]
	global_store_short_d16_hi v[106:107], v105, off
	v_mul_f32_e32 v105, v108, v110
	v_sub_f32_e32 v108, v70, v71
	v_min_f32_e32 v108, 0x42a00000, v108
	v_mul_f32_e32 v108, 0x3fb8aa3b, v108
	v_exp_f32_e32 v108, v108
	v_bfe_u32 v106, v105, 16, 1
	v_add3_u32 v105, v105, v106, s52
	v_lshl_add_u64 v[106:107], s[22:23], 0, v[64:65]
	global_store_short_d16_hi v[106:107], v105, off
	v_lshl_add_u64 v[106:107], s[72:73], 0, v[64:65]
	v_mul_f32_e32 v64, v76, v111
	v_mul_f32_e32 v65, v108, v64
	v_bfe_u32 v105, v65, 16, 1
	v_add3_u32 v65, v65, v105, s52
	global_store_short_d16_hi v[106:107], v65, off
	s_nop 0
	s_waitcnt lgkmcnt(6)
	v_sub_f32_e32 v62, v72, v70
	v_min_f32_e32 v62, 0x42a00000, v62
	v_mul_f32_e32 v62, 0x3fb8aa3b, v62
	v_add_u32_e32 v60, s9, v87
	v_exp_f32_e32 v87, v62
	v_mul_f32_e32 v106, 0x3fb8aa3b, v72
	v_exp_f32_e32 v108, v106
	v_sub_f32_e32 v109, v70, v72
	v_mad_i64_i32 v[60:61], s[0:1], v60, s13, v[16:17]
	v_min_f32_e32 v109, 0x42a00000, v109
	v_lshlrev_b64 v[60:61], 1, v[60:61]
	v_mul_f32_e32 v109, 0x3fb8aa3b, v109
	v_lshl_add_u64 v[62:63], s[28:29], 0, v[60:61]
	v_exp_f32_e32 v109, v109
	v_lshl_add_u64 v[106:107], s[22:23], 0, v[60:61]
	v_lshl_add_u64 v[60:61], s[72:73], 0, v[60:61]
	v_lshlrev_b32_e32 v65, 16, v188
	v_mul_f32_e32 v110, 0xbfb8aa3b, v65
	v_exp_f32_e32 v110, v110
	v_lshlrev_b32_e32 v105, 16, v189
	v_mul_f32_e32 v105, 0x3fb8aa3b, v105
	v_exp_f32_e32 v105, v105
	v_add_f32_e32 v110, 1.0, v110
	v_rcp_f32_e32 v110, v110
	v_add_f32_e32 v105, 1.0, v105
	v_rcp_f32_e32 v105, v105
	v_mul_f32_e32 v110, v110, v65
	v_mul_f32_e32 v87, v87, v110
	v_mul_f32_e32 v65, v76, v105
	v_bfe_u32 v105, v87, 16, 1
	v_add3_u32 v87, v87, v105, s52
	global_store_short_d16_hi v[62:63], v87, off
	v_mul_f32_e32 v62, v108, v110
	v_bfe_u32 v63, v62, 16, 1
	v_add3_u32 v62, v62, v63, s52
	global_store_short_d16_hi v[106:107], v62, off
	v_mul_f32_e32 v62, v109, v65
	v_bfe_u32 v63, v62, 16, 1
	v_add3_u32 v62, v62, v63, s52
	global_store_short_d16_hi v[60:61], v62, off
	s_nop 0
	s_waitcnt lgkmcnt(5)
	v_sub_f32_e32 v58, v73, v70
	v_min_f32_e32 v58, 0x42a00000, v58
	v_mul_f32_e32 v58, 0x3fb8aa3b, v58
	v_add_u32_e32 v56, s9, v86
	v_exp_f32_e32 v86, v58
	v_mad_i64_i32 v[56:57], s[0:1], v56, s13, v[16:17]
	v_mul_f32_e32 v60, 0x3fb8aa3b, v73
	v_lshlrev_b64 v[56:57], 1, v[56:57]
	v_exp_f32_e32 v87, v60
	v_sub_f32_e32 v105, v70, v73
	v_lshl_add_u64 v[58:59], s[28:29], 0, v[56:57]
	v_lshl_add_u64 v[60:61], s[22:23], 0, v[56:57]
	v_min_f32_e32 v105, 0x42a00000, v105
	v_mul_f32_e32 v105, 0x3fb8aa3b, v105
	v_exp_f32_e32 v105, v105
	v_lshlrev_b32_e32 v106, 16, v190
	v_mul_f32_e32 v62, 0xbfb8aa3b, v106
	v_exp_f32_e32 v62, v62
	v_lshlrev_b32_e32 v63, 16, v191
	v_mul_f32_e32 v63, 0x3fb8aa3b, v63
	v_exp_f32_e32 v63, v63
	v_add_f32_e32 v62, 1.0, v62
	v_rcp_f32_e32 v107, v62
	v_add_f32_e32 v62, 1.0, v63
	v_rcp_f32_e32 v108, v62
	v_lshl_add_u64 v[62:63], s[72:73], 0, v[56:57]
	v_mul_f32_e32 v57, v107, v106
	v_mul_f32_e32 v86, v86, v57
	v_bfe_u32 v106, v86, 16, 1
	v_add3_u32 v86, v86, v106, s52
	v_mul_f32_e32 v57, v87, v57
	global_store_short_d16_hi v[58:59], v86, off
	v_bfe_u32 v58, v57, 16, 1
	v_mul_f32_e32 v56, v76, v108
	v_add3_u32 v57, v57, v58, s52
	global_store_short_d16_hi v[60:61], v57, off
	v_mul_f32_e32 v57, v105, v56
	v_bfe_u32 v58, v57, 16, 1
	v_add3_u32 v57, v57, v58, s52
	global_store_short_d16_hi v[62:63], v57, off
	s_nop 0
	v_add_u32_e32 v52, s9, v84
	s_waitcnt lgkmcnt(4)
; #define LAS __attribute__((address_space(3)))
; __device__ __forceinline__ unsigned f2bf(float f) { unsigned u = __builtin_bit_cast(unsigned, f); return (u + 0x7fffu + ((u >> 16) & 1u)) >> 16; }
; __device__ __forceinline__ float siluf(float x) { return x * __builtin_amdgcn_rcpf(1.0f + __expf(-x)); }
; template <int TY> __device__ __forceinline__ void ma_even_item(const Params& p, ldsp lds, int item) {
;     ...
;     for (int i = 0; i < SEGL; ++i) { const int s = sg * SEGL + i; const float bs = Bl[s * DK + d]; float qv, kv;
;         if (TY == 0) { qv = bf2f(Pb[(size_t)s * NE + E_QA + h * 64 + d]) * 0.125f; kv = bf2f(Pb[(size_t)s * NE + E_KA + h * 64 + d]); }
;         else { qv = siluf(bf2f(Pb[(size_t)s * NE + E_QB + h * 128 + d])); const float xf = bf2f(Pb[(size_t)s * NE + E_FB + h * 128 + d]); kv = (1.0f - lbv) * __builtin_amdgcn_rcpf(1.0f + __expf(xf)); }
;         const size_t g = (size_t)(row0 + s) * 768 + col;
;         QT[g] = (bf16_t)f2bf(qv * __expf(fminf(bs - bmid, 80.f))); QH[g] = (bf16_t)f2bf(qv * __expf(bs)); KT[g] = (bf16_t)f2bf(kv * __expf(fminf(bmid - bs, 80.f)));
;         *(LAS bf16_t*)(KHT + (size_t)(d * 72 + s) * 2) = (bf16_t)f2bf(kv * __expf(blast - bs)); }
	v_sub_f32_e32 v54, v92, v70
	v_min_f32_e32 v54, 0x42a00000, v54
	v_mul_f32_e32 v54, 0x3fb8aa3b, v54
	v_exp_f32_e32 v61, v54
	v_mul_f32_e32 v58, 0x3fb8aa3b, v92
	v_exp_f32_e32 v62, v58
	v_sub_f32_e32 v63, v70, v92
	v_mad_i64_i32 v[52:53], s[0:1], v52, s13, v[16:17]
	v_min_f32_e32 v63, 0x42a00000, v63
	v_lshlrev_b64 v[52:53], 1, v[52:53]
	v_mul_f32_e32 v63, 0x3fb8aa3b, v63
	v_lshl_add_u64 v[54:55], s[28:29], 0, v[52:53]
	v_exp_f32_e32 v63, v63
	v_lshl_add_u64 v[58:59], s[22:23], 0, v[52:53]
	v_lshl_add_u64 v[52:53], s[72:73], 0, v[52:53]
	v_lshlrev_b32_e32 v57, 16, v192
	v_mul_f32_e32 v84, 0xbfb8aa3b, v57
	v_lshlrev_b32_e32 v60, 16, v193
	v_exp_f32_e32 v84, v84
	v_mul_f32_e32 v60, 0x3fb8aa3b, v60
	v_exp_f32_e32 v60, v60
	v_add_f32_e32 v84, 1.0, v84
	v_rcp_f32_e32 v84, v84
	v_add_f32_e32 v60, 1.0, v60
	v_rcp_f32_e32 v60, v60
	v_mul_f32_e32 v84, v84, v57
	v_mul_f32_e32 v57, v76, v60
	v_mul_f32_e32 v60, v61, v84
	v_bfe_u32 v61, v60, 16, 1
	v_add3_u32 v60, v60, v61, s52
	global_store_short_d16_hi v[54:55], v60, off
	v_mul_f32_e32 v54, v62, v84
	v_bfe_u32 v55, v54, 16, 1
	v_add3_u32 v54, v54, v55, s52
	global_store_short_d16_hi v[58:59], v54, off
	v_mul_f32_e32 v54, v63, v57
	v_bfe_u32 v55, v54, 16, 1
	v_add3_u32 v54, v54, v55, s52
	global_store_short_d16_hi v[52:53], v54, off
	s_nop 0
	v_lshlrev_b32_e32 v48, 16, v194
	v_mul_f32_e32 v50, 0xbfb8aa3b, v48
	v_exp_f32_e32 v50, v50
	v_lshlrev_b32_e32 v49, 16, v195
	v_mul_f32_e32 v49, 0x3fb8aa3b, v49
	v_exp_f32_e32 v49, v49
	v_add_f32_e32 v50, 1.0, v50
	v_rcp_f32_e32 v50, v50
	s_nop 0
	v_mul_f32_e32 v52, v50, v48
	v_add_f32_e32 v48, 1.0, v49
	v_rcp_f32_e32 v53, v48
	s_waitcnt lgkmcnt(3)
	v_sub_f32_e32 v48, v93, v70
	v_min_f32_e32 v48, 0x42a00000, v48
	v_mul_f32_e32 v48, 0x3fb8aa3b, v48
	v_exp_f32_e32 v50, v48
	v_add_u32_e32 v48, s9, v83
	v_mad_i64_i32 v[48:49], s[0:1], v48, s13, v[16:17]
	v_mul_f32_e32 v50, v50, v52
	v_bfe_u32 v51, v50, 16, 1
	v_add3_u32 v54, v50, v51, s52
	v_mul_f32_e32 v50, 0x3fb8aa3b, v93
	v_lshlrev_b64 v[48:49], 1, v[48:49]
	v_exp_f32_e32 v55, v50
	v_lshl_add_u64 v[50:51], s[28:29], 0, v[48:49]
	global_store_short_d16_hi v[50:51], v54, off
	v_sub_f32_e32 v54, v70, v93
	v_min_f32_e32 v54, 0x42a00000, v54
	v_mul_f32_e32 v54, 0x3fb8aa3b, v54
	v_mul_f32_e32 v50, v55, v52
	v_exp_f32_e32 v54, v54
	v_bfe_u32 v51, v50, 16, 1
	v_add3_u32 v52, v50, v51, s52
	v_lshl_add_u64 v[50:51], s[22:23], 0, v[48:49]
	global_store_short_d16_hi v[50:51], v52, off
	v_lshl_add_u64 v[50:51], s[72:73], 0, v[48:49]
	v_mul_f32_e32 v48, v76, v53
	v_mul_f32_e32 v49, v54, v48
	v_bfe_u32 v52, v49, 16, 1
	v_add3_u32 v49, v49, v52, s52
	global_store_short_d16_hi v[50:51], v49, off
	s_nop 0
	s_waitcnt lgkmcnt(2)
	v_sub_f32_e32 v42, v94, v70
	v_min_f32_e32 v42, 0x42a00000, v42
	v_mul_f32_e32 v42, 0x3fb8aa3b, v42
	v_exp_f32_e32 v53, v42
	v_mul_f32_e32 v50, 0x3fb8aa3b, v94
	v_add_u32_e32 v40, s9, v82
	v_exp_f32_e32 v54, v50
	v_sub_f32_e32 v55, v70, v94
	v_mad_i64_i32 v[40:41], s[0:1], v40, s13, v[16:17]
	v_min_f32_e32 v55, 0x42a00000, v55
	v_lshlrev_b64 v[40:41], 1, v[40:41]
	v_mul_f32_e32 v55, 0x3fb8aa3b, v55
	v_lshl_add_u64 v[42:43], s[28:29], 0, v[40:41]
	v_exp_f32_e32 v55, v55
	v_lshl_add_u64 v[50:51], s[22:23], 0, v[40:41]
	v_lshl_add_u64 v[40:41], s[72:73], 0, v[40:41]
	v_lshlrev_b32_e32 v49, 16, v196
	v_mul_f32_e32 v58, 0xbfb8aa3b, v49
	v_lshlrev_b32_e32 v52, 16, v197
	v_exp_f32_e32 v58, v58
	v_mul_f32_e32 v52, 0x3fb8aa3b, v52
	v_exp_f32_e32 v52, v52
	v_add_f32_e32 v58, 1.0, v58
	v_rcp_f32_e32 v58, v58
	v_add_f32_e32 v52, 1.0, v52
	v_rcp_f32_e32 v52, v52
	v_mul_f32_e32 v58, v58, v49
	v_mul_f32_e32 v49, v76, v52
	v_mul_f32_e32 v52, v53, v58
	v_bfe_u32 v53, v52, 16, 1
	v_add3_u32 v52, v52, v53, s52
	global_store_short_d16_hi v[42:43], v52, off
	v_mul_f32_e32 v42, v54, v58
	v_bfe_u32 v43, v42, 16, 1
	v_add3_u32 v42, v42, v43, s52
	global_store_short_d16_hi v[50:51], v42, off
	v_mul_f32_e32 v42, v55, v49
	v_bfe_u32 v43, v42, 16, 1
	v_add3_u32 v42, v42, v43, s52
	global_store_short_d16_hi v[40:41], v42, off
	s_nop 0
	s_waitcnt lgkmcnt(1)
	v_sub_f32_e32 v30, v95, v70
	v_min_f32_e32 v30, 0x42a00000, v30
	v_mul_f32_e32 v30, 0x3fb8aa3b, v30
	v_add_u32_e32 v24, s9, v81
	v_exp_f32_e32 v50, v30
	v_mad_i64_i32 v[24:25], s[0:1], v24, s13, v[16:17]
	v_mul_f32_e32 v40, 0x3fb8aa3b, v95
	v_lshlrev_b64 v[24:25], 1, v[24:25]
	v_exp_f32_e32 v51, v40
	v_sub_f32_e32 v52, v70, v95
	v_lshl_add_u64 v[30:31], s[28:29], 0, v[24:25]
	v_lshl_add_u64 v[40:41], s[22:23], 0, v[24:25]
	v_min_f32_e32 v52, 0x42a00000, v52
	v_mul_f32_e32 v52, 0x3fb8aa3b, v52
	v_exp_f32_e32 v52, v52
	v_lshlrev_b32_e32 v53, 16, v198
	v_mul_f32_e32 v42, 0xbfb8aa3b, v53
	v_exp_f32_e32 v42, v42
	v_lshlrev_b32_e32 v43, 16, v199
	v_mul_f32_e32 v43, 0x3fb8aa3b, v43
	v_exp_f32_e32 v43, v43
	v_add_f32_e32 v42, 1.0, v42
	v_rcp_f32_e32 v54, v42
	v_add_f32_e32 v42, 1.0, v43
	v_rcp_f32_e32 v55, v42
	v_lshl_add_u64 v[42:43], s[72:73], 0, v[24:25]
	v_mul_f32_e32 v25, v54, v53
	v_mul_f32_e32 v50, v50, v25
	v_bfe_u32 v53, v50, 16, 1
	v_add3_u32 v50, v50, v53, s52
	v_mul_f32_e32 v25, v51, v25
	global_store_short_d16_hi v[30:31], v50, off
	v_bfe_u32 v30, v25, 16, 1
	v_mul_f32_e32 v24, v76, v55
	v_add3_u32 v25, v25, v30, s52
	global_store_short_d16_hi v[40:41], v25, off
	v_mul_f32_e32 v25, v52, v24
	v_bfe_u32 v30, v25, 16, 1
	v_add3_u32 v25, v25, v30, s52
	global_store_short_d16_hi v[42:43], v25, off
	s_nop 0
	s_waitcnt lgkmcnt(0)
; #define LAS __attribute__((address_space(3)))
; __device__ __forceinline__ unsigned f2bf(float f) { unsigned u = __builtin_bit_cast(unsigned, f); return (u + 0x7fffu + ((u >> 16) & 1u)) >> 16; }
; __device__ __forceinline__ float siluf(float x) { return x * __builtin_amdgcn_rcpf(1.0f + __expf(-x)); }
; template <int TY> __device__ __forceinline__ void ma_even_item(const Params& p, ldsp lds, int item) {
;     ...
;     for (int i = 0; i < SEGL; ++i) { const int s = sg * SEGL + i; const float bs = Bl[s * DK + d]; float qv, kv;
;         if (TY == 0) { qv = bf2f(Pb[(size_t)s * NE + E_QA + h * 64 + d]) * 0.125f; kv = bf2f(Pb[(size_t)s * NE + E_KA + h * 64 + d]); }
;         else { qv = siluf(bf2f(Pb[(size_t)s * NE + E_QB + h * 128 + d])); const float xf = bf2f(Pb[(size_t)s * NE + E_FB + h * 128 + d]); kv = (1.0f - lbv) * __builtin_amdgcn_rcpf(1.0f + __expf(xf)); }
;         const size_t g = (size_t)(row0 + s) * 768 + col;
;         QT[g] = (bf16_t)f2bf(qv * __expf(fminf(bs - bmid, 80.f))); QH[g] = (bf16_t)f2bf(qv * __expf(bs)); KT[g] = (bf16_t)f2bf(kv * __expf(fminf(bmid - bs, 80.f)));
;         *(LAS bf16_t*)(KHT + (size_t)(d * 72 + s) * 2) = (bf16_t)f2bf(kv * __expf(blast - bs)); }
	v_sub_f32_e32 v18, v96, v70
	v_min_f32_e32 v18, 0x42a00000, v18
	v_mul_f32_e32 v18, 0x3fb8aa3b, v18
	v_exp_f32_e32 v41, v18
	v_mul_f32_e32 v30, 0x3fb8aa3b, v96
	v_add_u32_e32 v10, s9, v79
	v_exp_f32_e32 v42, v30
	v_sub_f32_e32 v43, v70, v96
	v_mad_i64_i32 v[10:11], s[0:1], v10, s13, v[16:17]
	v_min_f32_e32 v43, 0x42a00000, v43
	v_lshlrev_b64 v[10:11], 1, v[10:11]
	v_mul_f32_e32 v43, 0x3fb8aa3b, v43
	v_lshl_add_u64 v[18:19], s[28:29], 0, v[10:11]
	v_exp_f32_e32 v43, v43
	v_lshl_add_u64 v[30:31], s[22:23], 0, v[10:11]
	v_lshl_add_u64 v[10:11], s[72:73], 0, v[10:11]
	v_lshlrev_b32_e32 v25, 16, v200
	v_mul_f32_e32 v50, 0xbfb8aa3b, v25
	v_lshlrev_b32_e32 v40, 16, v201
	v_exp_f32_e32 v50, v50
	v_mul_f32_e32 v40, 0x3fb8aa3b, v40
	v_exp_f32_e32 v40, v40
	v_add_f32_e32 v50, 1.0, v50
	v_rcp_f32_e32 v50, v50
	v_add_f32_e32 v40, 1.0, v40
	v_rcp_f32_e32 v40, v40
	v_mul_f32_e32 v50, v50, v25
	v_mul_f32_e32 v25, v76, v40
	v_mul_f32_e32 v40, v41, v50
	v_bfe_u32 v41, v40, 16, 1
	v_add3_u32 v40, v40, v41, s52
	global_store_short_d16_hi v[18:19], v40, off
	v_mul_f32_e32 v18, v42, v50
	v_bfe_u32 v19, v18, 16, 1
	v_add3_u32 v18, v18, v19, s52
	global_store_short_d16_hi v[30:31], v18, off
	v_mul_f32_e32 v18, v43, v25
	v_bfe_u32 v19, v18, 16, 1
	v_add3_u32 v18, v18, v19, s52
	global_store_short_d16_hi v[10:11], v18, off
	v_add_u32_e32 v10, s9, v77
	v_mad_i64_i32 v[10:11], s[0:1], v10, s13, v[16:17]
	v_lshlrev_b64 v[10:11], 1, v[10:11]
	v_lshl_add_u64 v[18:19], s[28:29], 0, v[10:11]
	v_lshl_add_u64 v[30:31], s[22:23], 0, v[10:11]
	v_lshl_add_u64 v[40:41], s[72:73], 0, v[10:11]
	ds_read_b32 v50, v97
	ds_read_b32 v51, v98
	ds_read_b32 v52, v99
	ds_read_b32 v53, v100
	ds_read_b32 v54, v101
	ds_read_b32 v55, v102
	ds_read_b32 v43, v103
	ds_read_b32 v42, v104
	s_waitcnt lgkmcnt(7)
	v_sub_f32_e32 v10, v50, v70
	v_sub_f32_e32 v60, v70, v50
	v_min_f32_e32 v10, 0x42a00000, v10
	v_min_f32_e32 v60, 0x42a00000, v60
	v_mul_f32_e32 v10, 0x3fb8aa3b, v10
	v_mul_f32_e32 v11, 0x3fb8aa3b, v50
	v_mul_f32_e32 v60, 0x3fb8aa3b, v60
	v_exp_f32_e32 v62, v10
	v_exp_f32_e32 v11, v11
	v_exp_f32_e32 v60, v60
	v_lshlrev_b32_e32 v58, 16, v202
	v_lshlrev_b32_e32 v59, 16, v203
	v_mul_f32_e32 v61, 0xbfb8aa3b, v58
	v_mul_f32_e32 v59, 0x3fb8aa3b, v59
	v_exp_f32_e32 v61, v61
	v_exp_f32_e32 v59, v59
	v_add_f32_e32 v61, 1.0, v61
	v_add_f32_e32 v59, 1.0, v59
	v_rcp_f32_e32 v61, v61
	v_rcp_f32_e32 v59, v59
	v_mul_f32_e32 v58, v61, v58
	v_mul_f32_e32 v10, v76, v59
	v_mul_f32_e32 v59, v62, v58
	v_mul_f32_e32 v11, v11, v58
	v_mul_f32_e32 v58, v60, v10
	v_bfe_u32 v60, v59, 16, 1
	v_bfe_u32 v61, v11, 16, 1
	v_bfe_u32 v62, v58, 16, 1
	v_add3_u32 v59, v59, v60, s52
	v_add3_u32 v11, v11, v61, s52
	v_add3_u32 v58, v58, v62, s52
	global_store_short_d16_hi v[18:19], v59, off
	global_store_short_d16_hi v[30:31], v11, off
	global_store_short_d16_hi v[40:41], v58, off
	s_nop 0
	s_waitcnt lgkmcnt(6)
	v_sub_f32_e32 v39, v51, v70
	v_sub_f32_e32 v41, v70, v51
	v_min_f32_e32 v39, 0x42a00000, v39
	v_min_f32_e32 v41, 0x42a00000, v41
	v_mul_f32_e32 v39, 0x3fb8aa3b, v39
	v_mul_f32_e32 v40, 0x3fb8aa3b, v51
	v_mul_f32_e32 v41, 0x3fb8aa3b, v41
	v_exp_f32_e32 v39, v39
	v_exp_f32_e32 v40, v40
	v_exp_f32_e32 v41, v41
	v_add_u32_e32 v18, s9, v91
	v_mad_i64_i32 v[18:19], s[0:1], v18, s13, v[16:17]
	v_lshlrev_b64 v[18:19], 1, v[18:19]
	v_lshl_add_u64 v[30:31], s[28:29], 0, v[18:19]
	v_lshl_add_u64 v[36:37], s[22:23], 0, v[18:19]
	v_lshl_add_u64 v[18:19], s[72:73], 0, v[18:19]
	v_lshlrev_b32_e32 v11, 16, v204
	v_lshlrev_b32_e32 v38, 16, v205
	v_mul_f32_e32 v58, 0xbfb8aa3b, v11
	v_mul_f32_e32 v38, 0x3fb8aa3b, v38
	v_exp_f32_e32 v58, v58
	v_exp_f32_e32 v38, v38
	v_add_f32_e32 v58, 1.0, v58
	v_add_f32_e32 v38, 1.0, v38
	v_rcp_f32_e32 v58, v58
	v_rcp_f32_e32 v38, v38
	v_mul_f32_e32 v58, v58, v11
	v_mul_f32_e32 v11, v76, v38
	v_mul_f32_e32 v38, v39, v58
	v_mul_f32_e32 v39, v40, v58
	v_mul_f32_e32 v40, v41, v11
	v_bfe_u32 v41, v38, 16, 1
	v_bfe_u32 v58, v39, 16, 1
	v_bfe_u32 v59, v40, 16, 1
	v_add3_u32 v38, v38, v41, s52
	v_add3_u32 v39, v39, v58, s52
	v_add3_u32 v40, v40, v59, s52
	global_store_short_d16_hi v[30:31], v38, off
	global_store_short_d16_hi v[36:37], v39, off
	global_store_short_d16_hi v[18:19], v40, off
	s_nop 0
	v_add_u32_e32 v18, s9, v90
	v_mad_i64_i32 v[18:19], s[0:1], v18, s13, v[16:17]
	v_lshlrev_b64 v[18:19], 1, v[18:19]
	v_lshl_add_u64 v[30:31], s[28:29], 0, v[18:19]
	v_lshl_add_u64 v[32:33], s[22:23], 0, v[18:19]
	v_lshl_add_u64 v[34:35], s[72:73], 0, v[18:19]
	s_waitcnt lgkmcnt(5)
	v_sub_f32_e32 v18, v52, v70
	v_sub_f32_e32 v38, v70, v52
	v_min_f32_e32 v18, 0x42a00000, v18
	v_min_f32_e32 v38, 0x42a00000, v38
	v_mul_f32_e32 v18, 0x3fb8aa3b, v18
	v_mul_f32_e32 v19, 0x3fb8aa3b, v52
	v_mul_f32_e32 v38, 0x3fb8aa3b, v38
	v_exp_f32_e32 v40, v18
	v_exp_f32_e32 v19, v19
	v_exp_f32_e32 v38, v38
	s_waitcnt lgkmcnt(0)
; #define LAS __attribute__((address_space(3)))
; __device__ __forceinline__ unsigned f2bf(float f) { unsigned u = __builtin_bit_cast(unsigned, f); return (u + 0x7fffu + ((u >> 16) & 1u)) >> 16; }
; __device__ __forceinline__ float siluf(float x) { return x * __builtin_amdgcn_rcpf(1.0f + __expf(-x)); }
; template <int TY> __device__ __forceinline__ void ma_even_item(const Params& p, ldsp lds, int item) {
;     ...
;     for (int i = 0; i < SEGL; ++i) { const int s = sg * SEGL + i; const float bs = Bl[s * DK + d]; float qv, kv;
;         if (TY == 0) { qv = bf2f(Pb[(size_t)s * NE + E_QA + h * 64 + d]) * 0.125f; kv = bf2f(Pb[(size_t)s * NE + E_KA + h * 64 + d]); }
;         else { qv = siluf(bf2f(Pb[(size_t)s * NE + E_QB + h * 128 + d])); const float xf = bf2f(Pb[(size_t)s * NE + E_FB + h * 128 + d]); kv = (1.0f - lbv) * __builtin_amdgcn_rcpf(1.0f + __expf(xf)); }
;         const size_t g = (size_t)(row0 + s) * 768 + col;
;         QT[g] = (bf16_t)f2bf(qv * __expf(fminf(bs - bmid, 80.f))); QH[g] = (bf16_t)f2bf(qv * __expf(bs)); KT[g] = (bf16_t)f2bf(kv * __expf(fminf(bmid - bs, 80.f)));
;         *(LAS bf16_t*)(KHT + (size_t)(d * 72 + s) * 2) = (bf16_t)f2bf(kv * __expf(blast - bs)); }
	v_sub_f32_e32 v58, v70, v42
	v_lshlrev_b32_e32 v36, 16, v206
	v_lshlrev_b32_e32 v37, 16, v207
	v_mul_f32_e32 v39, 0xbfb8aa3b, v36
	v_mul_f32_e32 v37, 0x3fb8aa3b, v37
	v_exp_f32_e32 v39, v39
	v_exp_f32_e32 v37, v37
	v_add_f32_e32 v39, 1.0, v39
	v_add_f32_e32 v37, 1.0, v37
	v_rcp_f32_e32 v39, v39
	v_rcp_f32_e32 v37, v37
	v_mul_f32_e32 v36, v39, v36
	v_mul_f32_e32 v18, v76, v37
	v_mul_f32_e32 v37, v40, v36
	v_mul_f32_e32 v19, v19, v36
	v_mul_f32_e32 v36, v38, v18
	v_bfe_u32 v38, v37, 16, 1
	v_bfe_u32 v39, v19, 16, 1
	v_bfe_u32 v40, v36, 16, 1
	v_add3_u32 v37, v37, v38, s52
	v_add3_u32 v19, v19, v39, s52
	v_add3_u32 v36, v36, v40, s52
	global_store_short_d16_hi v[30:31], v37, off
	global_store_short_d16_hi v[32:33], v19, off
	global_store_short_d16_hi v[34:35], v36, off
	s_nop 0
	v_sub_f32_e32 v33, v53, v70
	v_sub_f32_e32 v35, v70, v53
	v_min_f32_e32 v33, 0x42a00000, v33
	v_min_f32_e32 v35, 0x42a00000, v35
	v_mul_f32_e32 v33, 0x3fb8aa3b, v33
	v_mul_f32_e32 v34, 0x3fb8aa3b, v53
	v_mul_f32_e32 v35, 0x3fb8aa3b, v35
	v_exp_f32_e32 v33, v33
	v_exp_f32_e32 v34, v34
	v_exp_f32_e32 v35, v35
	v_add_u32_e32 v26, s9, v89
	v_mad_i64_i32 v[26:27], s[0:1], v26, s13, v[16:17]
	v_lshlrev_b64 v[26:27], 1, v[26:27]
	v_lshl_add_u64 v[28:29], s[28:29], 0, v[26:27]
	v_lshl_add_u64 v[30:31], s[22:23], 0, v[26:27]
	v_lshl_add_u64 v[26:27], s[72:73], 0, v[26:27]
	v_add_u32_e32 v38, 0x7f, v74
	v_lshlrev_b32_e32 v19, 16, v208
	v_lshlrev_b32_e32 v32, 16, v209
	v_mul_f32_e32 v36, 0xbfb8aa3b, v19
	v_mul_f32_e32 v32, 0x3fb8aa3b, v32
	v_exp_f32_e32 v36, v36
	v_exp_f32_e32 v32, v32
	v_add_f32_e32 v36, 1.0, v36
	v_add_f32_e32 v32, 1.0, v32
	v_rcp_f32_e32 v36, v36
	v_rcp_f32_e32 v32, v32
	v_mul_f32_e32 v36, v36, v19
	v_mul_f32_e32 v19, v76, v32
	v_mul_f32_e32 v32, v33, v36
	v_mul_f32_e32 v33, v34, v36
	v_mul_f32_e32 v34, v35, v19
	v_bfe_u32 v35, v32, 16, 1
	v_bfe_u32 v36, v33, 16, 1
	v_bfe_u32 v37, v34, 16, 1
	v_add3_u32 v32, v32, v35, s52
	v_add3_u32 v33, v33, v36, s52
	v_add3_u32 v34, v34, v37, s52
	global_store_short_d16_hi v[28:29], v32, off
	global_store_short_d16_hi v[30:31], v33, off
	global_store_short_d16_hi v[26:27], v34, off
	s_nop 0
	v_add_u32_e32 v20, s9, v88
	v_mad_i64_i32 v[20:21], s[0:1], v20, s13, v[16:17]
	v_lshlrev_b64 v[20:21], 1, v[20:21]
	v_lshl_add_u64 v[22:23], s[28:29], 0, v[20:21]
	v_lshl_add_u64 v[26:27], s[22:23], 0, v[20:21]
	v_lshl_add_u64 v[28:29], s[72:73], 0, v[20:21]
	v_sub_f32_e32 v20, v54, v70
	v_sub_f32_e32 v32, v70, v54
	v_min_f32_e32 v20, 0x42a00000, v20
	v_min_f32_e32 v32, 0x42a00000, v32
	v_mul_f32_e32 v20, 0x3fb8aa3b, v20
	v_mul_f32_e32 v21, 0x3fb8aa3b, v54
	v_mul_f32_e32 v32, 0x3fb8aa3b, v32
	v_exp_f32_e32 v34, v20
	v_exp_f32_e32 v21, v21
	v_exp_f32_e32 v32, v32
	v_lshlrev_b32_e32 v30, 16, v210
	v_lshlrev_b32_e32 v31, 16, v211
	v_mul_f32_e32 v33, 0xbfb8aa3b, v30
	v_mul_f32_e32 v31, 0x3fb8aa3b, v31
	v_exp_f32_e32 v33, v33
	v_exp_f32_e32 v31, v31
	v_add_f32_e32 v33, 1.0, v33
	v_add_f32_e32 v31, 1.0, v31
	v_rcp_f32_e32 v33, v33
	v_rcp_f32_e32 v31, v31
	v_mul_f32_e32 v30, v33, v30
	v_mul_f32_e32 v20, v76, v31
	v_mul_f32_e32 v31, v34, v30
	v_mul_f32_e32 v21, v21, v30
	v_mul_f32_e32 v30, v32, v20
	v_bfe_u32 v32, v31, 16, 1
	v_bfe_u32 v33, v21, 16, 1
	v_bfe_u32 v34, v30, 16, 1
	v_add3_u32 v31, v31, v32, s52
	v_add3_u32 v21, v21, v33, s52
	v_add3_u32 v30, v30, v34, s52
	global_store_short_d16_hi v[22:23], v31, off
	global_store_short_d16_hi v[26:27], v21, off
	global_store_short_d16_hi v[28:29], v30, off
	s_nop 0
	v_sub_f32_e32 v27, v55, v70
	v_sub_f32_e32 v29, v70, v55
	v_min_f32_e32 v27, 0x42a00000, v27
	v_min_f32_e32 v29, 0x42a00000, v29
	v_mul_f32_e32 v27, 0x3fb8aa3b, v27
	v_mul_f32_e32 v28, 0x3fb8aa3b, v55
	v_mul_f32_e32 v29, 0x3fb8aa3b, v29
	v_exp_f32_e32 v27, v27
	v_exp_f32_e32 v28, v28
	v_exp_f32_e32 v29, v29
	v_add_u32_e32 v12, s9, v85
	v_mad_i64_i32 v[12:13], s[0:1], v12, s13, v[16:17]
	v_lshlrev_b64 v[12:13], 1, v[12:13]
	v_lshl_add_u64 v[14:15], s[28:29], 0, v[12:13]
	v_lshl_add_u64 v[22:23], s[22:23], 0, v[12:13]
	v_lshl_add_u64 v[12:13], s[72:73], 0, v[12:13]
	v_lshlrev_b32_e32 v21, 16, v212
	v_lshlrev_b32_e32 v26, 16, v213
	v_mul_f32_e32 v30, 0xbfb8aa3b, v21
	v_mul_f32_e32 v26, 0x3fb8aa3b, v26
	v_exp_f32_e32 v30, v30
	v_exp_f32_e32 v26, v26
	v_add_f32_e32 v30, 1.0, v30
	v_add_f32_e32 v26, 1.0, v26
	v_rcp_f32_e32 v30, v30
	v_rcp_f32_e32 v26, v26
	v_mul_f32_e32 v30, v30, v21
	v_mul_f32_e32 v21, v76, v26
	v_mul_f32_e32 v26, v27, v30
	v_mul_f32_e32 v27, v28, v30
	v_mul_f32_e32 v28, v29, v21
	v_bfe_u32 v29, v26, 16, 1
	v_bfe_u32 v30, v27, 16, 1
	v_bfe_u32 v31, v28, 16, 1
	v_add3_u32 v26, v26, v29, s52
	v_add3_u32 v27, v27, v30, s52
	v_add3_u32 v28, v28, v31, s52
	global_store_short_d16_hi v[14:15], v26, off
	global_store_short_d16_hi v[22:23], v27, off
	global_store_short_d16_hi v[12:13], v28, off
	v_mul_lo_u32 v4, v8, s53
	v_add_u32_e32 v5, v75, v4
	v_add_u32_e32 v4, v77, v4
	v_add_u32_e32 v6, s9, v78
	v_lshl_add_u32 v39, v5, 1, 0
	v_lshl_add_u32 v40, v4, 1, 0
	v_mad_i64_i32 v[4:5], s[0:1], v6, s13, v[16:17]
	v_lshlrev_b64 v[4:5], 1, v[4:5]
	v_lshl_add_u64 v[12:13], s[28:29], 0, v[4:5]
	v_lshl_add_u64 v[14:15], s[22:23], 0, v[4:5]
	v_lshl_add_u64 v[22:23], s[72:73], 0, v[4:5]
	v_add_f32_e32 v4, v44, v45
	v_add_f32_e32 v4, v4, v46
	v_add_f32_e32 v4, v4, v47
	v_sub_f32_e32 v44, v4, v51
	v_sub_f32_e32 v51, v43, v70
	v_sub_f32_e32 v46, v4, v53
	v_sub_f32_e32 v53, v70, v43
	v_min_f32_e32 v51, 0x42a00000, v51
	v_min_f32_e32 v53, 0x42a00000, v53
	v_mul_f32_e32 v51, 0x3fb8aa3b, v51
	v_sub_f32_e32 v45, v4, v52
	v_mul_f32_e32 v52, 0x3fb8aa3b, v43
; #define LAS __attribute__((address_space(3)))
; __device__ __forceinline__ unsigned f2bf(float f) { unsigned u = __builtin_bit_cast(unsigned, f); return (u + 0x7fffu + ((u >> 16) & 1u)) >> 16; }
; __device__ __forceinline__ float siluf(float x) { return x * __builtin_amdgcn_rcpf(1.0f + __expf(-x)); }
; template <int TY> __device__ __forceinline__ void ma_even_item(const Params& p, ldsp lds, int item) {
;     ...
;     for (int i = 0; i < SEGL; ++i) { const int s = sg * SEGL + i; const float bs = Bl[s * DK + d]; float qv, kv;
;         if (TY == 0) { qv = bf2f(Pb[(size_t)s * NE + E_QA + h * 64 + d]) * 0.125f; kv = bf2f(Pb[(size_t)s * NE + E_KA + h * 64 + d]); }
;         else { qv = siluf(bf2f(Pb[(size_t)s * NE + E_QB + h * 128 + d])); const float xf = bf2f(Pb[(size_t)s * NE + E_FB + h * 128 + d]); kv = (1.0f - lbv) * __builtin_amdgcn_rcpf(1.0f + __expf(xf)); }
;         const size_t g = (size_t)(row0 + s) * 768 + col;
;         QT[g] = (bf16_t)f2bf(qv * __expf(fminf(bs - bmid, 80.f))); QH[g] = (bf16_t)f2bf(qv * __expf(bs)); KT[g] = (bf16_t)f2bf(kv * __expf(fminf(bmid - bs, 80.f)));
;         *(LAS bf16_t*)(KHT + (size_t)(d * 72 + s) * 2) = (bf16_t)f2bf(kv * __expf(blast - bs)); }
;     if (sg == 0) ((float*)(p.ws + WS_DEC + (TY ? DEC_HGRN : 0)))[(size_t)item * DK + d] = __expf(blast);
	v_mul_f32_e32 v53, 0x3fb8aa3b, v53
	v_exp_f32_e32 v51, v51
	v_exp_f32_e32 v52, v52
	v_exp_f32_e32 v53, v53
	v_add_u32_e32 v7, s9, v80
	v_mad_i64_i32 v[6:7], s[0:1], v7, s13, v[16:17]
	v_sub_f32_e32 v5, v4, v71
	v_sub_f32_e32 v16, v4, v72
	v_sub_f32_e32 v32, v4, v73
	v_sub_f32_e32 v33, v4, v92
	v_sub_f32_e32 v34, v4, v93
	v_sub_f32_e32 v35, v4, v94
	v_sub_f32_e32 v36, v4, v95
	v_sub_f32_e32 v37, v4, v96
	v_sub_f32_e32 v41, v4, v50
	v_sub_f32_e32 v47, v4, v54
	v_sub_f32_e32 v50, v4, v55
	v_sub_f32_e32 v43, v4, v43
	v_sub_f32_e32 v54, v42, v70
	v_mul_f32_e32 v55, 0x3fb8aa3b, v42
	v_sub_f32_e32 v42, v4, v42
	v_mul_f32_e32 v42, 0x3fb8aa3b, v42
	s_mov_b32 s0, 0x7060302
	v_lshlrev_b64 v[6:7], 1, v[6:7]
	v_lshl_add_u64 v[26:27], s[28:29], 0, v[6:7]
	v_lshl_add_u64 v[28:29], s[22:23], 0, v[6:7]
	v_lshl_add_u64 v[6:7], s[72:73], 0, v[6:7]
	v_lshlrev_b32_e32 v30, 16, v214
	v_lshlrev_b32_e32 v31, 16, v215
	v_mul_f32_e32 v59, 0xbfb8aa3b, v30
	v_mul_f32_e32 v31, 0x3fb8aa3b, v31
	v_exp_f32_e32 v59, v59
	v_exp_f32_e32 v31, v31
	v_add_f32_e32 v59, 1.0, v59
	v_add_f32_e32 v31, 1.0, v31
	v_rcp_f32_e32 v59, v59
	v_rcp_f32_e32 v31, v31
	v_mul_f32_e32 v59, v59, v30
	v_mul_f32_e32 v30, v76, v31
	v_mul_f32_e32 v31, v51, v59
	v_mul_f32_e32 v51, v52, v59
	v_mul_f32_e32 v52, v53, v30
	v_bfe_u32 v53, v31, 16, 1
	v_bfe_u32 v59, v51, 16, 1
	v_bfe_u32 v60, v52, 16, 1
	v_add3_u32 v31, v31, v53, s52
	v_add3_u32 v51, v51, v59, s52
	v_add3_u32 v52, v52, v60, s52
	global_store_short_d16_hi v[12:13], v31, off
	global_store_short_d16_hi v[14:15], v51, off
	global_store_short_d16_hi v[22:23], v52, off
	s_nop 0
	v_mul_f32_e32 v0, 0x3fb8aa3b, v5
	v_mul_f32_e32 v1, 0x3fb8aa3b, v16
	v_exp_f32_e32 v0, v0
	v_exp_f32_e32 v1, v1
	v_mul_f32_e32 v2, 0x3fb8aa3b, v32
	v_mul_f32_e32 v3, 0x3fb8aa3b, v33
	v_exp_f32_e32 v2, v2
	v_exp_f32_e32 v3, v3
	v_mul_f32_e32 v5, 0x3fb8aa3b, v34
	v_mul_f32_e32 v13, 0x3fb8aa3b, v35
	v_mul_f32_e32 v14, 0x3fb8aa3b, v36
	v_mul_f32_e32 v15, 0x3fb8aa3b, v37
	v_mul_f32_e32 v16, 0x3fb8aa3b, v41
	v_mul_f32_e32 v36, 0x3fb8aa3b, v43
	v_min_f32_e32 v37, 0x42a00000, v54
	v_min_f32_e32 v43, 0x42a00000, v58
	v_pk_mul_f32 v[0:1], v[0:1], v[64:65]
	v_exp_f32_e32 v12, v5
	v_exp_f32_e32 v13, v13
	v_exp_f32_e32 v22, v16
	v_mul_f32_e32 v5, 0x3fb8aa3b, v37
	v_mul_f32_e32 v16, 0x3fb8aa3b, v43
	v_exp_f32_e32 v37, v42
	v_bfe_u32 v42, v1, 16, 1
	v_bfe_u32 v43, v0, 16, 1
	v_add3_u32 v0, v0, v43, s52
	v_add3_u32 v1, v1, v42, s52
	v_pk_mul_f32 v[2:3], v[2:3], v[56:57]
	v_exp_f32_e32 v14, v14
	v_exp_f32_e32 v15, v15
	v_perm_b32 v0, v1, v0, s0
	v_bfe_u32 v1, v3, 16, 1
	v_bfe_u32 v42, v2, 16, 1
	v_add3_u32 v2, v2, v42, s52
	v_add3_u32 v1, v3, v1, s52
	v_perm_b32 v1, v1, v2, s0
	v_pk_mul_f32 v[2:3], v[12:13], v[48:49]
	v_mul_f32_e32 v23, 0x3fb8aa3b, v44
	v_bfe_u32 v12, v3, 16, 1
	v_bfe_u32 v13, v2, 16, 1
	v_exp_f32_e32 v23, v23
	v_add3_u32 v2, v2, v13, s52
	v_add3_u32 v3, v3, v12, s52
	v_pk_mul_f32 v[12:13], v[14:15], v[24:25]
	v_perm_b32 v2, v3, v2, s0
	v_bfe_u32 v3, v13, 16, 1
	v_bfe_u32 v14, v12, 16, 1
	v_add3_u32 v12, v12, v14, s52
	v_add3_u32 v3, v13, v3, s52
	v_perm_b32 v3, v3, v12, s0
	v_mul_f32_e32 v32, 0x3fb8aa3b, v45
	v_mul_f32_e32 v33, 0x3fb8aa3b, v46
	ds_write_b128 v39, v[0:3] offset:40960
	v_pk_mul_f32 v[0:1], v[22:23], v[10:11]
	v_exp_f32_e32 v32, v32
	v_exp_f32_e32 v33, v33
	v_mul_f32_e32 v34, 0x3fb8aa3b, v47
	v_mul_f32_e32 v35, 0x3fb8aa3b, v50
	v_exp_f32_e32 v34, v34
	v_exp_f32_e32 v35, v35
	v_bfe_u32 v2, v1, 16, 1
	v_bfe_u32 v3, v0, 16, 1
	v_add3_u32 v0, v0, v3, s52
	v_add3_u32 v1, v1, v2, s52
	v_pk_mul_f32 v[2:3], v[32:33], v[18:19]
	v_perm_b32 v0, v1, v0, s0
	v_bfe_u32 v1, v3, 16, 1
	v_bfe_u32 v10, v2, 16, 1
	v_add3_u32 v2, v2, v10, s52
	v_add3_u32 v1, v3, v1, s52
	v_exp_f32_e32 v41, v55
	v_exp_f32_e32 v36, v36
	v_exp_f32_e32 v5, v5
	v_perm_b32 v1, v1, v2, s0
	v_pk_mul_f32 v[2:3], v[34:35], v[20:21]
	v_exp_f32_e32 v16, v16
	v_bfe_u32 v10, v3, 16, 1
	v_bfe_u32 v14, v2, 16, 1
	v_lshlrev_b32_e32 v11, 16, v216
	v_lshlrev_b32_e32 v12, 16, v217
	v_mul_f32_e32 v13, 0xbfb8aa3b, v11
	v_mul_f32_e32 v12, 0x3fb8aa3b, v12
	v_exp_f32_e32 v13, v13
	v_exp_f32_e32 v12, v12
	v_add3_u32 v2, v2, v14, s52
	v_add3_u32 v3, v3, v10, s52
	v_add_f32_e32 v13, 1.0, v13
	v_add_f32_e32 v12, 1.0, v12
	v_rcp_f32_e32 v13, v13
	v_rcp_f32_e32 v12, v12
	v_perm_b32 v2, v3, v2, s0
	v_mul_f32_e32 v3, v13, v11
	v_mul_f32_e32 v31, v76, v12
	v_mul_f32_e32 v5, v5, v3
	v_mul_f32_e32 v3, v41, v3
	v_pk_mul_f32 v[10:11], v[36:37], v[30:31]
	v_mul_f32_e32 v12, v16, v31
	v_bfe_u32 v13, v5, 16, 1
	v_bfe_u32 v14, v3, 16, 1
	v_bfe_u32 v16, v11, 16, 1
	v_bfe_u32 v18, v10, 16, 1
	v_bfe_u32 v15, v12, 16, 1
	v_add3_u32 v5, v5, v13, s52
	v_add3_u32 v3, v3, v14, s52
	v_add3_u32 v10, v10, v18, s52
	v_add3_u32 v11, v11, v16, s52
	v_add3_u32 v12, v12, v15, s52
	global_store_short_d16_hi v[26:27], v5, off
	global_store_short_d16_hi v[28:29], v3, off
	global_store_short_d16_hi v[6:7], v12, off
	v_perm_b32 v3, v11, v10, s0
	s_movk_i32 s0, 0xfe
	v_cmp_lt_u32_e32 vcc, s0, v38
	ds_write_b128 v40, v[0:3] offset:40960
	s_and_saveexec_b64 s[0:1], vcc
	s_xor_b64 s[0:1], exec, s[0:1]
	s_ashr_i32 s13, s12, 31
	s_or_saveexec_b64 s[0:1], s[0:1]
	v_mov_b64_e32 v[34:35], s[12:13]
	s_xor_b64 exec, exec, s[0:1]
	s_cbranch_execz .LBB0_1056
	v_mul_f32_e32 v0, 0x3fb8aa3b, v4
	s_ashr_i32 s13, s12, 31
	v_exp_f32_e32 v2, v0
	s_lshl_b64 s[14:15], s[12:13], 9
	v_readlane_b32 s9, v253, 53
	s_add_u32 s14, s9, s14
	v_readlane_b32 s9, v253, 54
	s_addc_u32 s15, s9, s15
	v_lshl_add_u64 v[0:1], v[8:9], 2, s[14:15]
	v_mov_b64_e32 v[34:35], s[12:13]
	global_store_dword v[0:1], v2, off

; __device__ __forceinline__ float logsig(float x) { return fminf(x, 0.f) - __logf(1.0f + __expf(-fabsf(x))); }
; #define BSYNC() do { asm volatile("s_waitcnt vmcnt(0) lgkmcnt(0)" ::: "memory"); __syncthreads(); } while (0)
; template <int TY> __device__ __forceinline__ void ma_even_item(const Params& p, ldsp lds, int item) {
;     ...
;     if (TY == 0) { for (int idx = tid; idx < 1024; idx += NTHREADS) LRs[idx] = bf2f(Pb[(size_t)(idx >> 4) * NE + E_LR + (idx & 15)]); }
;     stage_T<128>(VT, 72, Pb + (TY ? E_IB : E_VA) + h * 128, NE, wave, lane);
;     float w2[16]; float bias = 0.f, lbv = 0.f;
;     if (TY == 0) {
; #pragma unroll
;         for (int r = 0; r < 16; ++r) w2[r] = p.in[10][r * 256 + h * 64 + d];
;         bias = p.in[11][h * 64 + d];
;     } else { const float t0 = p.in[13][h * 128 + d], t1 = p.in[13][512 + h * 128 + d], t2 = p.in[13][1024 + h * 128 + d];
;         const float mx = fmaxf(t0, fmaxf(t1, t2)); const float e0 = __expf(t0 - mx), e1 = __expf(t1 - mx), e2 = __expf(t2 - mx); lbv = e0 / (e0 + e1 + e2); }
;     BSYNC();
;     float run = 0.f;
; #pragma unroll
;     for (int i = 0; i < SEGL; ++i) { const int s = sg * SEGL + i; float g;
;         if (TY == 0) { float x = bias;
; #pragma unroll
;             for (int r = 0; r < 16; ++r) x += LRs[s * 16 + r] * w2[r];
;             g = logsig(x) * 0.0625f;
;         } else { const float x = bf2f(Pb[(size_t)s * NE + E_FB + h * 128 + d]); const float sig = __builtin_amdgcn_rcpf(1.0f + __expf(-x)); g = __logf(lbv + (1.0f - lbv) * sig); }
;         run += g; Bl[s * DK + d] = run; }
.LBB0_1065:
	s_or_b64 exec, exec, s[8:9]
	s_bfe_u32 s9, s12, 0x20005
	s_ashr_i32 s8, s19, 6
	s_lshl_b32 s40, s9, 7
	s_lshl_b32 s14, s9, 8
	s_add_u32 s14, s0, s14
	s_addc_u32 s15, s1, 0
	s_lshl_b32 s16, s8, 5
	v_and_b32_e32 v1, 31, v0
	v_and_or_b32 v1, s16, 32, v1
	v_bfe_u32 v4, v0, 5, 1
	v_mul_u32_u24_e32 v2, 0xf00, v1
	v_and_or_b32 v6, s8, -2, v4
	v_lshlrev_b32_e32 v16, 1, v2
	v_lshlrev_b32_e32 v4, 3, v6
	v_lshl_add_u64 v[2:3], s[14:15], 0, v[16:17]
	v_ashrrev_i32_e32 v5, 31, v4
	v_lshl_add_u64 v[4:5], v[4:5], 1, v[2:3]
	global_load_dwordx4 v[22:25], v[4:5], off offset:1024
	global_load_dwordx4 v[30:33], v[4:5], off offset:1152
	v_ashrrev_i32_e32 v2, 31, v0
	v_lshrrev_b32_e32 v2, 26, v2
	v_add_u32_e32 v3, v0, v2
	v_and_b32_e32 v2, 0xffffffc0, v3
	v_sub_u32_e32 v2, v0, v2
	v_lshl_add_u32 v4, s9, 6, v2
	v_readlane_b32 s76, v252, 20
	v_ashrrev_i32_e32 v5, 31, v4
	v_readlane_b32 s77, v252, 21
	v_readlane_b32 s78, v252, 22
	v_readlane_b32 s79, v252, 23
	v_readlane_b32 s80, v252, 24
	v_readlane_b32 s81, v252, 25
	v_readlane_b32 s82, v252, 26
	v_readlane_b32 s83, v252, 27
	v_readlane_b32 s84, v252, 28
	v_readlane_b32 s85, v252, 29
	v_lshlrev_b64 v[8:9], 2, v[4:5]
	v_readlane_b32 s86, v252, 30
	v_readlane_b32 s87, v252, 31
	v_readlane_b32 s88, v252, 32
	v_readlane_b32 s89, v252, 33
	s_mov_b64 s[76:77], s[80:81]
	v_lshl_add_u64 v[26:27], s[76:77], 0, v[8:9]
	v_add_co_u32_e32 v18, vcc, s57, v26
	s_movk_i32 s9, 0x2000
	s_nop 0
	v_addc_co_u32_e32 v19, vcc, 0, v27, vcc
	s_mov_b64 s[78:79], s[82:83]
	v_add_co_u32_e32 v28, vcc, s9, v26
	v_lshl_add_u64 v[8:9], s[78:79], 0, v[8:9]
	s_nop 0
	v_addc_co_u32_e32 v29, vcc, 0, v27, vcc
	global_load_dword v8, v[8:9], off
	s_nop 0
	global_load_dword v12, v[26:27], off
	global_load_dword v13, v[26:27], off offset:1024
	global_load_dword v14, v[26:27], off offset:2048
	global_load_dword v15, v[26:27], off offset:3072
	global_load_dword v9, v[18:19], off offset:1024
	global_load_dword v10, v[18:19], off offset:2048
	global_load_dword v11, v[18:19], off offset:3072
	global_load_dword v39, v[28:29], off offset:-4096
	s_nop 0
	global_load_dword v19, v[28:29], off
	global_load_dword v20, v[28:29], off offset:1024
	global_load_dword v21, v[28:29], off offset:2048
	s_nop 0
	global_load_dword v29, v[28:29], off offset:3072
	v_add_co_u32_e32 v26, vcc, s56, v26
	s_movk_i32 s9, 0x240
	s_nop 0
	v_addc_co_u32_e32 v27, vcc, 0, v27, vcc
	global_load_dword v34, v[26:27], off
	global_load_dword v35, v[26:27], off offset:1024
	global_load_dword v36, v[26:27], off offset:2048
	global_load_dword v37, v[26:27], off offset:3072
	v_mul_lo_u32 v16, v6, s9
	v_or_b32_e32 v1, v1, v16
	v_ashrrev_i32_e32 v3, 6, v3
	v_lshl_add_u32 v1, v1, 1, 0
	v_lshl_add_u32 v40, v3, 9, 0
	v_add_u32_e32 v16, 0xe800, v1
	s_mov_b32 s9, 0xbfb8aa3b
	s_mov_b32 s15, 0x3f317217
	s_mov_b32 s16, 0x7f800000
	v_lshlrev_b32_e32 v18, 2, v2
	v_lshlrev_b32_e32 v6, 3, v3
	v_lshlrev_b32_e32 v3, 11, v3
	s_mov_b32 s14, 0x3d800000
	v_readlane_b32 s90, v252, 34
	v_readlane_b32 s91, v252, 35
	s_mov_b64 s[80:81], s[84:85]
	s_mov_b64 s[82:83], s[86:87]
	s_mov_b64 s[84:85], s[88:89]
	s_waitcnt vmcnt(0)
	ds_write_b16 v1, v22 offset:59392
	ds_write_b16_d16_hi v1, v22 offset:59536
	ds_write_b16 v1, v23 offset:59680
	ds_write_b16_d16_hi v1, v23 offset:59824
	ds_write_b16 v1, v24 offset:59968
	ds_write_b16_d16_hi v1, v24 offset:60112
	ds_write_b16 v1, v25 offset:60256
	ds_write_b16_d16_hi v1, v25 offset:60400
	ds_write_b16 v16, v30 offset:9216
	ds_write_b16_d16_hi v16, v30 offset:9360
	ds_write_b16 v16, v31 offset:9504
	ds_write_b16_d16_hi v16, v31 offset:9648
	ds_write_b16 v16, v32 offset:9792
	ds_write_b16_d16_hi v16, v32 offset:9936
	ds_write_b16 v16, v33 offset:10080
	ds_write_b16_d16_hi v16, v33 offset:10224
	s_waitcnt vmcnt(0) lgkmcnt(0)
	s_waitcnt lgkmcnt(0)
	s_barrier
	ds_read_b128 v[22:25], v40 offset:36864
	ds_read_b128 v[30:33], v40 offset:36880
	ds_read_b128 v[42:45], v40 offset:36896
	ds_read_b128 v[46:49], v40 offset:36912
	s_waitcnt lgkmcnt(3)
	v_fma_f32 v16, v12, v22, v8
	v_fmac_f32_e32 v16, v13, v23
	v_fmac_f32_e32 v16, v14, v24
	v_fmac_f32_e32 v16, v15, v25
	v_add_u32_e32 v22, 0, v18
	s_waitcnt lgkmcnt(2)
	v_fmac_f32_e32 v16, v39, v30
	v_fmac_f32_e32 v16, v9, v31
	v_fmac_f32_e32 v16, v10, v32
	v_fmac_f32_e32 v16, v11, v33
	s_waitcnt lgkmcnt(1)
	v_fmac_f32_e32 v16, v19, v42
	v_fmac_f32_e32 v16, v20, v43
	v_fmac_f32_e32 v16, v21, v44
	v_fmac_f32_e32 v16, v29, v45
	s_waitcnt lgkmcnt(0)
	v_fmac_f32_e32 v16, v34, v46
	v_fmac_f32_e32 v16, v35, v47
	v_fmac_f32_e32 v16, v36, v48
	v_fmac_f32_e32 v16, v37, v49
	v_mul_f32_e64 v1, |v16|, s9
	v_exp_f32_e32 v23, v1
	v_min_f32_e32 v16, 0, v16
	v_or_b32_e32 v1, 1, v6
	v_lshl_add_u32 v28, v1, 6, 0
	v_add_f32_e32 v23, 1.0, v23
	v_cmp_gt_f32_e32 vcc, s33, v23
	s_nop 1
	v_cndmask_b32_e64 v24, 0, 32, vcc
	v_ldexp_f32 v23, v23, v24
	v_log_f32_e32 v24, v23
	v_cndmask_b32_e32 v25, 0, v185, vcc
	v_add_u32_e32 v23, v22, v3
	v_add3_u32 v3, 0, v3, v18
	v_mul_f32_e32 v26, 0x3f317217, v24
	v_fma_f32 v26, v24, s15, -v26
	v_fmac_f32_e32 v26, 0x3377d1cf, v24
	v_fmac_f32_e32 v26, 0x3f317217, v24
	v_cmp_lt_f32_e64 vcc, |v24|, s16
	s_nop 1
	v_cndmask_b32_e32 v24, v24, v26, vcc
	v_sub_f32_e32 v24, v24, v25
	v_sub_f32_e32 v16, v16, v24
	v_fma_f32 v58, v16, s14, 0
	ds_write_b32 v23, v58
	ds_read_b128 v[24:27], v28 offset:36864
	ds_read_b128 v[30:33], v28 offset:36880
	ds_read_b128 v[42:45], v28 offset:36896
	ds_read_b128 v[46:49], v28 offset:36912
	s_waitcnt lgkmcnt(3)
	v_fma_f32 v28, v12, v24, v8
	v_fmac_f32_e32 v28, v13, v25
	v_fmac_f32_e32 v28, v14, v26
	v_fmac_f32_e32 v28, v15, v27
	s_waitcnt lgkmcnt(2)
; __device__ __forceinline__ float logsig(float x) { return fminf(x, 0.f) - __logf(1.0f + __expf(-fabsf(x))); }
; template <int TY> __device__ __forceinline__ void ma_even_item(const Params& p, ldsp lds, int item) {
;     ...
; #pragma unroll
;     for (int i = 0; i < SEGL; ++i) { const int s = sg * SEGL + i; float g;
;         if (TY == 0) { float x = bias;
; #pragma unroll
;             for (int r = 0; r < 16; ++r) x += LRs[s * 16 + r] * w2[r];
;             g = logsig(x) * 0.0625f;
;         } else { const float x = bf2f(Pb[(size_t)s * NE + E_FB + h * 128 + d]); const float sig = __builtin_amdgcn_rcpf(1.0f + __expf(-x)); g = __logf(lbv + (1.0f - lbv) * sig); }
;         run += g; Bl[s * DK + d] = run; }
	v_fmac_f32_e32 v28, v39, v30
	v_fmac_f32_e32 v28, v9, v31
	v_fmac_f32_e32 v28, v10, v32
	v_fmac_f32_e32 v28, v11, v33
	s_waitcnt lgkmcnt(1)
	v_fmac_f32_e32 v28, v19, v42
	v_fmac_f32_e32 v28, v20, v43
	v_fmac_f32_e32 v28, v21, v44
	v_fmac_f32_e32 v28, v29, v45
	s_waitcnt lgkmcnt(0)
	v_fmac_f32_e32 v28, v34, v46
	v_fmac_f32_e32 v28, v35, v47
	v_fmac_f32_e32 v28, v36, v48
	v_fmac_f32_e32 v28, v37, v49
	v_mul_f32_e64 v16, |v28|, s9
	v_exp_f32_e32 v24, v16
	v_min_f32_e32 v27, 0, v28
	v_or_b32_e32 v16, 2, v6
	v_lshl_add_u32 v25, v16, 6, 0
	v_add_f32_e32 v24, 1.0, v24
	v_cmp_gt_f32_e32 vcc, s33, v24
	s_nop 1
	v_cndmask_b32_e64 v26, 0, 32, vcc
	v_ldexp_f32 v24, v24, v26
	v_log_f32_e32 v26, v24
	v_cndmask_b32_e32 v28, 0, v185, vcc
	v_lshl_add_u32 v24, v1, 8, v22
	v_mul_f32_e32 v30, 0x3f317217, v26
	v_fma_f32 v30, v26, s15, -v30
	v_fmac_f32_e32 v30, 0x3377d1cf, v26
	v_fmac_f32_e32 v30, 0x3f317217, v26
	v_cmp_lt_f32_e64 vcc, |v26|, s16
	s_nop 1
	v_cndmask_b32_e32 v26, v26, v30, vcc
	v_sub_f32_e32 v26, v26, v28
	v_sub_f32_e32 v26, v27, v26
	v_fmac_f32_e32 v58, 0x3d800000, v26
	ds_write_b32 v24, v58
	ds_read_b128 v[30:33], v25 offset:36864
	ds_read_b128 v[42:45], v25 offset:36880
	ds_read_b128 v[46:49], v25 offset:36896
	ds_read_b128 v[50:53], v25 offset:36912
	s_waitcnt lgkmcnt(3)
	v_fma_f32 v26, v12, v30, v8
	v_fmac_f32_e32 v26, v13, v31
	v_fmac_f32_e32 v26, v14, v32
	v_fmac_f32_e32 v26, v15, v33
	s_waitcnt lgkmcnt(2)
	v_fmac_f32_e32 v26, v39, v42
	v_fmac_f32_e32 v26, v9, v43
	v_fmac_f32_e32 v26, v10, v44
	v_fmac_f32_e32 v26, v11, v45
	s_waitcnt lgkmcnt(1)
	v_fmac_f32_e32 v26, v19, v46
	v_fmac_f32_e32 v26, v20, v47
	v_fmac_f32_e32 v26, v21, v48
	v_fmac_f32_e32 v26, v29, v49
	s_waitcnt lgkmcnt(0)
	v_fmac_f32_e32 v26, v34, v50
	v_fmac_f32_e32 v26, v35, v51
	v_fmac_f32_e32 v26, v36, v52
	v_fmac_f32_e32 v26, v37, v53
	v_mul_f32_e64 v25, |v26|, s9
	v_exp_f32_e32 v27, v25
	v_min_f32_e32 v26, 0, v26
	v_or_b32_e32 v25, 3, v6
	v_lshl_add_u32 v31, v16, 8, v22
	v_add_f32_e32 v27, 1.0, v27
	v_cmp_gt_f32_e32 vcc, s33, v27
	v_lshl_add_u32 v28, v25, 6, 0
	s_nop 0
	v_cndmask_b32_e64 v30, 0, 32, vcc
	v_ldexp_f32 v27, v27, v30
	v_log_f32_e32 v27, v27
	v_cndmask_b32_e32 v30, 0, v185, vcc
	v_mul_f32_e32 v32, 0x3f317217, v27
	v_fma_f32 v32, v27, s15, -v32
	v_fmac_f32_e32 v32, 0x3377d1cf, v27
	v_fmac_f32_e32 v32, 0x3f317217, v27
	v_cmp_lt_f32_e64 vcc, |v27|, s16
	s_nop 1
	v_cndmask_b32_e32 v27, v27, v32, vcc
	v_sub_f32_e32 v27, v27, v30
	v_sub_f32_e32 v26, v26, v27
	v_fmac_f32_e32 v58, 0x3d800000, v26
	ds_write_b32 v31, v58
	ds_read_b128 v[42:45], v28 offset:36864
	ds_read_b128 v[46:49], v28 offset:36880
	ds_read_b128 v[50:53], v28 offset:36896
	ds_read_b128 v[54:57], v28 offset:36912
	s_waitcnt lgkmcnt(3)
	v_fma_f32 v27, v12, v42, v8
	v_fmac_f32_e32 v27, v13, v43
	v_fmac_f32_e32 v27, v14, v44
	v_fmac_f32_e32 v27, v15, v45
	s_waitcnt lgkmcnt(2)
	v_fmac_f32_e32 v27, v39, v46
	v_fmac_f32_e32 v27, v9, v47
	v_fmac_f32_e32 v27, v10, v48
	v_fmac_f32_e32 v27, v11, v49
	s_waitcnt lgkmcnt(1)
	v_fmac_f32_e32 v27, v19, v50
	v_fmac_f32_e32 v27, v20, v51
	v_fmac_f32_e32 v27, v21, v52
	v_fmac_f32_e32 v27, v29, v53
	s_waitcnt lgkmcnt(0)
	v_fmac_f32_e32 v27, v34, v54
	v_fmac_f32_e32 v27, v35, v55
	v_fmac_f32_e32 v27, v36, v56
	v_fmac_f32_e32 v27, v37, v57
	v_mul_f32_e64 v26, |v27|, s9
	v_exp_f32_e32 v28, v26
	v_min_f32_e32 v27, 0, v27
	v_or_b32_e32 v26, 4, v6
	v_lshl_add_u32 v30, v26, 6, 0
	v_add_f32_e32 v28, 1.0, v28
	v_cmp_gt_f32_e32 vcc, s33, v28
	s_nop 1
	v_cndmask_b32_e64 v32, 0, 32, vcc
	v_ldexp_f32 v28, v28, v32
	v_log_f32_e32 v28, v28
	v_cndmask_b32_e32 v33, 0, v185, vcc
	v_lshl_add_u32 v32, v25, 8, v22
	v_mul_f32_e32 v38, 0x3f317217, v28
	v_fma_f32 v38, v28, s15, -v38
	v_fmac_f32_e32 v38, 0x3377d1cf, v28
	v_fmac_f32_e32 v38, 0x3f317217, v28
	v_cmp_lt_f32_e64 vcc, |v28|, s16
	s_nop 1
	v_cndmask_b32_e32 v28, v28, v38, vcc
	v_sub_f32_e32 v28, v28, v33
	v_sub_f32_e32 v27, v27, v28
	v_fmac_f32_e32 v58, 0x3d800000, v27
	ds_write_b32 v32, v58
	ds_read_b128 v[42:45], v30 offset:36864
	ds_read_b128 v[46:49], v30 offset:36880
	ds_read_b128 v[50:53], v30 offset:36896
	ds_read_b128 v[54:57], v30 offset:36912
	s_waitcnt lgkmcnt(3)
	v_fma_f32 v28, v12, v42, v8
	v_fmac_f32_e32 v28, v13, v43
	v_fmac_f32_e32 v28, v14, v44
	v_fmac_f32_e32 v28, v15, v45
	s_waitcnt lgkmcnt(2)
	v_fmac_f32_e32 v28, v39, v46
	v_fmac_f32_e32 v28, v9, v47
	v_fmac_f32_e32 v28, v10, v48
	v_fmac_f32_e32 v28, v11, v49
	s_waitcnt lgkmcnt(1)
	v_fmac_f32_e32 v28, v19, v50
	v_fmac_f32_e32 v28, v20, v51
	v_fmac_f32_e32 v28, v21, v52
	v_fmac_f32_e32 v28, v29, v53
	s_waitcnt lgkmcnt(0)
	v_fmac_f32_e32 v28, v34, v54
	v_fmac_f32_e32 v28, v35, v55
	v_fmac_f32_e32 v28, v36, v56
	v_fmac_f32_e32 v28, v37, v57
	v_mul_f32_e64 v27, |v28|, s9
	v_exp_f32_e32 v30, v27
	v_min_f32_e32 v28, 0, v28
	v_or_b32_e32 v27, 5, v6
	v_lshl_add_u32 v38, v27, 6, 0
	v_add_f32_e32 v30, 1.0, v30
	v_cmp_gt_f32_e32 vcc, s33, v30
	s_nop 1
	v_cndmask_b32_e64 v33, 0, 32, vcc
	v_ldexp_f32 v30, v30, v33
	v_log_f32_e32 v30, v30
	v_cndmask_b32_e32 v41, 0, v185, vcc
	v_lshl_add_u32 v33, v26, 8, v22
	v_mul_f32_e32 v42, 0x3f317217, v30
	v_fma_f32 v42, v30, s15, -v42
	v_fmac_f32_e32 v42, 0x3377d1cf, v30
	v_fmac_f32_e32 v42, 0x3f317217, v30
	v_cmp_lt_f32_e64 vcc, |v30|, s16
	s_nop 1
	v_cndmask_b32_e32 v30, v30, v42, vcc
	v_sub_f32_e32 v30, v30, v41
	v_sub_f32_e32 v28, v28, v30
	v_fmac_f32_e32 v58, 0x3d800000, v28
	ds_write_b32 v33, v58
	ds_read_b128 v[42:45], v38 offset:36864
	ds_read_b128 v[46:49], v38 offset:36880
	ds_read_b128 v[50:53], v38 offset:36896
	ds_read_b128 v[54:57], v38 offset:36912
	s_waitcnt lgkmcnt(3)
; __device__ __forceinline__ float logsig(float x) { return fminf(x, 0.f) - __logf(1.0f + __expf(-fabsf(x))); }
; #define BSYNC() do { asm volatile("s_waitcnt vmcnt(0) lgkmcnt(0)" ::: "memory"); __syncthreads(); } while (0)
; template <int TY> __device__ __forceinline__ void ma_even_item(const Params& p, ldsp lds, int item) {
;     ...
; #pragma unroll
;     for (int i = 0; i < SEGL; ++i) { const int s = sg * SEGL + i; float g;
;         if (TY == 0) { float x = bias;
; #pragma unroll
;             for (int r = 0; r < 16; ++r) x += LRs[s * 16 + r] * w2[r];
;             g = logsig(x) * 0.0625f;
;         } else { const float x = bf2f(Pb[(size_t)s * NE + E_FB + h * 128 + d]); const float sig = __builtin_amdgcn_rcpf(1.0f + __expf(-x)); g = __logf(lbv + (1.0f - lbv) * sig); }
;         run += g; Bl[s * DK + d] = run; }
;     SEG[sg * 128 + d] = run;
;     BSYNC();
;     float off = 0.f, tot = 0.f;
; #pragma unroll
;     for (int s2 = 0; s2 < NSEG; ++s2) { const float v = SEG[s2 * 128 + d]; if (s2 < sg) off += v; tot += v; }
; #pragma unroll
;     for (int i = 0; i < SEGL; ++i) Bl[(sg * SEGL + i) * DK + d] += off;
;     BSYNC();
;     const float bmid = Bl[31 * DK + d], blast = tot;
	v_fma_f32 v28, v12, v42, v8
	v_fmac_f32_e32 v28, v13, v43
	v_fmac_f32_e32 v28, v14, v44
	v_fmac_f32_e32 v28, v15, v45
	s_waitcnt lgkmcnt(2)
	v_fmac_f32_e32 v28, v39, v46
	v_fmac_f32_e32 v28, v9, v47
	v_fmac_f32_e32 v28, v10, v48
	v_fmac_f32_e32 v28, v11, v49
	s_waitcnt lgkmcnt(1)
	v_fmac_f32_e32 v28, v19, v50
	v_fmac_f32_e32 v28, v20, v51
	v_fmac_f32_e32 v28, v21, v52
	v_fmac_f32_e32 v28, v29, v53
	s_waitcnt lgkmcnt(0)
	v_fmac_f32_e32 v28, v34, v54
	v_fmac_f32_e32 v28, v35, v55
	v_fmac_f32_e32 v28, v36, v56
	v_fmac_f32_e32 v28, v37, v57
	v_mul_f32_e64 v30, |v28|, s9
	v_exp_f32_e32 v38, v30
	v_min_f32_e32 v28, 0, v28
	v_or_b32_e32 v30, 6, v6
	v_lshl_add_u32 v41, v30, 6, 0
	v_add_f32_e32 v38, 1.0, v38
	v_cmp_gt_f32_e32 vcc, s33, v38
	s_nop 1
	v_cndmask_b32_e64 v42, 0, 32, vcc
	v_ldexp_f32 v38, v38, v42
	v_log_f32_e32 v42, v38
	v_cndmask_b32_e32 v43, 0, v185, vcc
	v_lshl_add_u32 v38, v27, 8, v22
	v_mul_f32_e32 v44, 0x3f317217, v42
	v_fma_f32 v44, v42, s15, -v44
	v_fmac_f32_e32 v44, 0x3377d1cf, v42
	v_fmac_f32_e32 v44, 0x3f317217, v42
	v_cmp_lt_f32_e64 vcc, |v42|, s16
	s_nop 1
	v_cndmask_b32_e32 v42, v42, v44, vcc
	v_sub_f32_e32 v42, v42, v43
	v_sub_f32_e32 v28, v28, v42
	v_fmac_f32_e32 v58, 0x3d800000, v28
	ds_write_b32 v38, v58
	ds_read_b128 v[42:45], v41 offset:36864
	ds_read_b128 v[46:49], v41 offset:36880
	ds_read_b128 v[50:53], v41 offset:36896
	ds_read_b128 v[54:57], v41 offset:36912
	s_waitcnt lgkmcnt(3)
	v_fma_f32 v42, v12, v42, v8
	v_fmac_f32_e32 v42, v13, v43
	v_fmac_f32_e32 v42, v14, v44
	v_fmac_f32_e32 v42, v15, v45
	s_waitcnt lgkmcnt(2)
	v_fmac_f32_e32 v42, v39, v46
	v_fmac_f32_e32 v42, v9, v47
	v_fmac_f32_e32 v42, v10, v48
	v_fmac_f32_e32 v42, v11, v49
	s_waitcnt lgkmcnt(1)
	v_fmac_f32_e32 v42, v19, v50
	v_fmac_f32_e32 v42, v20, v51
	v_fmac_f32_e32 v42, v21, v52
	v_fmac_f32_e32 v42, v29, v53
	s_waitcnt lgkmcnt(0)
	v_fmac_f32_e32 v42, v34, v54
	v_fmac_f32_e32 v42, v35, v55
	v_fmac_f32_e32 v42, v36, v56
	v_fmac_f32_e32 v42, v37, v57
	v_mul_f32_e64 v28, |v42|, s9
	v_exp_f32_e32 v41, v28
	v_min_f32_e32 v42, 0, v42
	v_or_b32_e32 v28, 7, v6
	v_lshl_add_u32 v54, v28, 6, 0
	v_add_f32_e32 v41, 1.0, v41
	v_cmp_gt_f32_e32 vcc, s33, v41
	s_nop 1
	v_cndmask_b32_e64 v43, 0, 32, vcc
	v_ldexp_f32 v41, v41, v43
	v_log_f32_e32 v43, v41
	v_cndmask_b32_e32 v44, 0, v185, vcc
	v_lshl_add_u32 v41, v30, 8, v22
	v_mul_f32_e32 v45, 0x3f317217, v43
	v_fma_f32 v45, v43, s15, -v45
	v_fmac_f32_e32 v45, 0x3377d1cf, v43
	v_fmac_f32_e32 v45, 0x3f317217, v43
	v_cmp_lt_f32_e64 vcc, |v43|, s16
	s_nop 1
	v_cndmask_b32_e32 v43, v43, v45, vcc
	v_sub_f32_e32 v43, v43, v44
	v_sub_f32_e32 v42, v42, v43
	v_fmac_f32_e32 v58, 0x3d800000, v42
	ds_write_b32 v41, v58
	ds_read_b128 v[42:45], v54 offset:36864
	ds_read_b128 v[46:49], v54 offset:36880
	ds_read_b128 v[50:53], v54 offset:36896
	ds_read_b128 v[54:57], v54 offset:36912
	s_waitcnt lgkmcnt(3)
	v_fmac_f32_e32 v8, v12, v42
	v_fmac_f32_e32 v8, v13, v43
	v_fmac_f32_e32 v8, v14, v44
	v_fmac_f32_e32 v8, v15, v45
	s_waitcnt lgkmcnt(2)
	v_fmac_f32_e32 v8, v39, v46
	v_fmac_f32_e32 v8, v9, v47
	v_fmac_f32_e32 v8, v10, v48
	v_fmac_f32_e32 v8, v11, v49
	s_waitcnt lgkmcnt(1)
	v_fmac_f32_e32 v8, v19, v50
	v_fmac_f32_e32 v8, v20, v51
	v_fmac_f32_e32 v8, v21, v52
	v_fmac_f32_e32 v8, v29, v53
	s_waitcnt lgkmcnt(0)
	v_fmac_f32_e32 v8, v34, v54
	v_fmac_f32_e32 v8, v35, v55
	v_fmac_f32_e32 v8, v36, v56
	v_fmac_f32_e32 v8, v37, v57
	v_mul_f32_e64 v9, |v8|, s9
	v_exp_f32_e32 v9, v9
	v_min_f32_e32 v8, 0, v8
	v_lshl_add_u32 v29, v28, 8, v22
	v_add_u32_e32 v10, v40, v18
	v_add_f32_e32 v9, 1.0, v9
	v_cmp_gt_f32_e32 vcc, s33, v9
	s_movk_i32 s9, 0x7f
	s_nop 0
	v_cndmask_b32_e64 v11, 0, 32, vcc
	v_ldexp_f32 v9, v9, v11
	v_log_f32_e32 v9, v9
	v_cndmask_b32_e32 v11, 0, v185, vcc
	v_mul_f32_e32 v12, 0x3f317217, v9
	v_fma_f32 v12, v9, s15, -v12
	v_fmac_f32_e32 v12, 0x3377d1cf, v9
	v_fmac_f32_e32 v12, 0x3f317217, v9
	v_cmp_lt_f32_e64 vcc, |v9|, s16
	s_nop 1
	v_cndmask_b32_e32 v9, v9, v12, vcc
	v_sub_f32_e32 v9, v9, v11
	v_sub_f32_e32 v8, v8, v9
	v_fmac_f32_e32 v58, 0x3d800000, v8
	ds_write_b32 v29, v58
	ds_write_b32 v10, v58 offset:32768
	s_waitcnt vmcnt(0) lgkmcnt(0)
	s_waitcnt lgkmcnt(0)
	s_barrier
	ds_read2st64_b32 v[10:11], v22 offset0:128 offset1:130
	ds_read2st64_b32 v[8:9], v22 offset0:132 offset1:134
	v_cmp_lt_i32_e32 vcc, 63, v0
	s_waitcnt lgkmcnt(1)
	v_add_f32_e32 v10, 0, v10
	v_cndmask_b32_e32 v12, 0, v10, vcc
	v_add_f32_e32 v13, v11, v12
	v_cmp_lt_i32_e32 vcc, s9, v0
	s_movk_i32 s9, 0xbf
	s_nop 0
	v_cndmask_b32_e32 v14, v12, v13, vcc
	ds_read2st64_b32 v[12:13], v22 offset0:136 offset1:138
	s_waitcnt lgkmcnt(1)
	v_add_f32_e32 v15, v8, v14
	v_cmp_lt_i32_e32 vcc, s9, v0
	s_movk_i32 s9, 0xff
	s_nop 0
	v_cndmask_b32_e32 v14, v14, v15, vcc
	v_add_f32_e32 v15, v9, v14
	v_cmp_lt_i32_e32 vcc, s9, v0
	s_movk_i32 s9, 0x13f
	s_nop 0
	v_cndmask_b32_e32 v19, v14, v15, vcc
	ds_read2st64_b32 v[14:15], v22 offset0:140 offset1:142
	s_waitcnt lgkmcnt(1)
	v_add_f32_e32 v20, v12, v19
	v_cmp_lt_i32_e32 vcc, s9, v0
	s_movk_i32 s9, 0x17f
	s_nop 0
	v_cndmask_b32_e32 v19, v19, v20, vcc
	v_add_f32_e32 v20, v13, v19
	v_cmp_lt_i32_e32 vcc, s9, v0
	s_movk_i32 s9, 0x1bf
	s_nop 0
	v_cndmask_b32_e32 v19, v19, v20, vcc
	s_waitcnt lgkmcnt(0)
	v_add_f32_e32 v20, v14, v19
	v_cmp_lt_i32_e32 vcc, s9, v0
	s_movk_i32 s9, 0x300
	s_nop 0
	v_cndmask_b32_e32 v20, v19, v20, vcc
	ds_read2st64_b32 v[18:19], v3 offset1:1
	v_add_f32_e32 v21, v15, v20
	v_cmp_lt_i32_e32 vcc, s60, v0
	s_nop 1
	v_cndmask_b32_e32 v39, v20, v21, vcc
	ds_read2st64_b32 v[20:21], v3 offset0:2 offset1:3
	ds_read2st64_b32 v[34:35], v3 offset0:4 offset1:5
	ds_read2st64_b32 v[36:37], v3 offset0:6 offset1:7
	s_waitcnt lgkmcnt(3)
	v_add_f32_e32 v18, v18, v39
	v_add_f32_e32 v19, v19, v39
	ds_write2st64_b32 v3, v18, v19 offset1:1
	s_waitcnt lgkmcnt(3)
	v_add_f32_e32 v18, v20, v39
	v_add_f32_e32 v19, v21, v39
	ds_write2st64_b32 v3, v18, v19 offset0:2 offset1:3
	s_waitcnt lgkmcnt(3)
	v_add_f32_e32 v18, v39, v34
	v_add_f32_e32 v19, v39, v35
	ds_write2st64_b32 v3, v18, v19 offset0:4 offset1:5
	s_waitcnt lgkmcnt(3)
	v_add_f32_e32 v18, v39, v36
	v_add_f32_e32 v19, v39, v37
	v_mov_b64_e32 v[20:21], s[0:1]
	ds_write2st64_b32 v3, v18, v19 offset0:6 offset1:7
	v_ashrrev_i32_e32 v3, 31, v2
	v_mad_i64_i32 v[18:19], s[0:1], v6, s55, v[20:21]
	v_lshl_add_u64 v[34:35], v[18:19], 0, s[40:41]
	v_lshlrev_b64 v[18:19], 1, v[2:3]
	v_lshl_add_u64 v[34:35], v[34:35], 0, v[18:19]
	s_waitcnt vmcnt(0) lgkmcnt(0)
	s_waitcnt lgkmcnt(0)
	s_barrier
; #define LAS __attribute__((address_space(3)))
; __device__ __forceinline__ unsigned f2bf(float f) { unsigned u = __builtin_bit_cast(unsigned, f); return (u + 0x7fffu + ((u >> 16) & 1u)) >> 16; }
; __device__ __forceinline__ float siluf(float x) { return x * __builtin_amdgcn_rcpf(1.0f + __expf(-x)); }
; template <int TY> __device__ __forceinline__ void ma_even_item(const Params& p, ldsp lds, int item) {
;     ...
;     bf16_t* QT = (bf16_t*)(p.ws + WS_QT); bf16_t* QH = (bf16_t*)(p.ws + WS_QH); bf16_t* KT = (bf16_t*)(p.ws + WS_KT);
;     const int col = TY ? 256 + h * 128 + d : h * 64 + d;
; #pragma unroll
;     for (int i = 0; i < SEGL; ++i) { const int s = sg * SEGL + i; const float bs = Bl[s * DK + d]; float qv, kv;
;         if (TY == 0) { qv = bf2f(Pb[(size_t)s * NE + E_QA + h * 64 + d]) * 0.125f; kv = bf2f(Pb[(size_t)s * NE + E_KA + h * 64 + d]); }
;         else { qv = siluf(bf2f(Pb[(size_t)s * NE + E_QB + h * 128 + d])); const float xf = bf2f(Pb[(size_t)s * NE + E_FB + h * 128 + d]); kv = (1.0f - lbv) * __builtin_amdgcn_rcpf(1.0f + __expf(xf)); }
;         const size_t g = (size_t)(row0 + s) * 768 + col;
;         QT[g] = (bf16_t)f2bf(qv * __expf(fminf(bs - bmid, 80.f))); QH[g] = (bf16_t)f2bf(qv * __expf(bs)); KT[g] = (bf16_t)f2bf(kv * __expf(fminf(bmid - bs, 80.f)));
;         *(LAS bf16_t*)(KHT + (size_t)(d * 72 + s) * 2) = (bf16_t)f2bf(kv * __expf(blast - bs)); }
	global_load_ushort v186, v[34:35], off
	global_load_ushort v187, v[34:35], off offset:512
	v_mad_i64_i32 v[188:189], s[0:1], v1, s55, v[20:21]
	v_lshl_add_u64 v[190:191], v[188:189], 0, s[40:41]
	v_lshl_add_u64 v[192:193], v[190:191], 0, v[18:19]
	global_load_ushort v194, v[192:193], off
	global_load_ushort v195, v[192:193], off offset:512
	v_mad_i64_i32 v[196:197], s[0:1], v16, s55, v[20:21]
	v_lshl_add_u64 v[198:199], v[196:197], 0, s[40:41]
	v_lshl_add_u64 v[200:201], v[198:199], 0, v[18:19]
	global_load_ushort v202, v[200:201], off
	global_load_ushort v203, v[200:201], off offset:512
	v_mad_i64_i32 v[204:205], s[0:1], v25, s55, v[20:21]
	v_lshl_add_u64 v[206:207], v[204:205], 0, s[40:41]
	v_lshl_add_u64 v[208:209], v[206:207], 0, v[18:19]
	global_load_ushort v210, v[208:209], off
	global_load_ushort v211, v[208:209], off offset:512
	v_mad_i64_i32 v[212:213], s[0:1], v26, s55, v[20:21]
	v_lshl_add_u64 v[214:215], v[212:213], 0, s[40:41]
	v_lshl_add_u64 v[216:217], v[214:215], 0, v[18:19]
	global_load_ushort v218, v[216:217], off
	global_load_ushort v219, v[216:217], off offset:512
	v_mad_i64_i32 v[220:221], s[0:1], v27, s55, v[20:21]
	v_lshl_add_u64 v[222:223], v[220:221], 0, s[40:41]
	v_lshl_add_u64 v[224:225], v[222:223], 0, v[18:19]
	global_load_ushort v226, v[224:225], off
	global_load_ushort v227, v[224:225], off offset:512
	v_mad_i64_i32 v[228:229], s[0:1], v30, s55, v[20:21]
	v_lshl_add_u64 v[230:231], v[228:229], 0, s[40:41]
	v_lshl_add_u64 v[232:233], v[230:231], 0, v[18:19]
	v_mad_i64_i32 v[234:235], s[0:1], v28, s55, v[20:21]
	v_lshl_add_u64 v[236:237], v[234:235], 0, s[40:41]
	v_lshl_add_u64 v[238:239], v[236:237], 0, v[18:19]
	global_load_ushort v240, v[232:233], off
	global_load_ushort v241, v[232:233], off offset:512
	global_load_ushort v242, v[238:239], off
	global_load_ushort v243, v[238:239], off offset:512
	v_add_u32_e32 v36, s13, v6
	v_mad_i64_i32 v[34:35], s[0:1], v1, s55, v[20:21]
	v_mad_i64_i32 v[36:37], s[0:1], v36, s9, v[4:5]
	v_lshl_add_u64 v[34:35], v[34:35], 0, s[40:41]
	v_lshlrev_b64 v[36:37], 1, v[36:37]
	v_lshl_add_u64 v[42:43], v[34:35], 0, v[18:19]
	v_lshl_add_u64 v[44:45], s[28:29], 0, v[36:37]
	v_lshl_add_u64 v[46:47], s[22:23], 0, v[36:37]
	v_lshl_add_u64 v[48:49], s[72:73], 0, v[36:37]
	ds_read_b32 v34, v22 offset:7936
	ds_read_b32 v35, v23
	ds_read_b32 v36, v24
	ds_read_b32 v31, v31
	ds_read_b32 v32, v32
	ds_read_b32 v33, v33
	ds_read_b32 v37, v38
	ds_read_b32 v38, v41
	s_waitcnt lgkmcnt(6)
	v_sub_f32_e32 v24, v34, v35
	v_sub_f32_e32 v22, v35, v34
	v_min_f32_e32 v24, 0x42a00000, v24
	v_min_f32_e32 v22, 0x42a00000, v22
	v_mul_f32_e32 v24, 0x3fb8aa3b, v24
	v_mul_f32_e32 v23, 0x3fb8aa3b, v35
	v_mul_f32_e32 v22, 0x3fb8aa3b, v22
	v_exp_f32_e32 v24, v24
	v_exp_f32_e32 v23, v23
	v_exp_f32_e32 v41, v22
	v_add_u32_e32 v1, s13, v1
	s_waitcnt vmcnt(0)
	v_lshlrev_b32_e32 v39, 16, v186
	v_lshlrev_b32_e32 v22, 16, v187
	v_mul_f32_e32 v39, 0x3e000000, v39
	v_mul_f32_e32 v24, v24, v22
	v_mul_f32_e32 v40, v41, v39
	v_mul_f32_e32 v23, v23, v39
	v_bfe_u32 v39, v24, 16, 1
	v_bfe_u32 v41, v40, 16, 1
	v_bfe_u32 v50, v23, 16, 1
	v_add3_u32 v24, v24, v39, s52
	v_add3_u32 v39, v40, v41, s52
	v_add3_u32 v23, v23, v50, s52
	global_store_short_d16_hi v[48:49], v24, off
	global_store_short_d16_hi v[44:45], v39, off
	global_store_short_d16_hi v[46:47], v23, off
	s_nop 0
	s_waitcnt lgkmcnt(5)
	v_sub_f32_e32 v48, v34, v36
	v_mad_i64_i32 v[42:43], s[0:1], v1, s9, v[4:5]
	v_sub_f32_e32 v1, v36, v34
	v_min_f32_e32 v48, 0x42a00000, v48
	v_min_f32_e32 v1, 0x42a00000, v1
	v_mul_f32_e32 v48, 0x3fb8aa3b, v48
	v_mul_f32_e32 v39, 0x3fb8aa3b, v36
	v_mul_f32_e32 v1, 0x3fb8aa3b, v1
	v_exp_f32_e32 v48, v48
	v_exp_f32_e32 v39, v39
	v_exp_f32_e32 v1, v1
	v_mad_i64_i32 v[40:41], s[0:1], v16, s55, v[20:21]
	v_lshlrev_b64 v[42:43], 1, v[42:43]
	v_lshl_add_u64 v[40:41], v[40:41], 0, s[40:41]
	v_lshl_add_u64 v[44:45], s[28:29], 0, v[42:43]
	v_lshl_add_u64 v[46:47], s[22:23], 0, v[42:43]
	v_lshl_add_u64 v[42:43], s[72:73], 0, v[42:43]
	v_lshl_add_u64 v[40:41], v[40:41], 0, v[18:19]
	v_add_u32_e32 v16, s13, v16
	v_lshlrev_b32_e32 v49, 16, v194
	v_lshlrev_b32_e32 v23, 16, v195
	v_mul_f32_e32 v24, 0x3e000000, v49
	v_mul_f32_e32 v48, v48, v23
	v_mul_f32_e32 v1, v1, v24
	v_mul_f32_e32 v24, v39, v24
	v_bfe_u32 v39, v48, 16, 1
	v_bfe_u32 v49, v1, 16, 1
	v_bfe_u32 v50, v24, 16, 1
	v_add3_u32 v39, v48, v39, s52
	v_add3_u32 v1, v1, v49, s52
	v_add3_u32 v24, v24, v50, s52
	global_store_short_d16_hi v[42:43], v39, off
	global_store_short_d16_hi v[44:45], v1, off
	global_store_short_d16_hi v[46:47], v24, off
	s_nop 0
	s_waitcnt lgkmcnt(4)
	v_sub_f32_e32 v48, v34, v31
	v_mad_i64_i32 v[42:43], s[0:1], v16, s9, v[4:5]
	v_sub_f32_e32 v16, v31, v34
	v_min_f32_e32 v48, 0x42a00000, v48
	v_min_f32_e32 v16, 0x42a00000, v16
	v_mul_f32_e32 v48, 0x3fb8aa3b, v48
	v_mul_f32_e32 v39, 0x3fb8aa3b, v31
	v_mul_f32_e32 v16, 0x3fb8aa3b, v16
	v_exp_f32_e32 v48, v48
	v_exp_f32_e32 v39, v39
	v_exp_f32_e32 v16, v16
	v_mad_i64_i32 v[40:41], s[0:1], v25, s55, v[20:21]
	v_lshlrev_b64 v[42:43], 1, v[42:43]
	v_lshl_add_u64 v[40:41], v[40:41], 0, s[40:41]
	v_lshl_add_u64 v[44:45], s[28:29], 0, v[42:43]
	v_lshl_add_u64 v[46:47], s[22:23], 0, v[42:43]
	v_lshl_add_u64 v[42:43], s[72:73], 0, v[42:43]
	v_lshl_add_u64 v[40:41], v[40:41], 0, v[18:19]
	v_add_u32_e32 v25, s13, v25
	v_lshlrev_b32_e32 v1, 16, v202
	v_lshlrev_b32_e32 v24, 16, v203
	v_mul_f32_e32 v1, 0x3e000000, v1
	v_mul_f32_e32 v48, v48, v24
	v_mul_f32_e32 v16, v16, v1
	v_mul_f32_e32 v1, v39, v1
	v_bfe_u32 v39, v48, 16, 1
	v_bfe_u32 v49, v16, 16, 1
	v_bfe_u32 v50, v1, 16, 1
	v_add3_u32 v39, v48, v39, s52
	v_add3_u32 v16, v16, v49, s52
	v_add3_u32 v1, v1, v50, s52
	global_store_short_d16_hi v[42:43], v39, off
	global_store_short_d16_hi v[44:45], v16, off
	global_store_short_d16_hi v[46:47], v1, off
	s_nop 0
	s_waitcnt lgkmcnt(3)
; #define LAS __attribute__((address_space(3)))
; __device__ __forceinline__ unsigned f2bf(float f) { unsigned u = __builtin_bit_cast(unsigned, f); return (u + 0x7fffu + ((u >> 16) & 1u)) >> 16; }
; __device__ __forceinline__ float siluf(float x) { return x * __builtin_amdgcn_rcpf(1.0f + __expf(-x)); }
; template <int TY> __device__ __forceinline__ void ma_even_item(const Params& p, ldsp lds, int item) {
;     ...
;     for (int i = 0; i < SEGL; ++i) { const int s = sg * SEGL + i; const float bs = Bl[s * DK + d]; float qv, kv;
;         if (TY == 0) { qv = bf2f(Pb[(size_t)s * NE + E_QA + h * 64 + d]) * 0.125f; kv = bf2f(Pb[(size_t)s * NE + E_KA + h * 64 + d]); }
;         else { qv = siluf(bf2f(Pb[(size_t)s * NE + E_QB + h * 128 + d])); const float xf = bf2f(Pb[(size_t)s * NE + E_FB + h * 128 + d]); kv = (1.0f - lbv) * __builtin_amdgcn_rcpf(1.0f + __expf(xf)); }
;         const size_t g = (size_t)(row0 + s) * 768 + col;
;         QT[g] = (bf16_t)f2bf(qv * __expf(fminf(bs - bmid, 80.f))); QH[g] = (bf16_t)f2bf(qv * __expf(bs)); KT[g] = (bf16_t)f2bf(kv * __expf(fminf(bmid - bs, 80.f)));
;         *(LAS bf16_t*)(KHT + (size_t)(d * 72 + s) * 2) = (bf16_t)f2bf(kv * __expf(blast - bs)); }
	v_sub_f32_e32 v48, v34, v32
	v_mad_i64_i32 v[42:43], s[0:1], v25, s9, v[4:5]
	v_sub_f32_e32 v25, v32, v34
	v_min_f32_e32 v48, 0x42a00000, v48
	v_min_f32_e32 v25, 0x42a00000, v25
	v_mul_f32_e32 v48, 0x3fb8aa3b, v48
	v_mul_f32_e32 v39, 0x3fb8aa3b, v32
	v_mul_f32_e32 v25, 0x3fb8aa3b, v25
	v_exp_f32_e32 v48, v48
	v_exp_f32_e32 v39, v39
	v_exp_f32_e32 v49, v25
	v_mad_i64_i32 v[40:41], s[0:1], v26, s55, v[20:21]
	v_lshlrev_b64 v[42:43], 1, v[42:43]
	v_lshl_add_u64 v[40:41], v[40:41], 0, s[40:41]
	v_lshl_add_u64 v[44:45], s[28:29], 0, v[42:43]
	v_lshl_add_u64 v[46:47], s[22:23], 0, v[42:43]
	v_lshl_add_u64 v[42:43], s[72:73], 0, v[42:43]
	v_lshl_add_u64 v[40:41], v[40:41], 0, v[18:19]
	v_add_u32_e32 v26, s13, v26
	v_lshlrev_b32_e32 v1, 16, v210
	v_lshlrev_b32_e32 v25, 16, v211
	v_mul_f32_e32 v1, 0x3e000000, v1
	v_mul_f32_e32 v16, v48, v25
	v_mul_f32_e32 v48, v49, v1
	v_mul_f32_e32 v1, v39, v1
	v_bfe_u32 v39, v16, 16, 1
	v_bfe_u32 v49, v48, 16, 1
	v_bfe_u32 v50, v1, 16, 1
	v_add3_u32 v16, v16, v39, s52
	v_add3_u32 v39, v48, v49, s52
	v_add3_u32 v1, v1, v50, s52
	global_store_short_d16_hi v[42:43], v16, off
	global_store_short_d16_hi v[44:45], v39, off
	global_store_short_d16_hi v[46:47], v1, off
	s_nop 0
	s_waitcnt lgkmcnt(2)
	v_sub_f32_e32 v48, v34, v33
	v_mad_i64_i32 v[42:43], s[0:1], v26, s9, v[4:5]
	v_sub_f32_e32 v26, v33, v34
	v_min_f32_e32 v48, 0x42a00000, v48
	v_min_f32_e32 v26, 0x42a00000, v26
	v_mul_f32_e32 v48, 0x3fb8aa3b, v48
	v_mul_f32_e32 v39, 0x3fb8aa3b, v33
	v_mul_f32_e32 v26, 0x3fb8aa3b, v26
	v_exp_f32_e32 v48, v48
	v_exp_f32_e32 v39, v39
	v_exp_f32_e32 v49, v26
	v_mad_i64_i32 v[40:41], s[0:1], v27, s55, v[20:21]
	v_lshlrev_b64 v[42:43], 1, v[42:43]
	v_lshl_add_u64 v[40:41], v[40:41], 0, s[40:41]
	v_lshl_add_u64 v[44:45], s[28:29], 0, v[42:43]
	v_lshl_add_u64 v[46:47], s[22:23], 0, v[42:43]
	v_lshl_add_u64 v[42:43], s[72:73], 0, v[42:43]
	v_lshl_add_u64 v[40:41], v[40:41], 0, v[18:19]
	v_add_u32_e32 v27, s13, v27
	v_lshlrev_b32_e32 v1, 16, v218
	v_lshlrev_b32_e32 v26, 16, v219
	v_mul_f32_e32 v1, 0x3e000000, v1
	v_mul_f32_e32 v16, v48, v26
	v_mul_f32_e32 v48, v49, v1
	v_mul_f32_e32 v1, v39, v1
	v_bfe_u32 v39, v16, 16, 1
	v_bfe_u32 v49, v48, 16, 1
	v_bfe_u32 v50, v1, 16, 1
	v_add3_u32 v16, v16, v39, s52
	v_add3_u32 v39, v48, v49, s52
	v_add3_u32 v1, v1, v50, s52
	global_store_short_d16_hi v[42:43], v16, off
	global_store_short_d16_hi v[44:45], v39, off
	global_store_short_d16_hi v[46:47], v1, off
	s_nop 0
	s_waitcnt lgkmcnt(1)
	v_sub_f32_e32 v48, v34, v37
	v_mad_i64_i32 v[42:43], s[0:1], v27, s9, v[4:5]
	v_sub_f32_e32 v27, v37, v34
	v_min_f32_e32 v48, 0x42a00000, v48
	v_min_f32_e32 v27, 0x42a00000, v27
	v_mul_f32_e32 v48, 0x3fb8aa3b, v48
	v_mul_f32_e32 v39, 0x3fb8aa3b, v37
	v_mul_f32_e32 v27, 0x3fb8aa3b, v27
	v_exp_f32_e32 v48, v48
	v_exp_f32_e32 v39, v39
	v_exp_f32_e32 v49, v27
	v_mad_i64_i32 v[40:41], s[0:1], v30, s55, v[20:21]
	v_lshlrev_b64 v[42:43], 1, v[42:43]
	v_lshl_add_u64 v[40:41], v[40:41], 0, s[40:41]
	v_lshl_add_u64 v[44:45], s[28:29], 0, v[42:43]
	v_lshl_add_u64 v[46:47], s[22:23], 0, v[42:43]
	v_lshl_add_u64 v[42:43], s[72:73], 0, v[42:43]
	v_lshl_add_u64 v[40:41], v[40:41], 0, v[18:19]
	v_add_u32_e32 v30, s13, v30
	v_mad_i64_i32 v[20:21], s[0:1], v28, s55, v[20:21]
	v_lshl_add_u64 v[20:21], v[20:21], 0, s[40:41]
	v_lshl_add_u64 v[18:19], v[20:21], 0, v[18:19]
	v_lshlrev_b32_e32 v1, 16, v226
	v_lshlrev_b32_e32 v27, 16, v227
	v_mul_f32_e32 v1, 0x3e000000, v1
	v_mul_f32_e32 v16, v48, v27
	v_mul_f32_e32 v48, v49, v1
	v_mul_f32_e32 v1, v39, v1
	v_bfe_u32 v39, v16, 16, 1
	v_bfe_u32 v49, v48, 16, 1
	v_bfe_u32 v50, v1, 16, 1
	v_add3_u32 v16, v16, v39, s52
	v_add3_u32 v39, v48, v49, s52
	v_add3_u32 v1, v1, v50, s52
	global_store_short_d16_hi v[42:43], v16, off
	global_store_short_d16_hi v[44:45], v39, off
	global_store_short_d16_hi v[46:47], v1, off
	s_nop 0
	s_waitcnt lgkmcnt(0)
; #define LAS __attribute__((address_space(3)))
; __device__ __forceinline__ unsigned f2bf(float f) { unsigned u = __builtin_bit_cast(unsigned, f); return (u + 0x7fffu + ((u >> 16) & 1u)) >> 16; }
; __device__ __forceinline__ float siluf(float x) { return x * __builtin_amdgcn_rcpf(1.0f + __expf(-x)); }
; template <int TY> __device__ __forceinline__ void ma_even_item(const Params& p, ldsp lds, int item) {
;     ...
;     for (int i = 0; i < SEGL; ++i) { const int s = sg * SEGL + i; const float bs = Bl[s * DK + d]; float qv, kv;
;         if (TY == 0) { qv = bf2f(Pb[(size_t)s * NE + E_QA + h * 64 + d]) * 0.125f; kv = bf2f(Pb[(size_t)s * NE + E_KA + h * 64 + d]); }
;         else { qv = siluf(bf2f(Pb[(size_t)s * NE + E_QB + h * 128 + d])); const float xf = bf2f(Pb[(size_t)s * NE + E_FB + h * 128 + d]); kv = (1.0f - lbv) * __builtin_amdgcn_rcpf(1.0f + __expf(xf)); }
;         const size_t g = (size_t)(row0 + s) * 768 + col;
;         QT[g] = (bf16_t)f2bf(qv * __expf(fminf(bs - bmid, 80.f))); QH[g] = (bf16_t)f2bf(qv * __expf(bs)); KT[g] = (bf16_t)f2bf(kv * __expf(fminf(bmid - bs, 80.f)));
;         *(LAS bf16_t*)(KHT + (size_t)(d * 72 + s) * 2) = (bf16_t)f2bf(kv * __expf(blast - bs)); }
;     if (sg == 0) ((float*)(p.ws + WS_DEC + (TY ? DEC_HGRN : 0)))[(size_t)item * DK + d] = __expf(blast);
	v_sub_f32_e32 v44, v34, v38
	v_mad_i64_i32 v[40:41], s[0:1], v30, s9, v[4:5]
	v_sub_f32_e32 v30, v38, v34
	v_min_f32_e32 v44, 0x42a00000, v44
	v_min_f32_e32 v30, 0x42a00000, v30
	v_mul_f32_e32 v44, 0x3fb8aa3b, v44
	v_mul_f32_e32 v39, 0x3fb8aa3b, v38
	v_mul_f32_e32 v30, 0x3fb8aa3b, v30
	v_exp_f32_e32 v44, v44
	v_exp_f32_e32 v39, v39
	v_exp_f32_e32 v45, v30
	v_lshlrev_b64 v[40:41], 1, v[40:41]
	v_lshl_add_u64 v[20:21], s[28:29], 0, v[40:41]
	v_lshl_add_u64 v[42:43], s[22:23], 0, v[40:41]
	v_lshl_add_u64 v[40:41], s[72:73], 0, v[40:41]
	v_lshlrev_b32_e32 v1, 16, v240
	v_lshlrev_b32_e32 v30, 16, v241
	v_mul_f32_e32 v1, 0x3e000000, v1
	v_mul_f32_e32 v16, v44, v30
	v_mul_f32_e32 v44, v45, v1
	v_mul_f32_e32 v1, v39, v1
	v_bfe_u32 v39, v16, 16, 1
	v_bfe_u32 v45, v44, 16, 1
	v_bfe_u32 v46, v1, 16, 1
	v_add3_u32 v16, v16, v39, s52
	v_add3_u32 v39, v44, v45, s52
	v_add3_u32 v1, v1, v46, s52
	global_store_short_d16_hi v[40:41], v16, off
	global_store_short_d16_hi v[20:21], v39, off
	global_store_short_d16_hi v[42:43], v1, off
	s_nop 0
	v_add_u32_e32 v1, s13, v28
	v_mad_i64_i32 v[4:5], s[0:1], v1, s9, v[4:5]
	v_add_f32_e32 v1, v10, v11
	v_add_f32_e32 v1, v1, v8
	v_add_f32_e32 v1, v1, v9
	v_add_f32_e32 v1, v1, v12
	ds_read_b32 v8, v29
	v_add_f32_e32 v1, v1, v13
	v_add_f32_e32 v1, v1, v14
	v_add_f32_e32 v1, v1, v15
	v_sub_f32_e32 v9, v1, v35
	v_sub_f32_e32 v10, v1, v36
	v_sub_f32_e32 v11, v1, v31
	s_waitcnt lgkmcnt(0)
	v_sub_f32_e32 v28, v8, v34
	v_mul_f32_e32 v29, 0x3fb8aa3b, v8
	v_sub_f32_e32 v31, v34, v8
	v_sub_f32_e32 v8, v1, v8
	v_mul_f32_e32 v9, 0x3fb8aa3b, v9
	v_mul_f32_e32 v10, 0x3fb8aa3b, v10
	v_sub_f32_e32 v12, v1, v32
	v_mul_f32_e32 v32, 0x3fb8aa3b, v8
	v_exp_f32_e32 v8, v9
	v_exp_f32_e32 v9, v10
	v_mul_f32_e32 v11, 0x3fb8aa3b, v11
	v_mul_f32_e32 v12, 0x3fb8aa3b, v12
	v_exp_f32_e32 v10, v11
	v_exp_f32_e32 v11, v12
	v_sub_f32_e32 v13, v1, v33
	v_sub_f32_e32 v14, v1, v37
	v_mul_f32_e32 v13, 0x3fb8aa3b, v13
	v_mul_f32_e32 v14, 0x3fb8aa3b, v14
	v_pk_mul_f32 v[8:9], v[8:9], v[22:23]
	v_mad_u64_u32 v[18:19], s[0:1], v2, s53, v[6:7]
	v_exp_f32_e32 v12, v13
	v_exp_f32_e32 v13, v14
	v_bfe_u32 v22, v9, 16, 1
	v_bfe_u32 v23, v8, 16, 1
	v_add3_u32 v8, v8, v23, s52
	v_add3_u32 v9, v9, v22, s52
	s_mov_b32 s0, 0x7060302
	v_pk_mul_f32 v[10:11], v[10:11], v[24:25]
	v_sub_f32_e32 v15, v1, v38
	v_perm_b32 v8, v9, v8, s0
	v_bfe_u32 v9, v11, 16, 1
	v_bfe_u32 v22, v10, 16, 1
	v_mul_f32_e32 v15, 0x3fb8aa3b, v15
	v_min_f32_e32 v28, 0x42a00000, v28
	v_min_f32_e32 v31, 0x42a00000, v31
	v_add3_u32 v10, v10, v22, s52
	v_add3_u32 v9, v11, v9, s52
	v_exp_f32_e32 v14, v15
	v_mul_f32_e32 v28, 0x3fb8aa3b, v28
	v_mul_f32_e32 v31, 0x3fb8aa3b, v31
	v_exp_f32_e32 v15, v32
	v_perm_b32 v9, v9, v10, s0
	v_pk_mul_f32 v[10:11], v[12:13], v[26:27]
	v_exp_f32_e32 v29, v29
	v_exp_f32_e32 v28, v28
	v_exp_f32_e32 v32, v31
	v_bfe_u32 v12, v11, 16, 1
	v_bfe_u32 v13, v10, 16, 1
	v_add3_u32 v10, v10, v13, s52
	v_add3_u32 v11, v11, v12, s52
	v_perm_b32 v10, v11, v10, s0
	v_add_u32_e32 v40, 63, v0
	v_lshlrev_b64 v[4:5], 1, v[4:5]
	v_lshl_add_u32 v6, v18, 1, 0
	v_lshl_add_u64 v[18:19], s[28:29], 0, v[4:5]
	v_lshl_add_u64 v[20:21], s[22:23], 0, v[4:5]
	v_lshl_add_u64 v[4:5], s[72:73], 0, v[4:5]
	v_lshlrev_b32_e32 v11, 16, v242
	v_lshlrev_b32_e32 v31, 16, v243
	v_mul_f32_e32 v11, 0x3e000000, v11
	v_pk_mul_f32 v[12:13], v[14:15], v[30:31]
	v_mul_f32_e32 v16, v32, v31
	v_mul_f32_e32 v14, v28, v11
	v_mul_f32_e32 v11, v29, v11
	v_bfe_u32 v22, v13, 16, 1
	v_bfe_u32 v23, v12, 16, 1
	v_bfe_u32 v15, v16, 16, 1
	v_bfe_u32 v25, v11, 16, 1
	v_add3_u32 v12, v12, v23, s52
	v_add3_u32 v13, v13, v22, s52
	v_bfe_u32 v24, v14, 16, 1
	v_add3_u32 v15, v16, v15, s52
	v_add3_u32 v16, v11, v25, s52
	v_perm_b32 v11, v13, v12, s0
	s_movk_i32 s0, 0x7e
	v_add3_u32 v14, v14, v24, s52
	v_cmp_lt_u32_e32 vcc, s0, v40
	global_store_short_d16_hi v[4:5], v15, off
	global_store_short_d16_hi v[18:19], v14, off
	global_store_short_d16_hi v[20:21], v16, off
	ds_write_b128 v6, v[8:11] offset:40960
	s_and_saveexec_b64 s[0:1], vcc
	s_xor_b64 s[0:1], exec, s[0:1]
	s_ashr_i32 s13, s12, 31
	s_or_saveexec_b64 s[0:1], s[0:1]
	v_mov_b64_e32 v[4:5], s[12:13]
	s_xor_b64 exec, exec, s[0:1]
	s_cbranch_execz .LBB0_1048
	v_mul_f32_e32 v1, 0x3fb8aa3b, v1
	s_ashr_i32 s13, s12, 31
	v_exp_f32_e32 v1, v1
	s_lshl_b64 s[14:15], s[12:13], 8
	v_readlane_b32 s9, v253, 57
	s_add_u32 s14, s9, s14
	v_readlane_b32 s9, v253, 58
	s_addc_u32 s15, s9, s15
	v_lshl_add_u64 v[2:3], v[2:3], 2, s[14:15]
	v_mov_b64_e32 v[4:5], s[12:13]
	global_store_dword v[2:3], v1, off
	s_branch .LBB0_1048
